# phase-3 work queue: next item claimed at the start of hg_prep units only (shortest units), other units claim synchronously
# speedup vs baseline: 1.0034x; 1.0034x over previous
; DI float bf2f(bfr v) { return __uint_as_float(((unsigned)v) << 16); }
; DI void stream_of(int n, int cpc, int& m, int& T, int& soff) { if (n < cpc) { m = n; T = CTX; soff = 0; } else { m = n - cpc; T = SEQ; soff = CTX; } }
; DI void hg_prep_unit(const Params& p, int l, int unit, unsigned char* smem) {
;     ...
;   const int n = unit % 136, hd = (unit / 136) & 3, b = (unit / 544) & 3, dir = unit / 2176;
;   int m, T, soff; stream_of(n, 8, m, T, soff);
;   bfr* sQt = (bfr*)smem;
;   bfr* sKt = (bfr*)(smem + 8704);
;   bfr* sVT = (bfr*)(smem + 17408);
;   const bfr* P = (const bfr*)(WS_ + O_P);
;   bfr* U = (bfr*)(WS_ + O_HGU) + (size_t)unit * HG_USZ;
;   bfr* g_qhat = U; bfr* g_khT = U + 4096; bfr* g_vT = U + 8192;
;   float* OHG = (float*)(WS_ + O_OHG) + (size_t)dir * NTOK * 512;
;   const int rowbase = b * SP + soff;
;   float* sTot = (float*)(smem + 27648);
;   __syncthreads();
;   {
;     const int dk = tid & 127, hf = tid >> 7, i0 = 16 * hf;
;     const float lbv = ((const float*)(WS_ + O_LB))[(l * 2 + dir) * 512 + hd * 128 + dk];
;     float G[16], KK[16], Q[16];
;     unsigned vv[8];
; #pragma unroll
;     for (int i = 0; i < 16; ++i) {
;       const int pos = 32 * m + i0 + i, t = dir ? T - 1 - pos : pos;
;       const size_t row = rowbase + t;
;       KK[i] = bf2f(P[row * PLD + C_HGF + dir * 512 + hd * 128 + dk]);
;       Q[i] = bf2f(P[row * PLD + C_HGQ + hd * 128 + dk]);
;       const unsigned x = P[row * PLD + C_HGI + hd * 128 + dk];
;       if (i & 1) vv[i >> 1] |= x << 16; else vv[i >> 1] = x;
;     }
; __global__ void __launch_bounds__(256, 2) mega(Params p) {
;     ...
;       for (;;) {
;         __syncthreads();
;         if (tid == 0) s_item = (int)atomicAdd(ctr3, 1u);
;         __syncthreads();
;         const int it = s_item - n_att3 + dft0;
;         if (it >= N_DFT + N_DN + N_HG) break;
;         if (it < dft0) attn_unit(p, l, 448 + (it - dft0) + n_att3, smem);
;         else if (it < N_DFT) dft_tile(p, it, smem);
;         else if (it < N_DFT + N_DN) dn_prep_unit(p, l, it - N_DFT, smem);
;         else hg_prep_unit(p, l, it - N_DFT - N_DN, smem);
.LBB0_315:
	s_or_b64 exec, exec, s[4:5]
	s_waitcnt lgkmcnt(0)
	s_barrier
	ds_read_b32 v0, v218
	v_mov_b32_e32 v241, -1
	s_mov_b64 s[4:5], -1
	s_waitcnt lgkmcnt(0)
	v_readfirstlane_b32 s38, v0
	s_add_i32 s39, s38, s35
	s_add_i32 s41, s39, s34
	s_cmpk_gt_i32 s41, 0x1b9f
	s_cbranch_scc1 .LBB0_310
	s_cmp_gt_i32 s39, -1
	s_cbranch_scc0 .LBB0_471
	s_cmpk_gt_i32 s41, 0x21f
	s_cbranch_scc0 .LBB0_462
	s_cmpk_gt_u32 s41, 0xa9f
	s_cbranch_scc0 .LBB0_322
	s_mov_b64 s[6:7], exec
	s_mov_b64 exec, s[10:11]
	v_mov_b32_e32 v241, 1
	s_nop 0
	global_atomic_add v241, v209, v241, s[20:21] sc0
	s_mov_b64 exec, s[6:7]
	s_add_i32 s24, s41, 0xfffff560
	s_and_b32 s4, s24, 0xffff
	s_mul_i32 s4, s4, 0xf0f1
	s_lshr_b32 s25, s4, 16
	s_lshr_b32 s4, s4, 23
	s_mulk_i32 s4, 0x88
	s_sub_i32 s4, s24, s4
	s_and_b32 s4, s4, 0xffff
	s_cmp_lt_u32 s4, 8
	s_cselect_b32 s6, 0, -8
	s_mov_b64 s[8:9], s[84:85]
	s_cselect_b32 s46, 0x100, s95
	s_cselect_b32 s47, 0, 0x100
	s_add_i32 s30, s6, s4
	s_add_u32 s6, s8, 0xcc00000
	s_addc_u32 s7, s9, 0
	s_mul_i32 s26, s24, 0x6000
	s_mul_hi_u32 s4, s24, 0x6000
	s_add_u32 s26, s8, s26
	s_addc_u32 s4, s9, s4
	s_mul_i32 s5, s24, 0xf0f1
	s_add_u32 s28, s26, 0x619cf600
	s_addc_u32 s29, s4, 0
	s_bfe_u32 s4, s5, 0x20019
	s_mulk_i32 s4, 0x1100
	s_add_i32 s47, s47, s4
	s_cmpk_gt_u32 s24, 0x87f
	s_cselect_b64 s[26:27], -1, 0
	s_and_b64 s[4:5], s[26:27], exec
	s_cselect_b32 s31, 0x200, 0
	s_and_b32 s50, s25, 0x180
	v_mov_b32_e32 v28, v216
	s_or_b32 s4, s36, s50
	s_or_b32 s4, s4, s31
	v_and_b32_e32 v29, 0x7f, v28
	v_ashrrev_i32_e32 v30, 3, v28
	v_and_b32_e32 v31, -16, v30
	v_or_b32_e32 v208, s4, v29
	s_lshl_b32 s51, s30, 5
	v_lshl_add_u64 v[0:1], v[208:209], 2, s[8:9]
	s_mov_b32 s4, 0x53cc8000
	v_add_u32_e32 v2, s51, v31
	s_cmpk_lt_u32 s24, 0x880
	v_add_co_u32_e32 v0, vcc, s4, v0
	v_xad_u32 v3, v2, -1, s46
	s_cselect_b64 s[4:5], -1, 0
	v_cndmask_b32_e64 v3, v3, v2, s[4:5]
	v_add_u32_e32 v4, s47, v3
	v_ashrrev_i32_e32 v5, 31, v4
	v_lshlrev_b64 v[4:5], 15, v[4:5]
	v_lshl_add_u64 v[4:5], s[6:7], 0, v[4:5]
	s_lshl_b32 s44, s31, 1
	v_lshl_add_u64 v[6:7], v[4:5], 0, s[44:45]
	s_lshl_b32 s30, s50, 1
	s_mov_b32 s31, s45
	v_or_b32_e32 v3, 1, v2
	v_xad_u32 v10, v2, -2, s46
	v_lshl_add_u64 v[6:7], v[6:7], 0, s[30:31]
	v_lshlrev_b32_e32 v208, 1, v29
	v_cndmask_b32_e64 v3, v10, v3, s[4:5]
	v_addc_co_u32_e32 v1, vcc, 0, v1, vcc
	v_lshl_add_u64 v[6:7], v[6:7], 0, v[208:209]
	s_movk_i32 s25, 0x2000
	v_add_u32_e32 v10, s47, v3
	v_add_co_u32_e32 v6, vcc, s25, v6
	v_lshl_add_u64 v[4:5], v[4:5], 0, s[30:31]
	v_ashrrev_i32_e32 v11, 31, v10
	v_addc_co_u32_e32 v7, vcc, 0, v7, vcc
	v_lshl_add_u64 v[4:5], v[4:5], 0, v[208:209]
	v_lshlrev_b64 v[10:11], 15, v[10:11]
	v_add_co_u32_e32 v8, vcc, s95, v4
	v_lshl_add_u64 v[10:11], s[6:7], 0, v[10:11]
	s_nop 0
	v_addc_co_u32_e32 v9, vcc, 0, v5, vcc
	v_lshl_add_u64 v[12:13], v[10:11], 0, s[44:45]
	v_or_b32_e32 v3, 2, v2
	v_xad_u32 v16, v2, -3, s46
	v_add_co_u32_e32 v4, vcc, s25, v4
	v_lshl_add_u64 v[12:13], v[12:13], 0, s[30:31]
	v_cndmask_b32_e64 v3, v16, v3, s[4:5]
	v_addc_co_u32_e32 v5, vcc, 0, v5, vcc
	v_lshl_add_u64 v[12:13], v[12:13], 0, v[208:209]
	v_add_u32_e32 v16, s47, v3
	v_add_co_u32_e32 v12, vcc, s25, v12
	v_lshl_add_u64 v[10:11], v[10:11], 0, s[30:31]
	v_ashrrev_i32_e32 v17, 31, v16
	v_addc_co_u32_e32 v13, vcc, 0, v13, vcc
	v_lshl_add_u64 v[10:11], v[10:11], 0, v[208:209]
	v_lshlrev_b64 v[16:17], 15, v[16:17]
	v_add_co_u32_e32 v14, vcc, s95, v10
	v_lshl_add_u64 v[16:17], s[6:7], 0, v[16:17]
	s_nop 0
	v_addc_co_u32_e32 v15, vcc, 0, v11, vcc
	v_lshl_add_u64 v[18:19], v[16:17], 0, s[44:45]
	v_add_co_u32_e32 v10, vcc, s25, v10
	v_lshl_add_u64 v[18:19], v[18:19], 0, s[30:31]
	s_nop 0
	v_addc_co_u32_e32 v11, vcc, 0, v11, vcc
	v_lshl_add_u64 v[18:19], v[18:19], 0, v[208:209]
	v_add_co_u32_e32 v18, vcc, s25, v18
	s_barrier
	s_nop 0
	v_addc_co_u32_e32 v19, vcc, 0, v19, vcc
	flat_load_ushort v22, v[6:7]
	flat_load_ushort v23, v[8:9] offset:3072
	flat_load_ushort v26, v[4:5] offset:2048
	flat_load_ushort v27, v[12:13]
	flat_load_ushort v32, v[14:15] offset:3072
	flat_load_ushort v33, v[10:11] offset:2048
	flat_load_ushort v34, v[18:19]
	v_or_b32_e32 v3, 3, v2
	v_xad_u32 v8, v2, -4, s46
	v_cndmask_b32_e64 v3, v8, v3, s[4:5]
	v_add_u32_e32 v8, s47, v3
	v_lshl_add_u64 v[4:5], v[16:17], 0, s[30:31]
	v_ashrrev_i32_e32 v9, 31, v8
	v_lshl_add_u64 v[4:5], v[4:5], 0, v[208:209]
	v_lshlrev_b64 v[8:9], 15, v[8:9]
	v_add_co_u32_e32 v6, vcc, s95, v4
	v_lshl_add_u64 v[8:9], s[6:7], 0, v[8:9]
	s_nop 0
	v_addc_co_u32_e32 v7, vcc, 0, v5, vcc
	v_lshl_add_u64 v[10:11], v[8:9], 0, s[44:45]
	v_or_b32_e32 v3, 4, v2
	v_xad_u32 v14, v2, -5, s46
	v_add_co_u32_e32 v4, vcc, s25, v4
	v_lshl_add_u64 v[10:11], v[10:11], 0, s[30:31]
	v_cndmask_b32_e64 v3, v14, v3, s[4:5]
	v_addc_co_u32_e32 v5, vcc, 0, v5, vcc
	v_lshl_add_u64 v[10:11], v[10:11], 0, v[208:209]
	v_add_u32_e32 v14, s47, v3
	v_add_co_u32_e32 v10, vcc, s25, v10
	v_lshl_add_u64 v[8:9], v[8:9], 0, s[30:31]
	v_ashrrev_i32_e32 v15, 31, v14
	v_addc_co_u32_e32 v11, vcc, 0, v11, vcc
	v_lshl_add_u64 v[8:9], v[8:9], 0, v[208:209]
	v_lshlrev_b64 v[14:15], 15, v[14:15]
	v_add_co_u32_e32 v12, vcc, s95, v8
	v_lshl_add_u64 v[14:15], s[6:7], 0, v[14:15]
	s_nop 0
	v_addc_co_u32_e32 v13, vcc, 0, v9, vcc
	v_lshl_add_u64 v[16:17], v[14:15], 0, s[44:45]
	v_add_co_u32_e32 v8, vcc, s25, v8
	v_lshl_add_u64 v[16:17], v[16:17], 0, s[30:31]
	s_nop 0
	v_addc_co_u32_e32 v9, vcc, 0, v9, vcc
	v_lshl_add_u64 v[16:17], v[16:17], 0, v[208:209]
	v_add_co_u32_e32 v16, vcc, s25, v16
	v_lshl_add_u64 v[14:15], v[14:15], 0, s[30:31]
	s_nop 0
	v_addc_co_u32_e32 v17, vcc, 0, v17, vcc
	v_lshl_add_u64 v[14:15], v[14:15], 0, v[208:209]
	v_add_co_u32_e32 v18, vcc, s95, v14
	v_or_b32_e32 v3, 5, v2
	s_nop 0
	v_addc_co_u32_e32 v19, vcc, 0, v15, vcc
	v_add_co_u32_e32 v14, vcc, s25, v14
	s_waitcnt vmcnt(0) lgkmcnt(0)
; DI float bf2f(bfr v) { return __uint_as_float(((unsigned)v) << 16); }
; DI void hg_prep_unit(const Params& p, int l, int unit, unsigned char* smem) {
;     ...
;     for (int i = 0; i < 16; ++i) {
;       const int pos = 32 * m + i0 + i, t = dir ? T - 1 - pos : pos;
;       const size_t row = rowbase + t;
;       KK[i] = bf2f(P[row * PLD + C_HGF + dir * 512 + hd * 128 + dk]);
;       Q[i] = bf2f(P[row * PLD + C_HGQ + hd * 128 + dk]);
;       const unsigned x = P[row * PLD + C_HGI + hd * 128 + dk];
;       if (i & 1) vv[i >> 1] |= x << 16; else vv[i >> 1] = x;
;     }
	v_lshlrev_b32_e32 v74, 16, v22
	v_addc_co_u32_e32 v15, vcc, 0, v15, vcc
	flat_load_ushort v35, v[6:7] offset:3072
	flat_load_ushort v36, v[4:5] offset:2048
	flat_load_ushort v37, v[10:11]
	flat_load_ushort v38, v[12:13] offset:3072
	flat_load_ushort v39, v[8:9] offset:2048
	flat_load_ushort v40, v[16:17]
	flat_load_ushort v44, v[18:19] offset:3072
	flat_load_ushort v45, v[14:15] offset:2048
	v_xad_u32 v4, v2, -6, s46
	v_cndmask_b32_e64 v3, v4, v3, s[4:5]
	v_add_u32_e32 v4, s47, v3
	v_ashrrev_i32_e32 v5, 31, v4
	v_lshlrev_b64 v[4:5], 15, v[4:5]
	v_lshl_add_u64 v[4:5], s[6:7], 0, v[4:5]
	v_lshl_add_u64 v[6:7], v[4:5], 0, s[44:45]
	v_or_b32_e32 v3, 6, v2
	v_xad_u32 v10, v2, -7, s46
	v_lshl_add_u64 v[6:7], v[6:7], 0, s[30:31]
	v_cndmask_b32_e64 v3, v10, v3, s[4:5]
	v_lshl_add_u64 v[6:7], v[6:7], 0, v[208:209]
	v_add_u32_e32 v10, s47, v3
	v_add_co_u32_e32 v6, vcc, s25, v6
	v_lshl_add_u64 v[4:5], v[4:5], 0, s[30:31]
	v_ashrrev_i32_e32 v11, 31, v10
	v_addc_co_u32_e32 v7, vcc, 0, v7, vcc
	v_lshl_add_u64 v[4:5], v[4:5], 0, v[208:209]
	v_lshlrev_b64 v[10:11], 15, v[10:11]
	v_add_co_u32_e32 v8, vcc, s95, v4
	v_lshl_add_u64 v[10:11], s[6:7], 0, v[10:11]
	s_nop 0
	v_addc_co_u32_e32 v9, vcc, 0, v5, vcc
	v_lshl_add_u64 v[12:13], v[10:11], 0, s[44:45]
	v_or_b32_e32 v3, 7, v2
	v_xad_u32 v16, v2, -8, s46
	v_add_co_u32_e32 v4, vcc, s25, v4
	v_lshl_add_u64 v[12:13], v[12:13], 0, s[30:31]
	v_cndmask_b32_e64 v3, v16, v3, s[4:5]
	v_addc_co_u32_e32 v5, vcc, 0, v5, vcc
	v_lshl_add_u64 v[12:13], v[12:13], 0, v[208:209]
	v_add_u32_e32 v16, s47, v3
	v_add_co_u32_e32 v12, vcc, s25, v12
	v_lshl_add_u64 v[10:11], v[10:11], 0, s[30:31]
	v_ashrrev_i32_e32 v17, 31, v16
	v_addc_co_u32_e32 v13, vcc, 0, v13, vcc
	v_lshl_add_u64 v[10:11], v[10:11], 0, v[208:209]
	v_lshlrev_b64 v[16:17], 15, v[16:17]
	v_add_co_u32_e32 v14, vcc, s95, v10
	v_lshl_add_u64 v[16:17], s[6:7], 0, v[16:17]
	s_nop 0
	v_addc_co_u32_e32 v15, vcc, 0, v11, vcc
	v_lshl_add_u64 v[18:19], v[16:17], 0, s[44:45]
	v_add_co_u32_e32 v10, vcc, s25, v10
	v_lshl_add_u64 v[18:19], v[18:19], 0, s[30:31]
	s_nop 0
	v_addc_co_u32_e32 v11, vcc, 0, v11, vcc
	v_lshl_add_u64 v[18:19], v[18:19], 0, v[208:209]
	v_add_co_u32_e32 v18, vcc, s25, v18
	v_lshl_add_u64 v[16:17], v[16:17], 0, s[30:31]
	s_nop 0
	v_addc_co_u32_e32 v19, vcc, 0, v19, vcc
	v_lshl_add_u64 v[16:17], v[16:17], 0, v[208:209]
	v_add_co_u32_e32 v20, vcc, s95, v16
	v_or_b32_e32 v3, 8, v2
	s_nop 0
	v_addc_co_u32_e32 v21, vcc, 0, v17, vcc
	flat_load_ushort v46, v[6:7]
	flat_load_ushort v47, v[8:9] offset:3072
	flat_load_ushort v48, v[4:5] offset:2048
	flat_load_ushort v49, v[12:13]
	flat_load_ushort v50, v[14:15] offset:3072
	flat_load_ushort v51, v[10:11] offset:2048
	flat_load_ushort v52, v[18:19]
	flat_load_ushort v53, v[20:21] offset:3072
	v_xad_u32 v6, v2, -9, s46
	v_cndmask_b32_e64 v3, v6, v3, s[4:5]
	v_add_u32_e32 v6, s47, v3
	v_ashrrev_i32_e32 v7, 31, v6
	v_lshlrev_b64 v[6:7], 15, v[6:7]
	v_lshl_add_u64 v[6:7], s[6:7], 0, v[6:7]
	v_lshl_add_u64 v[8:9], v[6:7], 0, s[44:45]
	v_or_b32_e32 v3, 9, v2
	v_xad_u32 v12, v2, -10, s46
	v_add_co_u32_e32 v4, vcc, s25, v16
	v_lshl_add_u64 v[8:9], v[8:9], 0, s[30:31]
	v_cndmask_b32_e64 v3, v12, v3, s[4:5]
	v_addc_co_u32_e32 v5, vcc, 0, v17, vcc
	v_lshl_add_u64 v[8:9], v[8:9], 0, v[208:209]
	v_add_u32_e32 v12, s47, v3
	v_add_co_u32_e32 v8, vcc, s25, v8
	v_lshl_add_u64 v[6:7], v[6:7], 0, s[30:31]
	v_ashrrev_i32_e32 v13, 31, v12
	v_addc_co_u32_e32 v9, vcc, 0, v9, vcc
	v_lshl_add_u64 v[6:7], v[6:7], 0, v[208:209]
	v_lshlrev_b64 v[12:13], 15, v[12:13]
	v_add_co_u32_e32 v10, vcc, s95, v6
	v_lshl_add_u64 v[12:13], s[6:7], 0, v[12:13]
	s_nop 0
	v_addc_co_u32_e32 v11, vcc, 0, v7, vcc
	v_lshl_add_u64 v[14:15], v[12:13], 0, s[44:45]
	v_or_b32_e32 v3, 10, v2
	v_xad_u32 v18, v2, -11, s46
	v_add_co_u32_e32 v6, vcc, s25, v6
	v_lshl_add_u64 v[14:15], v[14:15], 0, s[30:31]
	v_cndmask_b32_e64 v3, v18, v3, s[4:5]
	v_addc_co_u32_e32 v7, vcc, 0, v7, vcc
	v_lshl_add_u64 v[14:15], v[14:15], 0, v[208:209]
	v_add_u32_e32 v18, s47, v3
	v_add_co_u32_e32 v14, vcc, s25, v14
	v_lshl_add_u64 v[12:13], v[12:13], 0, s[30:31]
	v_ashrrev_i32_e32 v19, 31, v18
	v_addc_co_u32_e32 v15, vcc, 0, v15, vcc
	v_lshl_add_u64 v[12:13], v[12:13], 0, v[208:209]
	v_lshlrev_b64 v[18:19], 15, v[18:19]
	v_add_co_u32_e32 v16, vcc, s95, v12
	v_lshl_add_u64 v[18:19], s[6:7], 0, v[18:19]
	s_nop 0
	v_addc_co_u32_e32 v17, vcc, 0, v13, vcc
	v_lshl_add_u64 v[20:21], v[18:19], 0, s[44:45]
	v_add_co_u32_e32 v12, vcc, s25, v12
	v_lshl_add_u64 v[20:21], v[20:21], 0, s[30:31]
	s_nop 0
	v_addc_co_u32_e32 v13, vcc, 0, v13, vcc
	v_lshl_add_u64 v[20:21], v[20:21], 0, v[208:209]
	v_add_co_u32_e32 v20, vcc, s25, v20
	v_or_b32_e32 v3, 11, v2
	s_nop 0
	v_addc_co_u32_e32 v21, vcc, 0, v21, vcc
	flat_load_ushort v54, v[4:5] offset:2048
	flat_load_ushort v55, v[8:9]
	flat_load_ushort v56, v[10:11] offset:3072
	flat_load_ushort v57, v[6:7] offset:2048
	flat_load_ushort v58, v[14:15]
	flat_load_ushort v59, v[16:17] offset:3072
	flat_load_ushort v60, v[12:13] offset:2048
	s_nop 0
	flat_load_ushort v21, v[20:21]
	v_xad_u32 v8, v2, -12, s46
	v_cndmask_b32_e64 v3, v8, v3, s[4:5]
	v_add_u32_e32 v8, s47, v3
	v_lshl_add_u64 v[4:5], v[18:19], 0, s[30:31]
	v_ashrrev_i32_e32 v9, 31, v8
	v_lshl_add_u64 v[4:5], v[4:5], 0, v[208:209]
	v_lshlrev_b64 v[8:9], 15, v[8:9]
	v_add_co_u32_e32 v6, vcc, s95, v4
	v_lshl_add_u64 v[8:9], s[6:7], 0, v[8:9]
	s_nop 0
	v_addc_co_u32_e32 v7, vcc, 0, v5, vcc
	v_lshl_add_u64 v[10:11], v[8:9], 0, s[44:45]
	v_or_b32_e32 v3, 12, v2
	v_xad_u32 v14, v2, -13, s46
	v_add_co_u32_e32 v4, vcc, s25, v4
	v_lshl_add_u64 v[10:11], v[10:11], 0, s[30:31]
	v_cndmask_b32_e64 v3, v14, v3, s[4:5]
	v_addc_co_u32_e32 v5, vcc, 0, v5, vcc
	v_lshl_add_u64 v[10:11], v[10:11], 0, v[208:209]
	v_add_u32_e32 v14, s47, v3
	v_add_co_u32_e32 v10, vcc, s25, v10
	v_lshl_add_u64 v[8:9], v[8:9], 0, s[30:31]
	v_ashrrev_i32_e32 v15, 31, v14
	v_addc_co_u32_e32 v11, vcc, 0, v11, vcc
	v_lshl_add_u64 v[8:9], v[8:9], 0, v[208:209]
	v_lshlrev_b64 v[14:15], 15, v[14:15]
	v_add_co_u32_e32 v12, vcc, s95, v8
	v_lshl_add_u64 v[14:15], s[6:7], 0, v[14:15]
	s_nop 0
	v_addc_co_u32_e32 v13, vcc, 0, v9, vcc
	v_lshl_add_u64 v[16:17], v[14:15], 0, s[44:45]
	v_add_co_u32_e32 v8, vcc, s25, v8
	v_lshl_add_u64 v[16:17], v[16:17], 0, s[30:31]
	s_nop 0
	v_addc_co_u32_e32 v9, vcc, 0, v9, vcc
	v_lshl_add_u64 v[16:17], v[16:17], 0, v[208:209]
	v_add_co_u32_e32 v16, vcc, s25, v16
	v_lshl_add_u64 v[14:15], v[14:15], 0, s[30:31]
	s_nop 0
	v_addc_co_u32_e32 v17, vcc, 0, v17, vcc
	v_lshl_add_u64 v[14:15], v[14:15], 0, v[208:209]
	v_add_co_u32_e32 v18, vcc, s95, v14
	v_or_b32_e32 v3, 13, v2
	s_nop 0
	v_addc_co_u32_e32 v19, vcc, 0, v15, vcc
	v_add_co_u32_e32 v14, vcc, s25, v14
	s_waitcnt vmcnt(0) lgkmcnt(0)
; DI float bf2f(bfr v) { return __uint_as_float(((unsigned)v) << 16); }
; DI float sigmoidf_(float x) { return 1.f / (1.f + __expf(-x)); }
; DI void hg_prep_unit(const Params& p, int l, int unit, unsigned char* smem) {
;     ...
;     const float lbv = ((const float*)(WS_ + O_LB))[(l * 2 + dir) * 512 + hd * 128 + dk];
;     float G[16], KK[16], Q[16];
;     unsigned vv[8];
; #pragma unroll
;     for (int i = 0; i < 16; ++i) {
;       const int pos = 32 * m + i0 + i, t = dir ? T - 1 - pos : pos;
;       const size_t row = rowbase + t;
;       KK[i] = bf2f(P[row * PLD + C_HGF + dir * 512 + hd * 128 + dk]);
;       Q[i] = bf2f(P[row * PLD + C_HGQ + hd * 128 + dk]);
;       const unsigned x = P[row * PLD + C_HGI + hd * 128 + dk];
;       if (i & 1) vv[i >> 1] |= x << 16; else vv[i >> 1] = x;
;     }
;     float cum = 0.f;
; #pragma unroll
;     for (int i = 0; i < 16; ++i) {
;       const float kkv = fminf((1.f - lbv) * sigmoidf_(-KK[i]), 0.9999999f);
;       KK[i] = kkv;
;       cum += log1pf(-kkv);
;       G[i] = cum;
	v_lshlrev_b32_e32 v41, 16, v38
	v_addc_co_u32_e32 v15, vcc, 0, v15, vcc
	flat_load_ushort v61, v[6:7] offset:3072
	flat_load_ushort v62, v[4:5] offset:2048
	flat_load_ushort v63, v[10:11]
	flat_load_ushort v64, v[12:13] offset:3072
	flat_load_ushort v65, v[8:9] offset:2048
	s_nop 0
	flat_load_ushort v17, v[16:17]
	s_nop 0
	flat_load_ushort v66, v[18:19] offset:3072
	flat_load_ushort v67, v[14:15] offset:2048
	v_xad_u32 v4, v2, -14, s46
	v_cndmask_b32_e64 v3, v4, v3, s[4:5]
	v_add_u32_e32 v4, s47, v3
	v_ashrrev_i32_e32 v5, 31, v4
	v_lshlrev_b64 v[4:5], 15, v[4:5]
	v_or_b32_e32 v3, 14, v2
	v_xad_u32 v10, v2, -15, s46
	v_lshl_add_u64 v[4:5], s[6:7], 0, v[4:5]
	v_cndmask_b32_e64 v3, v10, v3, s[4:5]
	v_lshl_add_u64 v[6:7], v[4:5], 0, s[44:45]
	v_add_u32_e32 v10, s47, v3
	v_lshl_add_u64 v[6:7], v[6:7], 0, s[30:31]
	v_ashrrev_i32_e32 v11, 31, v10
	v_lshl_add_u64 v[6:7], v[6:7], 0, v[208:209]
	v_lshlrev_b64 v[10:11], 15, v[10:11]
	v_or_b32_e32 v3, 15, v2
	v_xad_u32 v2, v2, -16, s46
	v_add_co_u32_e32 v6, vcc, s25, v6
	v_lshl_add_u64 v[4:5], v[4:5], 0, s[30:31]
	v_lshl_add_u64 v[10:11], s[6:7], 0, v[10:11]
	v_cndmask_b32_e64 v2, v2, v3, s[4:5]
	v_addc_co_u32_e32 v7, vcc, 0, v7, vcc
	v_lshl_add_u64 v[8:9], v[4:5], 0, v[208:209]
	v_lshl_add_u64 v[12:13], v[10:11], 0, s[44:45]
	v_add_u32_e32 v2, s47, v2
	v_add_co_u32_e32 v4, vcc, s25, v8
	v_lshl_add_u64 v[12:13], v[12:13], 0, s[30:31]
	v_ashrrev_i32_e32 v3, 31, v2
	v_addc_co_u32_e32 v5, vcc, 0, v9, vcc
	v_lshl_add_u64 v[12:13], v[12:13], 0, v[208:209]
	v_lshlrev_b64 v[2:3], 15, v[2:3]
	v_add_co_u32_e32 v12, vcc, s25, v12
	v_lshl_add_u64 v[10:11], v[10:11], 0, s[30:31]
	v_lshl_add_u64 v[2:3], s[6:7], 0, v[2:3]
	v_addc_co_u32_e32 v13, vcc, 0, v13, vcc
	v_lshl_add_u64 v[24:25], v[10:11], 0, v[208:209]
	v_lshl_add_u64 v[14:15], v[2:3], 0, s[44:45]
	v_add_co_u32_e32 v10, vcc, s25, v24
	v_lshl_add_u64 v[14:15], v[14:15], 0, s[30:31]
	s_nop 0
	v_addc_co_u32_e32 v11, vcc, 0, v25, vcc
	v_lshl_add_u64 v[14:15], v[14:15], 0, v[208:209]
	v_add_co_u32_e32 v14, vcc, s25, v14
	v_lshl_add_u64 v[2:3], v[2:3], 0, s[30:31]
	s_nop 0
	v_addc_co_u32_e32 v15, vcc, 0, v15, vcc
	flat_load_ushort v68, v[6:7]
	flat_load_ushort v69, v[4:5] offset:2048
	flat_load_ushort v70, v[12:13]
	s_nop 0
	flat_load_ushort v10, v[10:11] offset:2048
	s_nop 0
	flat_load_ushort v71, v[14:15]
	v_lshl_add_u64 v[6:7], v[2:3], 0, v[208:209]
	v_add_co_u32_e32 v2, vcc, s25, v6
	v_lshlrev_b32_e32 v12, 16, v40
	s_nop 0
	v_addc_co_u32_e32 v3, vcc, 0, v7, vcc
	flat_load_ushort v72, v[2:3] offset:2048
	flat_load_dword v73, v[0:1]
	v_add_co_u32_e32 v8, vcc, s95, v8
	v_lshlrev_b32_e32 v40, 16, v44
	s_nop 0
	v_addc_co_u32_e32 v9, vcc, 0, v9, vcc
	v_add_co_u32_e32 v24, vcc, s95, v24
	v_lshlrev_b32_e32 v14, 16, v46
	s_nop 0
	v_addc_co_u32_e32 v25, vcc, 0, v25, vcc
	v_add_co_u32_e32 v6, vcc, s95, v6
	v_lshl_or_b32 v2, v48, 16, v45
	s_nop 0
	v_addc_co_u32_e32 v7, vcc, 0, v7, vcc
	flat_load_ushort v44, v[6:7] offset:3072
	flat_load_ushort v45, v[24:25] offset:3072
	flat_load_ushort v46, v[8:9] offset:3072
	v_mul_f32_e32 v6, 0x3fb8aa3b, v74
	v_exp_f32_e32 v7, v6
	s_waitcnt vmcnt(0) lgkmcnt(0)
	v_lshlrev_b32_e32 v22, 16, v17
	v_lshl_or_b32 v1, v39, 16, v36
	v_lshlrev_b32_e32 v39, 16, v47
	v_add_f32_e32 v8, 1.0, v7
	v_div_scale_f32 v9, s[6:7], v8, v8, 1.0
	v_rcp_f32_e32 v17, v9
	v_lshlrev_b32_e32 v13, 16, v49
	s_mov_b32 s25, 0x3f2aaaab
	v_lshlrev_b32_e32 v38, 16, v50
	v_lshlrev_b32_e32 v36, 16, v56
	v_lshl_or_b32 v4, v60, 16, v57
	v_lshlrev_b32_e32 v15, 16, v52
	v_lshl_or_b32 v3, v54, 16, v51
	v_lshlrev_b32_e32 v11, 16, v37
	v_lshlrev_b32_e32 v37, 16, v53
	v_lshlrev_b32_e32 v18, 16, v55
	v_lshlrev_b32_e32 v20, 16, v58
	s_mov_b32 s30, 0x3f317218
	v_lshlrev_b32_e32 v16, 16, v35
	v_lshlrev_b32_e32 v35, 16, v59
	v_lshlrev_b32_e32 v75, 16, v34
	v_lshlrev_b32_e32 v34, 16, v61
	v_lshlrev_b32_e32 v27, 16, v27
	s_mov_b32 s31, 0xff800000
	s_mov_b32 s44, 0x33800000
	v_lshlrev_b32_e32 v19, 16, v21
	v_lshlrev_b32_e32 v21, 16, v63
	v_lshl_or_b32 v5, v65, 16, v62
	v_mul_f32_e32 v11, 0x3fb8aa3b, v11
	v_exp_f32_e32 v11, v11
	v_mul_f32_e32 v12, 0x3fb8aa3b, v12
	v_exp_f32_e32 v12, v12
	v_mul_f32_e32 v14, 0x3fb8aa3b, v14
	v_add_f32_e32 v11, 1.0, v11
	v_exp_f32_e32 v14, v14
	v_add_f32_e32 v12, 1.0, v12
	v_lshl_or_b32 v0, v33, 16, v26
	v_lshlrev_b32_e32 v33, 16, v64
	v_add_f32_e32 v14, 1.0, v14
	v_mul_f32_e32 v13, 0x3fb8aa3b, v13
	v_exp_f32_e32 v13, v13
	v_mul_f32_e32 v15, 0x3fb8aa3b, v15
	v_exp_f32_e32 v15, v15
	v_lshlrev_b32_e32 v42, 16, v32
	v_add_f32_e32 v13, 1.0, v13
	v_lshlrev_b32_e32 v32, 16, v66
	v_add_f32_e32 v15, 1.0, v15
	v_mul_f32_e32 v18, 0x3fb8aa3b, v18
	v_exp_f32_e32 v18, v18
	v_mul_f32_e32 v20, 0x3fb8aa3b, v20
	v_lshl_or_b32 v6, v69, 16, v67
	v_exp_f32_e32 v20, v20
	v_add_f32_e32 v18, 1.0, v18
	v_lshlrev_b32_e32 v24, 16, v68
	v_mul_f32_e32 v19, 0x3fb8aa3b, v19
	v_add_f32_e32 v20, 1.0, v20
	v_exp_f32_e32 v19, v19
	v_lshlrev_b32_e32 v43, 16, v23
	v_lshlrev_b32_e32 v23, 16, v70
	v_lshl_or_b32 v7, v72, 16, v10
	v_fma_f32 v10, -v9, v17, 1.0
	v_fmac_f32_e32 v17, v10, v17
	v_div_scale_f32 v10, vcc, 1.0, v8, 1.0
	v_mul_f32_e32 v47, v10, v17
	v_fma_f32 v48, -v9, v47, v10
	v_fmac_f32_e32 v47, v48, v17
	v_fma_f32 v9, -v9, v47, v10
	v_div_fmas_f32 v9, v9, v17, v47
	v_sub_f32_e32 v25, 1.0, v73
	v_div_fixup_f32 v8, v9, v8, 1.0
	v_mul_f32_e32 v8, v25, v8
	v_min_f32_e32 v8, 0x3f7ffffe, v8
	v_sub_f32_e32 v9, 1.0, v8
	v_add_f32_e32 v10, -1.0, v9
	v_sub_f32_e32 v17, v10, v9
	v_add_f32_e32 v17, 1.0, v17
	v_sub_f32_e64 v10, -v8, v10
	v_add_f32_e32 v10, v10, v17
	v_frexp_mant_f32_e32 v17, v9
	v_cvt_f64_f32_e32 v[48:49], v9
	v_frexp_exp_i32_f64_e32 v47, v[48:49]
	v_cmp_gt_f32_e32 vcc, s25, v17
; DI float sigmoidf_(float x) { return 1.f / (1.f + __expf(-x)); }
; DI void hg_prep_unit(const Params& p, int l, int unit, unsigned char* smem) {
;     ...
;     float cum = 0.f;
; #pragma unroll
;     for (int i = 0; i < 16; ++i) {
;       const float kkv = fminf((1.f - lbv) * sigmoidf_(-KK[i]), 0.9999999f);
;       KK[i] = kkv;
;       cum += log1pf(-kkv);
;       G[i] = cum;
;     }
	v_add_f32_e32 v19, 1.0, v19
	v_lshlrev_b32_e32 v26, 16, v71
	v_subbrev_co_u32_e32 v17, vcc, 0, v47, vcc
	v_sub_u32_e32 v47, 0, v17
	v_ldexp_f32 v9, v9, v47
	v_ldexp_f32 v10, v10, v47
	v_add_f32_e32 v47, -1.0, v9
	v_add_f32_e32 v49, 1.0, v9
	v_add_f32_e32 v48, 1.0, v47
	v_add_f32_e32 v50, -1.0, v49
	v_sub_f32_e32 v48, v9, v48
	v_sub_f32_e32 v9, v9, v50
	v_add_f32_e32 v9, v10, v9
	v_add_f32_e32 v48, v10, v48
	v_add_f32_e32 v10, v49, v9
	v_rcp_f32_e32 v56, v10
	v_sub_f32_e32 v49, v10, v49
	v_sub_f32_e32 v9, v9, v49
	v_add_f32_e32 v49, v47, v48
	v_mul_f32_e32 v57, v49, v56
	v_mul_f32_e32 v50, v10, v57
	v_fma_f32 v52, v57, v10, -v50
	v_sub_f32_e32 v47, v49, v47
	v_fmac_f32_e32 v52, v57, v9
	v_sub_f32_e32 v47, v48, v47
	v_add_f32_e32 v48, v50, v52
	v_sub_f32_e32 v51, v49, v48
	v_pk_add_f32 v[54:55], v[48:49], v[50:51] neg_lo:[0,1] neg_hi:[0,1]
	v_mov_b32_e32 v53, v48
	v_pk_add_f32 v[48:49], v[54:55], v[52:53] neg_lo:[0,1] neg_hi:[0,1]
	v_cmp_neq_f32_e32 vcc, s31, v8
	v_add_f32_e32 v47, v47, v49
	v_add_f32_e32 v47, v48, v47
	v_add_f32_e32 v49, v51, v47
	v_mul_f32_e32 v58, v56, v49
	v_mul_f32_e32 v50, v10, v58
	v_fma_f32 v52, v58, v10, -v50
	v_fmac_f32_e32 v52, v58, v9
	v_add_f32_e32 v48, v50, v52
	v_sub_f32_e32 v9, v51, v49
	v_sub_f32_e32 v51, v49, v48
	v_pk_add_f32 v[54:55], v[48:49], v[50:51] neg_lo:[0,1] neg_hi:[0,1]
	v_mov_b32_e32 v53, v48
	v_add_f32_e32 v9, v47, v9
	v_pk_add_f32 v[48:49], v[54:55], v[52:53] neg_lo:[0,1] neg_hi:[0,1]
	v_add_f32_e32 v10, v57, v58
	v_add_f32_e32 v9, v9, v49
	v_add_f32_e32 v9, v48, v9
	v_add_f32_e32 v9, v51, v9
	v_sub_f32_e32 v47, v10, v57
	v_mul_f32_e32 v9, v56, v9
	v_sub_f32_e32 v47, v58, v47
	v_add_f32_e32 v9, v47, v9
	v_add_f32_e32 v47, v10, v9
	v_mul_f32_e32 v49, v47, v47
	v_fmamk_f32 v48, v49, 0x3e9b6dac, v212
	v_fmaak_f32 v211, v49, v48, 0x3f2aaada
	v_cvt_f32_i32_e32 v48, v17
	v_mul_f32_e32 v49, v47, v49
	v_ldexp_f32 v51, v47, 1
	v_sub_f32_e32 v10, v47, v10
	v_pk_mul_f32 v[52:53], v[48:49], v[210:211]
	v_sub_f32_e32 v9, v9, v10
	v_fma_f32 v50, v48, s30, -v52
	v_fmac_f32_e32 v50, 0xb102e308, v48
	v_pk_add_f32 v[48:49], v[52:53], v[50:51]
	v_ldexp_f32 v9, v9, 1
	v_sub_f32_e32 v10, v49, v51
	v_sub_f32_e32 v10, v53, v10
	v_add_f32_e32 v55, v9, v10
	v_mov_b32_e32 v54, v52
	v_pk_add_f32 v[52:53], v[48:49], v[52:53] neg_lo:[0,1] neg_hi:[0,1]
	v_pk_add_f32 v[56:57], v[48:49], v[54:55]
	v_mov_b32_e32 v51, v48
	v_mov_b32_e32 v53, v57
	v_pk_add_f32 v[58:59], v[50:51], v[52:53] neg_lo:[0,1] neg_hi:[0,1]
	v_pk_add_f32 v[50:51], v[50:51], v[52:53]
	v_mov_b32_e32 v54, v55
	v_pk_add_f32 v[52:53], v[50:51], v[48:49] op_sel:[1,0] op_sel_hi:[0,1] neg_lo:[0,1] neg_hi:[0,1]
	v_pk_add_f32 v[60:61], v[56:57], v[52:53] op_sel_hi:[1,0] neg_lo:[0,1] neg_hi:[0,1]
	v_mov_b32_e32 v56, v57
	v_mov_b32_e32 v57, v51
	v_pk_mov_b32 v[52:53], v[48:49], v[52:53] op_sel:[1,0]
	v_mov_b32_e32 v55, v48
	v_pk_add_f32 v[52:53], v[56:57], v[52:53] neg_lo:[0,1] neg_hi:[0,1]
	v_mov_b32_e32 v60, v58
	v_pk_add_f32 v[48:49], v[54:55], v[52:53] neg_lo:[0,1] neg_hi:[0,1]
	v_mul_f32_e32 v10, 0x3fb8aa3b, v27
	v_pk_add_f32 v[52:53], v[60:61], v[48:49]
	v_mov_b32_e32 v59, v51
	v_pk_add_f32 v[54:55], v[52:53], v[52:53] op_sel:[0,1] op_sel_hi:[1,0]
	v_exp_f32_e32 v10, v10
	v_pk_add_f32 v[50:51], v[50:51], v[54:55] op_sel:[1,0] op_sel_hi:[0,1]
	v_mov_b32_e32 v53, v50
	v_pk_add_f32 v[56:57], v[52:53], v[58:59] neg_lo:[0,1] neg_hi:[0,1]
	v_mov_b32_e32 v49, v54
	v_sub_f32_e32 v9, v52, v56
	v_pk_add_f32 v[48:49], v[48:49], v[56:57] neg_lo:[0,1] neg_hi:[0,1]
	v_sub_f32_e32 v9, v58, v9
	v_add_f32_e32 v10, 1.0, v10
	v_add_f32_e32 v9, v48, v9
	v_div_scale_f32 v17, s[6:7], v10, v10, 1.0
	v_add_f32_e32 v9, v9, v49
	v_rcp_f32_e32 v27, v17
	v_add_f32_e32 v9, v50, v9
	v_cndmask_b32_e32 v9, v214, v9, vcc
	v_cmp_lt_f32_e64 s[6:7], |v8|, s44
	v_mul_f32_e32 v21, 0x3fb8aa3b, v21
	v_exp_f32_e32 v21, v21
	v_cndmask_b32_e64 v9, v9, -v8, s[6:7]
	v_add_f32_e32 v47, 0, v9
	v_fma_f32 v9, -v17, v27, 1.0
	v_fmac_f32_e32 v27, v9, v27
	v_div_scale_f32 v9, vcc, 1.0, v10, 1.0
	v_mul_f32_e32 v48, v9, v27
	v_fma_f32 v49, -v17, v48, v9
	v_fmac_f32_e32 v48, v49, v27
	v_fma_f32 v9, -v17, v48, v9
	v_div_fmas_f32 v9, v9, v27, v48
	v_div_fixup_f32 v9, v9, v10, 1.0
	v_mul_f32_e32 v9, v25, v9
	v_min_f32_e32 v10, 0x3f7ffffe, v9
	v_sub_f32_e32 v9, 1.0, v10
	v_add_f32_e32 v17, -1.0, v9
	v_sub_f32_e32 v27, v17, v9
	v_add_f32_e32 v27, 1.0, v27
	v_sub_f32_e64 v17, -v10, v17
	v_add_f32_e32 v17, v17, v27
	v_frexp_mant_f32_e32 v27, v9
	v_cvt_f64_f32_e32 v[48:49], v9
	v_frexp_exp_i32_f64_e32 v48, v[48:49]
	v_cmp_gt_f32_e32 vcc, s25, v27
	v_add_f32_e32 v21, 1.0, v21
	v_mul_f32_e32 v22, 0x3fb8aa3b, v22
	v_subbrev_co_u32_e32 v27, vcc, 0, v48, vcc
	v_sub_u32_e32 v48, 0, v27
	v_ldexp_f32 v9, v9, v48
	v_ldexp_f32 v17, v17, v48
	v_add_f32_e32 v48, -1.0, v9
	v_add_f32_e32 v49, 1.0, v48
	v_sub_f32_e32 v49, v9, v49
	v_add_f32_e32 v50, v17, v49
	v_add_f32_e32 v49, 1.0, v9
	v_add_f32_e32 v51, -1.0, v49
	v_sub_f32_e32 v9, v9, v51
	v_add_f32_e32 v9, v17, v9
	v_add_f32_e32 v17, v49, v9
	v_rcp_f32_e32 v56, v17
	v_sub_f32_e32 v49, v17, v49
	v_sub_f32_e32 v9, v9, v49
	v_add_f32_e32 v49, v48, v50
	v_sub_f32_e32 v48, v49, v48
	v_mul_f32_e32 v58, v49, v56
	v_sub_f32_e32 v57, v50, v48
	v_mul_f32_e32 v50, v17, v58
	v_fma_f32 v52, v58, v17, -v50
	v_fmac_f32_e32 v52, v58, v9
	v_add_f32_e32 v48, v50, v52
	v_sub_f32_e32 v51, v49, v48
	v_pk_add_f32 v[54:55], v[48:49], v[50:51] neg_lo:[0,1] neg_hi:[0,1]
	v_mov_b32_e32 v53, v48
	v_pk_add_f32 v[48:49], v[54:55], v[52:53] neg_lo:[0,1] neg_hi:[0,1]
	v_cmp_neq_f32_e32 vcc, s31, v10
	v_add_f32_e32 v49, v57, v49
	v_add_f32_e32 v48, v48, v49
	v_add_f32_e32 v49, v51, v48
	v_mul_f32_e32 v57, v56, v49
; DI float sigmoidf_(float x) { return 1.f / (1.f + __expf(-x)); }
; DI void hg_prep_unit(const Params& p, int l, int unit, unsigned char* smem) {
;     ...
;     float cum = 0.f;
; #pragma unroll
;     for (int i = 0; i < 16; ++i) {
;       const float kkv = fminf((1.f - lbv) * sigmoidf_(-KK[i]), 0.9999999f);
;       KK[i] = kkv;
;       cum += log1pf(-kkv);
;       G[i] = cum;
;     }
	v_mul_f32_e32 v50, v17, v57
	v_fma_f32 v52, v57, v17, -v50
	v_fmac_f32_e32 v52, v57, v9
	v_sub_f32_e32 v9, v51, v49
	v_add_f32_e32 v9, v48, v9
	v_add_f32_e32 v48, v50, v52
	v_sub_f32_e32 v51, v49, v48
	v_pk_add_f32 v[54:55], v[48:49], v[50:51] neg_lo:[0,1] neg_hi:[0,1]
	v_mov_b32_e32 v53, v48
	v_pk_add_f32 v[48:49], v[54:55], v[52:53] neg_lo:[0,1] neg_hi:[0,1]
	v_add_f32_e32 v17, v58, v57
	v_add_f32_e32 v9, v9, v49
	v_add_f32_e32 v9, v48, v9
	v_add_f32_e32 v9, v51, v9
	v_sub_f32_e32 v48, v17, v58
	v_mul_f32_e32 v9, v56, v9
	v_sub_f32_e32 v48, v57, v48
	v_add_f32_e32 v9, v48, v9
	v_add_f32_e32 v49, v17, v9
	v_mul_f32_e32 v50, v49, v49
	v_fmamk_f32 v48, v50, 0x3e9b6dac, v212
	v_fmaak_f32 v211, v50, v48, 0x3f2aaada
	v_cvt_f32_i32_e32 v48, v27
	v_sub_f32_e32 v17, v49, v17
	v_ldexp_f32 v51, v49, 1
	v_mul_f32_e32 v49, v49, v50
	v_pk_mul_f32 v[52:53], v[48:49], v[210:211]
	v_sub_f32_e32 v9, v9, v17
	v_fma_f32 v50, v48, s30, -v52
	v_fmac_f32_e32 v50, 0xb102e308, v48
	v_pk_add_f32 v[48:49], v[52:53], v[50:51]
	v_ldexp_f32 v9, v9, 1
	v_sub_f32_e32 v17, v49, v51
	v_sub_f32_e32 v17, v53, v17
	v_add_f32_e32 v55, v9, v17
	v_mov_b32_e32 v54, v52
	v_pk_add_f32 v[52:53], v[48:49], v[52:53] neg_lo:[0,1] neg_hi:[0,1]
	v_pk_add_f32 v[56:57], v[48:49], v[54:55]
	v_mov_b32_e32 v51, v48
	v_mov_b32_e32 v53, v57
	v_pk_add_f32 v[58:59], v[50:51], v[52:53] neg_lo:[0,1] neg_hi:[0,1]
	v_pk_add_f32 v[50:51], v[50:51], v[52:53]
	v_mov_b32_e32 v54, v55
	v_pk_add_f32 v[52:53], v[50:51], v[48:49] op_sel:[1,0] op_sel_hi:[0,1] neg_lo:[0,1] neg_hi:[0,1]
	v_pk_add_f32 v[60:61], v[56:57], v[52:53] op_sel_hi:[1,0] neg_lo:[0,1] neg_hi:[0,1]
	v_mov_b32_e32 v56, v57
	v_mov_b32_e32 v57, v51
	v_pk_mov_b32 v[52:53], v[48:49], v[52:53] op_sel:[1,0]
	v_mov_b32_e32 v55, v48
	v_pk_add_f32 v[52:53], v[56:57], v[52:53] neg_lo:[0,1] neg_hi:[0,1]
	v_mov_b32_e32 v60, v58
	v_pk_add_f32 v[48:49], v[54:55], v[52:53] neg_lo:[0,1] neg_hi:[0,1]
	v_mul_f32_e32 v17, 0x3fb8aa3b, v75
	v_pk_add_f32 v[52:53], v[60:61], v[48:49]
	v_mov_b32_e32 v59, v51
	v_pk_add_f32 v[54:55], v[52:53], v[52:53] op_sel:[0,1] op_sel_hi:[1,0]
	v_exp_f32_e32 v17, v17
	v_pk_add_f32 v[50:51], v[50:51], v[54:55] op_sel:[1,0] op_sel_hi:[0,1]
	v_mov_b32_e32 v53, v50
	v_pk_add_f32 v[56:57], v[52:53], v[58:59] neg_lo:[0,1] neg_hi:[0,1]
	v_mov_b32_e32 v49, v54
	v_sub_f32_e32 v9, v52, v56
	v_pk_add_f32 v[48:49], v[48:49], v[56:57] neg_lo:[0,1] neg_hi:[0,1]
	v_sub_f32_e32 v9, v58, v9
	v_add_f32_e32 v17, 1.0, v17
	v_add_f32_e32 v9, v48, v9
	v_div_scale_f32 v27, s[6:7], v17, v17, 1.0
	v_add_f32_e32 v9, v9, v49
	v_rcp_f32_e32 v49, v27
	v_add_f32_e32 v9, v50, v9
	v_cndmask_b32_e32 v9, v214, v9, vcc
	v_cmp_lt_f32_e64 s[6:7], |v10|, s44
	v_exp_f32_e32 v22, v22
	v_mul_f32_e32 v24, 0x3fb8aa3b, v24
	v_cndmask_b32_e64 v9, v9, -v10, s[6:7]
	v_add_f32_e32 v48, v47, v9
	v_fma_f32 v9, -v27, v49, 1.0
	v_fmac_f32_e32 v49, v9, v49
	v_div_scale_f32 v9, vcc, 1.0, v17, 1.0
	v_mul_f32_e32 v50, v9, v49
	v_fma_f32 v51, -v27, v50, v9
	v_fmac_f32_e32 v50, v51, v49
	v_fma_f32 v9, -v27, v50, v9
	v_div_fmas_f32 v9, v9, v49, v50
	v_div_fixup_f32 v9, v9, v17, 1.0
	v_mul_f32_e32 v9, v25, v9
	v_min_f32_e32 v9, 0x3f7ffffe, v9
	v_sub_f32_e32 v17, 1.0, v9
	v_add_f32_e32 v27, -1.0, v17
	v_sub_f32_e32 v49, v27, v17
	v_add_f32_e32 v49, 1.0, v49
	v_sub_f32_e64 v27, -v9, v27
	v_add_f32_e32 v27, v27, v49
	v_frexp_mant_f32_e32 v49, v17
	v_cvt_f64_f32_e32 v[50:51], v17
	v_frexp_exp_i32_f64_e32 v50, v[50:51]
	v_cmp_gt_f32_e32 vcc, s25, v49
	v_add_f32_e32 v22, 1.0, v22
	v_exp_f32_e32 v24, v24
	v_subbrev_co_u32_e32 v49, vcc, 0, v50, vcc
	v_sub_u32_e32 v50, 0, v49
	v_ldexp_f32 v17, v17, v50
	v_ldexp_f32 v27, v27, v50
	v_add_f32_e32 v50, -1.0, v17
	v_add_f32_e32 v51, 1.0, v50
	v_sub_f32_e32 v51, v17, v51
	v_add_f32_e32 v52, v27, v51
	v_add_f32_e32 v51, 1.0, v17
	v_add_f32_e32 v53, -1.0, v51
	v_sub_f32_e32 v17, v17, v53
	v_add_f32_e32 v17, v27, v17
	v_add_f32_e32 v27, v51, v17
	v_rcp_f32_e32 v58, v27
	v_sub_f32_e32 v51, v27, v51
	v_sub_f32_e32 v17, v17, v51
	v_add_f32_e32 v51, v50, v52
	v_sub_f32_e32 v50, v51, v50
	v_mul_f32_e32 v60, v51, v58
	v_sub_f32_e32 v59, v52, v50
	v_mul_f32_e32 v52, v27, v60
	v_fma_f32 v54, v60, v27, -v52
	v_fmac_f32_e32 v54, v60, v17
	v_add_f32_e32 v50, v52, v54
	v_sub_f32_e32 v53, v51, v50
	v_pk_add_f32 v[56:57], v[50:51], v[52:53] neg_lo:[0,1] neg_hi:[0,1]
	v_mov_b32_e32 v55, v50
	v_pk_add_f32 v[50:51], v[56:57], v[54:55] neg_lo:[0,1] neg_hi:[0,1]
	v_cmp_neq_f32_e32 vcc, s31, v9
	v_add_f32_e32 v51, v59, v51
	v_add_f32_e32 v50, v50, v51
	v_add_f32_e32 v51, v53, v50
	v_mul_f32_e32 v59, v58, v51
	v_mul_f32_e32 v52, v27, v59
	v_fma_f32 v54, v59, v27, -v52
	v_fmac_f32_e32 v54, v59, v17
	v_sub_f32_e32 v17, v53, v51
	v_add_f32_e32 v17, v50, v17
	v_add_f32_e32 v50, v52, v54
	v_sub_f32_e32 v53, v51, v50
	v_pk_add_f32 v[56:57], v[50:51], v[52:53] neg_lo:[0,1] neg_hi:[0,1]
	v_mov_b32_e32 v55, v50
	v_pk_add_f32 v[50:51], v[56:57], v[54:55] neg_lo:[0,1] neg_hi:[0,1]
	v_add_f32_e32 v27, v60, v59
	v_add_f32_e32 v17, v17, v51
	v_add_f32_e32 v17, v50, v17
	v_add_f32_e32 v17, v53, v17
	v_sub_f32_e32 v50, v27, v60
	v_mul_f32_e32 v17, v58, v17
	v_sub_f32_e32 v50, v59, v50
	v_add_f32_e32 v17, v50, v17
	v_add_f32_e32 v51, v27, v17
	v_mul_f32_e32 v52, v51, v51
	v_fmamk_f32 v50, v52, 0x3e9b6dac, v212
	v_fmaak_f32 v211, v52, v50, 0x3f2aaada
	v_cvt_f32_i32_e32 v50, v49
	v_sub_f32_e32 v27, v51, v27
	v_ldexp_f32 v53, v51, 1
	v_mul_f32_e32 v51, v51, v52
	v_pk_mul_f32 v[54:55], v[50:51], v[210:211]
	v_sub_f32_e32 v17, v17, v27
	v_fma_f32 v52, v50, s30, -v54
	v_fmac_f32_e32 v52, 0xb102e308, v50
	v_pk_add_f32 v[50:51], v[54:55], v[52:53]
	v_ldexp_f32 v17, v17, 1
	v_sub_f32_e32 v27, v51, v53
; DI float sigmoidf_(float x) { return 1.f / (1.f + __expf(-x)); }
; DI void hg_prep_unit(const Params& p, int l, int unit, unsigned char* smem) {
;     ...
;     float cum = 0.f;
; #pragma unroll
;     for (int i = 0; i < 16; ++i) {
;       const float kkv = fminf((1.f - lbv) * sigmoidf_(-KK[i]), 0.9999999f);
;       KK[i] = kkv;
;       cum += log1pf(-kkv);
;       G[i] = cum;
;     }
	v_sub_f32_e32 v27, v55, v27
	v_add_f32_e32 v57, v17, v27
	v_mov_b32_e32 v56, v54
	v_pk_add_f32 v[54:55], v[50:51], v[54:55] neg_lo:[0,1] neg_hi:[0,1]
	v_pk_add_f32 v[58:59], v[50:51], v[56:57]
	v_mov_b32_e32 v53, v50
	v_mov_b32_e32 v55, v59
	v_pk_add_f32 v[60:61], v[52:53], v[54:55] neg_lo:[0,1] neg_hi:[0,1]
	v_pk_add_f32 v[52:53], v[52:53], v[54:55]
	v_mov_b32_e32 v56, v57
	v_pk_add_f32 v[54:55], v[52:53], v[50:51] op_sel:[1,0] op_sel_hi:[0,1] neg_lo:[0,1] neg_hi:[0,1]
	v_pk_add_f32 v[62:63], v[58:59], v[54:55] op_sel_hi:[1,0] neg_lo:[0,1] neg_hi:[0,1]
	v_mov_b32_e32 v58, v59
	v_mov_b32_e32 v59, v53
	v_pk_mov_b32 v[54:55], v[50:51], v[54:55] op_sel:[1,0]
	v_mov_b32_e32 v57, v50
	v_pk_add_f32 v[54:55], v[58:59], v[54:55] neg_lo:[0,1] neg_hi:[0,1]
	v_mov_b32_e32 v62, v60
	v_pk_add_f32 v[50:51], v[56:57], v[54:55] neg_lo:[0,1] neg_hi:[0,1]
	v_mov_b32_e32 v61, v53
	v_pk_add_f32 v[54:55], v[62:63], v[50:51]
	v_div_scale_f32 v27, s[6:7], v11, v11, 1.0
	v_pk_add_f32 v[56:57], v[54:55], v[54:55] op_sel:[0,1] op_sel_hi:[1,0]
	v_cmp_lt_f32_e64 s[6:7], |v9|, s44
	v_pk_add_f32 v[52:53], v[52:53], v[56:57] op_sel:[1,0] op_sel_hi:[0,1]
	v_mov_b32_e32 v55, v52
	v_pk_add_f32 v[58:59], v[54:55], v[60:61] neg_lo:[0,1] neg_hi:[0,1]
	v_mov_b32_e32 v51, v56
	v_sub_f32_e32 v17, v54, v58
	v_pk_add_f32 v[50:51], v[50:51], v[58:59] neg_lo:[0,1] neg_hi:[0,1]
	v_sub_f32_e32 v17, v60, v17
	v_add_f32_e32 v17, v50, v17
	v_add_f32_e32 v17, v17, v51
	v_rcp_f32_e32 v50, v27
	v_add_f32_e32 v17, v52, v17
	v_cndmask_b32_e32 v17, v214, v17, vcc
	v_cndmask_b32_e64 v17, v17, -v9, s[6:7]
	v_add_f32_e32 v49, v48, v17
	v_fma_f32 v17, -v27, v50, 1.0
	v_fmac_f32_e32 v50, v17, v50
	v_div_scale_f32 v17, vcc, 1.0, v11, 1.0
	v_mul_f32_e32 v51, v17, v50
	v_fma_f32 v52, -v27, v51, v17
	v_fmac_f32_e32 v51, v52, v50
	v_fma_f32 v17, -v27, v51, v17
	v_div_fmas_f32 v17, v17, v50, v51
	v_div_fixup_f32 v11, v17, v11, 1.0
	v_mul_f32_e32 v11, v25, v11
	v_min_f32_e32 v11, 0x3f7ffffe, v11
	v_sub_f32_e32 v17, 1.0, v11
	v_add_f32_e32 v27, -1.0, v17
	v_sub_f32_e32 v50, v27, v17
	v_add_f32_e32 v50, 1.0, v50
	v_sub_f32_e64 v27, -v11, v27
	v_add_f32_e32 v27, v27, v50
	v_frexp_mant_f32_e32 v52, v17
	v_cvt_f64_f32_e32 v[50:51], v17
	v_frexp_exp_i32_f64_e32 v50, v[50:51]
	v_cmp_gt_f32_e32 vcc, s25, v52
	v_add_f32_e32 v24, 1.0, v24
	v_mul_f32_e32 v23, 0x3fb8aa3b, v23
	v_subbrev_co_u32_e32 v58, vcc, 0, v50, vcc
	v_sub_u32_e32 v50, 0, v58
	v_ldexp_f32 v17, v17, v50
	v_ldexp_f32 v27, v27, v50
	v_add_f32_e32 v50, -1.0, v17
	v_add_f32_e32 v51, 1.0, v50
	v_sub_f32_e32 v51, v17, v51
	v_add_f32_e32 v52, v27, v51
	v_add_f32_e32 v51, 1.0, v17
	v_add_f32_e32 v53, -1.0, v51
	v_sub_f32_e32 v17, v17, v53
	v_add_f32_e32 v17, v27, v17
	v_add_f32_e32 v27, v51, v17
	v_rcp_f32_e32 v59, v27
	v_sub_f32_e32 v51, v27, v51
	v_sub_f32_e32 v17, v17, v51
	v_add_f32_e32 v51, v50, v52
	v_sub_f32_e32 v50, v51, v50
	v_mul_f32_e32 v61, v51, v59
	v_sub_f32_e32 v60, v52, v50
	v_mul_f32_e32 v52, v27, v61
	v_fma_f32 v54, v61, v27, -v52
	v_fmac_f32_e32 v54, v61, v17
	v_add_f32_e32 v50, v52, v54
	v_sub_f32_e32 v53, v51, v50
	v_pk_add_f32 v[56:57], v[50:51], v[52:53] neg_lo:[0,1] neg_hi:[0,1]
	v_mov_b32_e32 v55, v50
	v_pk_add_f32 v[50:51], v[56:57], v[54:55] neg_lo:[0,1] neg_hi:[0,1]
	v_cmp_neq_f32_e32 vcc, s31, v11
	v_add_f32_e32 v51, v60, v51
	v_add_f32_e32 v50, v50, v51
	v_add_f32_e32 v51, v53, v50
	v_mul_f32_e32 v60, v59, v51
	v_mul_f32_e32 v52, v27, v60
	v_fma_f32 v54, v60, v27, -v52
	v_fmac_f32_e32 v54, v60, v17
	v_sub_f32_e32 v17, v53, v51
	v_add_f32_e32 v17, v50, v17
	v_add_f32_e32 v50, v52, v54
	v_sub_f32_e32 v53, v51, v50
	v_pk_add_f32 v[56:57], v[50:51], v[52:53] neg_lo:[0,1] neg_hi:[0,1]
	v_mov_b32_e32 v55, v50
	v_pk_add_f32 v[50:51], v[56:57], v[54:55] neg_lo:[0,1] neg_hi:[0,1]
	v_add_f32_e32 v27, v61, v60
	v_add_f32_e32 v17, v17, v51
	v_add_f32_e32 v17, v50, v17
	v_add_f32_e32 v17, v53, v17
	v_sub_f32_e32 v50, v27, v61
	v_mul_f32_e32 v17, v59, v17
	v_sub_f32_e32 v50, v60, v50
	v_add_f32_e32 v17, v50, v17
	v_add_f32_e32 v51, v27, v17
	v_mul_f32_e32 v52, v51, v51
	v_fmamk_f32 v50, v52, 0x3e9b6dac, v212
	v_fmaak_f32 v211, v52, v50, 0x3f2aaada
	v_cvt_f32_i32_e32 v50, v58
	v_sub_f32_e32 v27, v51, v27
	v_ldexp_f32 v53, v51, 1
	v_mul_f32_e32 v51, v51, v52
	v_pk_mul_f32 v[54:55], v[50:51], v[210:211]
	v_sub_f32_e32 v17, v17, v27
	v_fma_f32 v52, v50, s30, -v54
	v_fmac_f32_e32 v52, 0xb102e308, v50
	v_pk_add_f32 v[50:51], v[54:55], v[52:53]
	v_ldexp_f32 v17, v17, 1
	v_sub_f32_e32 v27, v51, v53
	v_sub_f32_e32 v27, v55, v27
	v_add_f32_e32 v57, v17, v27
	v_mov_b32_e32 v56, v54
	v_pk_add_f32 v[54:55], v[50:51], v[54:55] neg_lo:[0,1] neg_hi:[0,1]
	v_pk_add_f32 v[58:59], v[50:51], v[56:57]
	v_mov_b32_e32 v53, v50
	v_mov_b32_e32 v55, v59
	v_pk_add_f32 v[60:61], v[52:53], v[54:55] neg_lo:[0,1] neg_hi:[0,1]
	v_pk_add_f32 v[52:53], v[52:53], v[54:55]
	v_mov_b32_e32 v56, v57
	v_pk_add_f32 v[54:55], v[52:53], v[50:51] op_sel:[1,0] op_sel_hi:[0,1] neg_lo:[0,1] neg_hi:[0,1]
	v_pk_add_f32 v[62:63], v[58:59], v[54:55] op_sel_hi:[1,0] neg_lo:[0,1] neg_hi:[0,1]
	v_mov_b32_e32 v58, v59
	v_mov_b32_e32 v59, v53
	v_pk_mov_b32 v[54:55], v[50:51], v[54:55] op_sel:[1,0]
	v_mov_b32_e32 v57, v50
	v_pk_add_f32 v[54:55], v[58:59], v[54:55] neg_lo:[0,1] neg_hi:[0,1]
	v_mov_b32_e32 v62, v60
	v_pk_add_f32 v[50:51], v[56:57], v[54:55] neg_lo:[0,1] neg_hi:[0,1]
	v_mov_b32_e32 v61, v53
	v_pk_add_f32 v[54:55], v[62:63], v[50:51]
	v_div_scale_f32 v27, s[6:7], v12, v12, 1.0
	v_pk_add_f32 v[56:57], v[54:55], v[54:55] op_sel:[0,1] op_sel_hi:[1,0]
	v_cmp_lt_f32_e64 s[6:7], |v11|, s44
	v_pk_add_f32 v[52:53], v[52:53], v[56:57] op_sel:[1,0] op_sel_hi:[0,1]
	v_mov_b32_e32 v55, v52
; DI float sigmoidf_(float x) { return 1.f / (1.f + __expf(-x)); }
; DI void hg_prep_unit(const Params& p, int l, int unit, unsigned char* smem) {
;     ...
;     float cum = 0.f;
; #pragma unroll
;     for (int i = 0; i < 16; ++i) {
;       const float kkv = fminf((1.f - lbv) * sigmoidf_(-KK[i]), 0.9999999f);
;       KK[i] = kkv;
;       cum += log1pf(-kkv);
;       G[i] = cum;
;     }
	v_pk_add_f32 v[58:59], v[54:55], v[60:61] neg_lo:[0,1] neg_hi:[0,1]
	v_mov_b32_e32 v51, v56
	v_sub_f32_e32 v17, v54, v58
	v_pk_add_f32 v[50:51], v[50:51], v[58:59] neg_lo:[0,1] neg_hi:[0,1]
	v_sub_f32_e32 v17, v60, v17
	v_add_f32_e32 v17, v50, v17
	v_rcp_f32_e32 v50, v27
	v_add_f32_e32 v17, v17, v51
	v_add_f32_e32 v17, v52, v17
	v_cndmask_b32_e32 v17, v214, v17, vcc
	v_fma_f32 v51, -v27, v50, 1.0
	v_fmac_f32_e32 v50, v51, v50
	v_div_scale_f32 v51, vcc, 1.0, v12, 1.0
	v_mul_f32_e32 v52, v51, v50
	v_fma_f32 v53, -v27, v52, v51
	v_fmac_f32_e32 v52, v53, v50
	v_fma_f32 v27, -v27, v52, v51
	v_div_fmas_f32 v27, v27, v50, v52
	v_div_fixup_f32 v12, v27, v12, 1.0
	v_mul_f32_e32 v12, v25, v12
	v_min_f32_e32 v12, 0x3f7ffffe, v12
	v_sub_f32_e32 v27, 1.0, v12
	v_add_f32_e32 v50, -1.0, v27
	v_sub_f32_e32 v51, v50, v27
	v_add_f32_e32 v51, 1.0, v51
	v_sub_f32_e64 v50, -v12, v50
	v_add_f32_e32 v52, v50, v51
	v_frexp_mant_f32_e32 v53, v27
	v_cvt_f64_f32_e32 v[50:51], v27
	v_frexp_exp_i32_f64_e32 v50, v[50:51]
	v_cmp_gt_f32_e32 vcc, s25, v53
	v_cndmask_b32_e64 v17, v17, -v11, s[6:7]
	v_add_f32_e32 v17, v49, v17
	v_subbrev_co_u32_e32 v58, vcc, 0, v50, vcc
	v_sub_u32_e32 v50, 0, v58
	v_ldexp_f32 v27, v27, v50
	v_ldexp_f32 v50, v52, v50
	v_add_f32_e32 v52, -1.0, v27
	v_add_f32_e32 v51, 1.0, v52
	v_sub_f32_e32 v51, v27, v51
	v_add_f32_e32 v53, v50, v51
	v_add_f32_e32 v51, 1.0, v27
	v_add_f32_e32 v54, -1.0, v51
	v_sub_f32_e32 v27, v27, v54
	v_add_f32_e32 v27, v50, v27
	v_add_f32_e32 v59, v51, v27
	v_rcp_f32_e32 v60, v59
	v_sub_f32_e32 v50, v59, v51
	v_add_f32_e32 v51, v52, v53
	v_sub_f32_e32 v27, v27, v50
	v_mul_f32_e32 v62, v51, v60
	v_sub_f32_e32 v50, v51, v52
	v_mul_f32_e32 v52, v59, v62
	v_fma_f32 v54, v62, v59, -v52
	v_fmac_f32_e32 v54, v62, v27
	v_sub_f32_e32 v61, v53, v50
	v_add_f32_e32 v50, v52, v54
	v_sub_f32_e32 v53, v51, v50
	v_pk_add_f32 v[56:57], v[50:51], v[52:53] neg_lo:[0,1] neg_hi:[0,1]
	v_mov_b32_e32 v55, v50
	v_pk_add_f32 v[50:51], v[56:57], v[54:55] neg_lo:[0,1] neg_hi:[0,1]
	v_cmp_neq_f32_e32 vcc, s31, v12
	v_add_f32_e32 v51, v61, v51
	v_add_f32_e32 v50, v50, v51
	v_add_f32_e32 v51, v53, v50
	v_mul_f32_e32 v61, v60, v51
	v_mul_f32_e32 v52, v59, v61
	v_fma_f32 v54, v61, v59, -v52
	v_fmac_f32_e32 v54, v61, v27
	v_sub_f32_e32 v27, v53, v51
	v_add_f32_e32 v27, v50, v27
	v_add_f32_e32 v50, v52, v54
	v_sub_f32_e32 v53, v51, v50
	v_pk_add_f32 v[56:57], v[50:51], v[52:53] neg_lo:[0,1] neg_hi:[0,1]
	v_mov_b32_e32 v55, v50
	v_pk_add_f32 v[50:51], v[56:57], v[54:55] neg_lo:[0,1] neg_hi:[0,1]
	v_exp_f32_e32 v23, v23
	v_add_f32_e32 v27, v27, v51
	v_add_f32_e32 v27, v50, v27
	v_add_f32_e32 v51, v62, v61
	v_add_f32_e32 v27, v53, v27
	v_sub_f32_e32 v50, v51, v62
	v_mul_f32_e32 v27, v60, v27
	v_sub_f32_e32 v50, v61, v50
	v_add_f32_e32 v27, v50, v27
	v_add_f32_e32 v52, v51, v27
	v_mul_f32_e32 v54, v52, v52
	v_fmamk_f32 v50, v54, 0x3e9b6dac, v212
	v_fmaak_f32 v211, v54, v50, 0x3f2aaada
	v_cvt_f32_i32_e32 v50, v58
	v_sub_f32_e32 v51, v52, v51
	v_sub_f32_e32 v27, v27, v51
	v_mul_f32_e32 v51, v52, v54
	v_pk_mul_f32 v[54:55], v[50:51], v[210:211]
	v_ldexp_f32 v53, v52, 1
	v_fma_f32 v52, v50, s30, -v54
	v_fmac_f32_e32 v52, 0xb102e308, v50
	v_pk_add_f32 v[50:51], v[54:55], v[52:53]
	v_ldexp_f32 v27, v27, 1
	v_sub_f32_e32 v53, v51, v53
	v_sub_f32_e32 v53, v55, v53
	v_add_f32_e32 v57, v27, v53
	v_mov_b32_e32 v56, v54
	v_pk_add_f32 v[54:55], v[50:51], v[54:55] neg_lo:[0,1] neg_hi:[0,1]
	v_pk_add_f32 v[58:59], v[50:51], v[56:57]
	v_mov_b32_e32 v53, v50
	v_mov_b32_e32 v55, v59
	v_pk_add_f32 v[60:61], v[52:53], v[54:55] neg_lo:[0,1] neg_hi:[0,1]
	v_pk_add_f32 v[52:53], v[52:53], v[54:55]
	v_mov_b32_e32 v56, v57
	v_pk_add_f32 v[54:55], v[52:53], v[50:51] op_sel:[1,0] op_sel_hi:[0,1] neg_lo:[0,1] neg_hi:[0,1]
	v_pk_add_f32 v[62:63], v[58:59], v[54:55] op_sel_hi:[1,0] neg_lo:[0,1] neg_hi:[0,1]
	v_mov_b32_e32 v58, v59
	v_mov_b32_e32 v59, v53
	v_pk_mov_b32 v[54:55], v[50:51], v[54:55] op_sel:[1,0]
	v_mov_b32_e32 v57, v50
	v_pk_add_f32 v[54:55], v[58:59], v[54:55] neg_lo:[0,1] neg_hi:[0,1]
	v_mov_b32_e32 v62, v60
	v_pk_add_f32 v[50:51], v[56:57], v[54:55] neg_lo:[0,1] neg_hi:[0,1]
	v_mov_b32_e32 v61, v53
	v_pk_add_f32 v[54:55], v[62:63], v[50:51]
	v_add_f32_e32 v23, 1.0, v23
	v_pk_add_f32 v[56:57], v[54:55], v[54:55] op_sel:[0,1] op_sel_hi:[1,0]
	v_mul_f32_e32 v26, 0x3fb8aa3b, v26
	v_pk_add_f32 v[52:53], v[52:53], v[56:57] op_sel:[1,0] op_sel_hi:[0,1]
	v_mov_b32_e32 v55, v52
	v_pk_add_f32 v[58:59], v[54:55], v[60:61] neg_lo:[0,1] neg_hi:[0,1]
	v_mov_b32_e32 v51, v56
	v_sub_f32_e32 v27, v54, v58
	v_pk_add_f32 v[50:51], v[50:51], v[58:59] neg_lo:[0,1] neg_hi:[0,1]
	v_sub_f32_e32 v27, v60, v27
	v_add_f32_e32 v27, v50, v27
	v_add_f32_e32 v27, v27, v51
	v_div_scale_f32 v51, s[6:7], v14, v14, 1.0
	v_add_f32_e32 v27, v52, v27
	v_rcp_f32_e32 v52, v51
	v_cndmask_b32_e32 v27, v214, v27, vcc
	v_cmp_lt_f32_e64 s[6:7], |v12|, s44
	v_exp_f32_e32 v26, v26
	s_nop 0
	v_cndmask_b32_e64 v27, v27, -v12, s[6:7]
	v_add_f32_e32 v50, v17, v27
	v_fma_f32 v27, -v51, v52, 1.0
	v_fmac_f32_e32 v52, v27, v52
	v_div_scale_f32 v27, vcc, 1.0, v14, 1.0
	v_mul_f32_e32 v53, v27, v52
	v_fma_f32 v54, -v51, v53, v27
	v_fmac_f32_e32 v53, v54, v52
	v_fma_f32 v27, -v51, v53, v27
	v_div_fmas_f32 v27, v27, v52, v53
	v_div_fixup_f32 v14, v27, v14, 1.0
	v_mul_f32_e32 v14, v25, v14
	v_min_f32_e32 v14, 0x3f7ffffe, v14
	v_sub_f32_e32 v27, 1.0, v14
	v_add_f32_e32 v51, -1.0, v27
	v_sub_f32_e32 v52, v51, v27
	v_add_f32_e32 v52, 1.0, v52
	v_sub_f32_e64 v51, -v14, v51
	v_add_f32_e32 v51, v51, v52
	v_frexp_mant_f32_e32 v54, v27
	v_cvt_f64_f32_e32 v[52:53], v27
	v_frexp_exp_i32_f64_e32 v52, v[52:53]
	v_cmp_gt_f32_e32 vcc, s25, v54
; DI float sigmoidf_(float x) { return 1.f / (1.f + __expf(-x)); }
; DI void hg_prep_unit(const Params& p, int l, int unit, unsigned char* smem) {
;     ...
;     float cum = 0.f;
; #pragma unroll
;     for (int i = 0; i < 16; ++i) {
;       const float kkv = fminf((1.f - lbv) * sigmoidf_(-KK[i]), 0.9999999f);
;       KK[i] = kkv;
;       cum += log1pf(-kkv);
;       G[i] = cum;
;     }
	v_add_f32_e32 v26, 1.0, v26
	s_nop 0
	v_subbrev_co_u32_e32 v60, vcc, 0, v52, vcc
	v_sub_u32_e32 v52, 0, v60
	v_ldexp_f32 v27, v27, v52
	v_ldexp_f32 v51, v51, v52
	v_add_f32_e32 v52, -1.0, v27
	v_add_f32_e32 v53, 1.0, v52
	v_sub_f32_e32 v53, v27, v53
	v_add_f32_e32 v54, v51, v53
	v_add_f32_e32 v53, 1.0, v27
	v_add_f32_e32 v55, -1.0, v53
	v_sub_f32_e32 v27, v27, v55
	v_add_f32_e32 v27, v51, v27
	v_add_f32_e32 v51, v53, v27
	v_rcp_f32_e32 v61, v51
	v_sub_f32_e32 v53, v51, v53
	v_sub_f32_e32 v27, v27, v53
	v_add_f32_e32 v53, v52, v54
	v_sub_f32_e32 v52, v53, v52
	v_mul_f32_e32 v63, v53, v61
	v_sub_f32_e32 v62, v54, v52
	v_mul_f32_e32 v54, v51, v63
	v_fma_f32 v56, v63, v51, -v54
	v_fmac_f32_e32 v56, v63, v27
	v_add_f32_e32 v52, v54, v56
	v_sub_f32_e32 v55, v53, v52
	v_pk_add_f32 v[58:59], v[52:53], v[54:55] neg_lo:[0,1] neg_hi:[0,1]
	v_mov_b32_e32 v57, v52
	v_pk_add_f32 v[52:53], v[58:59], v[56:57] neg_lo:[0,1] neg_hi:[0,1]
	v_cmp_neq_f32_e32 vcc, s31, v14
	v_add_f32_e32 v53, v62, v53
	v_add_f32_e32 v52, v52, v53
	v_add_f32_e32 v53, v55, v52
	v_mul_f32_e32 v62, v61, v53
	v_mul_f32_e32 v54, v51, v62
	v_fma_f32 v56, v62, v51, -v54
	v_fmac_f32_e32 v56, v62, v27
	v_sub_f32_e32 v27, v55, v53
	v_add_f32_e32 v27, v52, v27
	v_add_f32_e32 v52, v54, v56
	v_sub_f32_e32 v55, v53, v52
	v_pk_add_f32 v[58:59], v[52:53], v[54:55] neg_lo:[0,1] neg_hi:[0,1]
	v_mov_b32_e32 v57, v52
	v_pk_add_f32 v[52:53], v[58:59], v[56:57] neg_lo:[0,1] neg_hi:[0,1]
	v_add_f32_e32 v51, v63, v62
	v_add_f32_e32 v27, v27, v53
	v_add_f32_e32 v27, v52, v27
	v_add_f32_e32 v27, v55, v27
	v_sub_f32_e32 v52, v51, v63
	v_mul_f32_e32 v27, v61, v27
	v_sub_f32_e32 v52, v62, v52
	v_add_f32_e32 v27, v52, v27
	v_add_f32_e32 v53, v51, v27
	v_mul_f32_e32 v54, v53, v53
	v_fmamk_f32 v52, v54, 0x3e9b6dac, v212
	v_fmaak_f32 v211, v54, v52, 0x3f2aaada
	v_cvt_f32_i32_e32 v52, v60
	v_sub_f32_e32 v51, v53, v51
	v_ldexp_f32 v55, v53, 1
	v_mul_f32_e32 v53, v53, v54
	v_pk_mul_f32 v[56:57], v[52:53], v[210:211]
	v_sub_f32_e32 v27, v27, v51
	v_fma_f32 v54, v52, s30, -v56
	v_fmac_f32_e32 v54, 0xb102e308, v52
	v_pk_add_f32 v[52:53], v[56:57], v[54:55]
	v_ldexp_f32 v27, v27, 1
	v_sub_f32_e32 v51, v53, v55
	v_sub_f32_e32 v51, v57, v51
	v_add_f32_e32 v59, v27, v51
	v_mov_b32_e32 v58, v56
	v_pk_add_f32 v[56:57], v[52:53], v[56:57] neg_lo:[0,1] neg_hi:[0,1]
	v_pk_add_f32 v[60:61], v[52:53], v[58:59]
	v_mov_b32_e32 v55, v52
	v_mov_b32_e32 v57, v61
	v_pk_add_f32 v[62:63], v[54:55], v[56:57] neg_lo:[0,1] neg_hi:[0,1]
	v_pk_add_f32 v[54:55], v[54:55], v[56:57]
	v_mov_b32_e32 v58, v59
	v_pk_add_f32 v[56:57], v[54:55], v[52:53] op_sel:[1,0] op_sel_hi:[0,1] neg_lo:[0,1] neg_hi:[0,1]
	v_pk_add_f32 v[64:65], v[60:61], v[56:57] op_sel_hi:[1,0] neg_lo:[0,1] neg_hi:[0,1]
	v_mov_b32_e32 v60, v61
	v_mov_b32_e32 v61, v55
	v_pk_mov_b32 v[56:57], v[52:53], v[56:57] op_sel:[1,0]
	v_mov_b32_e32 v59, v52
	v_pk_add_f32 v[56:57], v[60:61], v[56:57] neg_lo:[0,1] neg_hi:[0,1]
	v_mov_b32_e32 v64, v62
	v_pk_add_f32 v[52:53], v[58:59], v[56:57] neg_lo:[0,1] neg_hi:[0,1]
	v_mov_b32_e32 v63, v55
	v_pk_add_f32 v[56:57], v[64:65], v[52:53]
	s_nop 0
	v_pk_add_f32 v[58:59], v[56:57], v[56:57] op_sel:[0,1] op_sel_hi:[1,0]
	s_nop 0
	v_pk_add_f32 v[54:55], v[54:55], v[58:59] op_sel:[1,0] op_sel_hi:[0,1]
	v_mov_b32_e32 v57, v54
	v_pk_add_f32 v[60:61], v[56:57], v[62:63] neg_lo:[0,1] neg_hi:[0,1]
	v_mov_b32_e32 v53, v58
	v_sub_f32_e32 v27, v56, v60
	v_pk_add_f32 v[52:53], v[52:53], v[60:61] neg_lo:[0,1] neg_hi:[0,1]
	v_sub_f32_e32 v27, v62, v27
	v_add_f32_e32 v27, v52, v27
	v_div_scale_f32 v52, s[6:7], v13, v13, 1.0
	v_add_f32_e32 v27, v27, v53
	v_rcp_f32_e32 v53, v52
	v_add_f32_e32 v27, v54, v27
	v_cndmask_b32_e32 v27, v214, v27, vcc
	v_cmp_lt_f32_e64 s[6:7], |v14|, s44
	s_nop 1
	v_cndmask_b32_e64 v27, v27, -v14, s[6:7]
	v_add_f32_e32 v51, v50, v27
	v_fma_f32 v27, -v52, v53, 1.0
	v_fmac_f32_e32 v53, v27, v53
	v_div_scale_f32 v27, vcc, 1.0, v13, 1.0
	v_mul_f32_e32 v54, v27, v53
	v_fma_f32 v55, -v52, v54, v27
	v_fmac_f32_e32 v54, v55, v53
	v_fma_f32 v27, -v52, v54, v27
	v_div_fmas_f32 v27, v27, v53, v54
	v_div_fixup_f32 v13, v27, v13, 1.0
	v_mul_f32_e32 v13, v25, v13
	v_min_f32_e32 v13, 0x3f7ffffe, v13
	v_sub_f32_e32 v27, 1.0, v13
	v_add_f32_e32 v52, -1.0, v27
	v_sub_f32_e32 v53, v52, v27
	v_add_f32_e32 v53, 1.0, v53
	v_sub_f32_e64 v52, -v13, v52
	v_add_f32_e32 v54, v52, v53
	v_frexp_mant_f32_e32 v55, v27
	v_cvt_f64_f32_e32 v[52:53], v27
	v_frexp_exp_i32_f64_e32 v52, v[52:53]
	v_cmp_gt_f32_e32 vcc, s25, v55
	s_nop 1
	v_subbrev_co_u32_e32 v60, vcc, 0, v52, vcc
	v_sub_u32_e32 v52, 0, v60
	v_ldexp_f32 v27, v27, v52
	v_ldexp_f32 v52, v54, v52
	v_add_f32_e32 v54, -1.0, v27
	v_add_f32_e32 v53, 1.0, v54
	v_sub_f32_e32 v53, v27, v53
	v_add_f32_e32 v55, v52, v53
	v_add_f32_e32 v53, 1.0, v27
	v_add_f32_e32 v56, -1.0, v53
	v_sub_f32_e32 v27, v27, v56
	v_add_f32_e32 v27, v52, v27
	v_add_f32_e32 v61, v53, v27
	v_rcp_f32_e32 v62, v61
	v_sub_f32_e32 v52, v61, v53
	v_add_f32_e32 v53, v54, v55
	v_sub_f32_e32 v27, v27, v52
	v_mul_f32_e32 v64, v53, v62
	v_sub_f32_e32 v52, v53, v54
	v_mul_f32_e32 v54, v61, v64
	v_fma_f32 v56, v64, v61, -v54
	v_fmac_f32_e32 v56, v64, v27
	v_sub_f32_e32 v63, v55, v52
	v_add_f32_e32 v52, v54, v56
	v_sub_f32_e32 v55, v53, v52
	v_pk_add_f32 v[58:59], v[52:53], v[54:55] neg_lo:[0,1] neg_hi:[0,1]
	v_mov_b32_e32 v57, v52
	v_pk_add_f32 v[52:53], v[58:59], v[56:57] neg_lo:[0,1] neg_hi:[0,1]
	v_cmp_neq_f32_e32 vcc, s31, v13
	v_add_f32_e32 v53, v63, v53
	v_add_f32_e32 v52, v52, v53
	v_add_f32_e32 v53, v55, v52
	v_mul_f32_e32 v63, v62, v53
	v_mul_f32_e32 v54, v61, v63
	v_fma_f32 v56, v63, v61, -v54
	v_fmac_f32_e32 v56, v63, v27
	v_sub_f32_e32 v27, v55, v53
; DI float sigmoidf_(float x) { return 1.f / (1.f + __expf(-x)); }
; DI void hg_prep_unit(const Params& p, int l, int unit, unsigned char* smem) {
;     ...
;     float cum = 0.f;
; #pragma unroll
;     for (int i = 0; i < 16; ++i) {
;       const float kkv = fminf((1.f - lbv) * sigmoidf_(-KK[i]), 0.9999999f);
;       KK[i] = kkv;
;       cum += log1pf(-kkv);
;       G[i] = cum;
;     }
	v_add_f32_e32 v27, v52, v27
	v_add_f32_e32 v52, v54, v56
	v_sub_f32_e32 v55, v53, v52
	v_pk_add_f32 v[58:59], v[52:53], v[54:55] neg_lo:[0,1] neg_hi:[0,1]
	v_mov_b32_e32 v57, v52
	v_pk_add_f32 v[52:53], v[58:59], v[56:57] neg_lo:[0,1] neg_hi:[0,1]
	s_nop 0
	v_add_f32_e32 v27, v27, v53
	v_add_f32_e32 v27, v52, v27
	v_add_f32_e32 v53, v64, v63
	v_add_f32_e32 v27, v55, v27
	v_sub_f32_e32 v52, v53, v64
	v_mul_f32_e32 v27, v62, v27
	v_sub_f32_e32 v52, v63, v52
	v_add_f32_e32 v27, v52, v27
	v_add_f32_e32 v54, v53, v27
	v_mul_f32_e32 v56, v54, v54
	v_fmamk_f32 v52, v56, 0x3e9b6dac, v212
	v_fmaak_f32 v211, v56, v52, 0x3f2aaada
	v_cvt_f32_i32_e32 v52, v60
	v_sub_f32_e32 v53, v54, v53
	v_sub_f32_e32 v27, v27, v53
	v_mul_f32_e32 v53, v54, v56
	v_pk_mul_f32 v[56:57], v[52:53], v[210:211]
	v_ldexp_f32 v55, v54, 1
	v_fma_f32 v54, v52, s30, -v56
	v_fmac_f32_e32 v54, 0xb102e308, v52
	v_pk_add_f32 v[52:53], v[56:57], v[54:55]
	v_ldexp_f32 v27, v27, 1
	v_sub_f32_e32 v55, v53, v55
	v_sub_f32_e32 v55, v57, v55
	v_add_f32_e32 v59, v27, v55
	v_mov_b32_e32 v58, v56
	v_pk_add_f32 v[56:57], v[52:53], v[56:57] neg_lo:[0,1] neg_hi:[0,1]
	v_pk_add_f32 v[60:61], v[52:53], v[58:59]
	v_mov_b32_e32 v55, v52
	v_mov_b32_e32 v57, v61
	v_pk_add_f32 v[62:63], v[54:55], v[56:57] neg_lo:[0,1] neg_hi:[0,1]
	v_pk_add_f32 v[54:55], v[54:55], v[56:57]
	v_mov_b32_e32 v58, v59
	v_pk_add_f32 v[56:57], v[54:55], v[52:53] op_sel:[1,0] op_sel_hi:[0,1] neg_lo:[0,1] neg_hi:[0,1]
	v_pk_add_f32 v[64:65], v[60:61], v[56:57] op_sel_hi:[1,0] neg_lo:[0,1] neg_hi:[0,1]
	v_mov_b32_e32 v60, v61
	v_mov_b32_e32 v61, v55
	v_pk_mov_b32 v[56:57], v[52:53], v[56:57] op_sel:[1,0]
	v_mov_b32_e32 v59, v52
	v_pk_add_f32 v[56:57], v[60:61], v[56:57] neg_lo:[0,1] neg_hi:[0,1]
	v_mov_b32_e32 v64, v62
	v_pk_add_f32 v[52:53], v[58:59], v[56:57] neg_lo:[0,1] neg_hi:[0,1]
	v_mov_b32_e32 v63, v55
	v_pk_add_f32 v[56:57], v[64:65], v[52:53]
	s_nop 0
	v_pk_add_f32 v[58:59], v[56:57], v[56:57] op_sel:[0,1] op_sel_hi:[1,0]
	s_nop 0
	v_pk_add_f32 v[54:55], v[54:55], v[58:59] op_sel:[1,0] op_sel_hi:[0,1]
	v_mov_b32_e32 v57, v54
	v_pk_add_f32 v[60:61], v[56:57], v[62:63] neg_lo:[0,1] neg_hi:[0,1]
	v_mov_b32_e32 v53, v58
	v_sub_f32_e32 v27, v56, v60
	v_pk_add_f32 v[52:53], v[52:53], v[60:61] neg_lo:[0,1] neg_hi:[0,1]
	v_sub_f32_e32 v27, v62, v27
	v_add_f32_e32 v27, v52, v27
	v_add_f32_e32 v27, v27, v53
	v_div_scale_f32 v53, s[6:7], v15, v15, 1.0
	v_add_f32_e32 v27, v54, v27
	v_rcp_f32_e32 v54, v53
	v_cndmask_b32_e32 v27, v214, v27, vcc
	v_cmp_lt_f32_e64 s[6:7], |v13|, s44
	s_nop 1
	v_cndmask_b32_e64 v27, v27, -v13, s[6:7]
	v_add_f32_e32 v52, v51, v27
	v_fma_f32 v27, -v53, v54, 1.0
	v_fmac_f32_e32 v54, v27, v54
	v_div_scale_f32 v27, vcc, 1.0, v15, 1.0
	v_mul_f32_e32 v55, v27, v54
	v_fma_f32 v56, -v53, v55, v27
	v_fmac_f32_e32 v55, v56, v54
	v_fma_f32 v27, -v53, v55, v27
	v_div_fmas_f32 v27, v27, v54, v55
	v_div_fixup_f32 v15, v27, v15, 1.0
	v_mul_f32_e32 v15, v25, v15
	v_min_f32_e32 v15, 0x3f7ffffe, v15
	v_sub_f32_e32 v27, 1.0, v15
	v_add_f32_e32 v53, -1.0, v27
	v_sub_f32_e32 v54, v53, v27
	v_add_f32_e32 v54, 1.0, v54
	v_sub_f32_e64 v53, -v15, v53
	v_add_f32_e32 v53, v53, v54
	v_frexp_mant_f32_e32 v56, v27
	v_cvt_f64_f32_e32 v[54:55], v27
	v_frexp_exp_i32_f64_e32 v54, v[54:55]
	v_cmp_gt_f32_e32 vcc, s25, v56
	s_nop 1
	v_subbrev_co_u32_e32 v62, vcc, 0, v54, vcc
	v_sub_u32_e32 v54, 0, v62
	v_ldexp_f32 v27, v27, v54
	v_ldexp_f32 v53, v53, v54
	v_add_f32_e32 v54, -1.0, v27
	v_add_f32_e32 v55, 1.0, v54
	v_sub_f32_e32 v55, v27, v55
	v_add_f32_e32 v56, v53, v55
	v_add_f32_e32 v55, 1.0, v27
	v_add_f32_e32 v57, -1.0, v55
	v_sub_f32_e32 v27, v27, v57
	v_add_f32_e32 v27, v53, v27
	v_add_f32_e32 v53, v55, v27
	v_rcp_f32_e32 v63, v53
	v_sub_f32_e32 v55, v53, v55
	v_sub_f32_e32 v27, v27, v55
	v_add_f32_e32 v55, v54, v56
	v_sub_f32_e32 v54, v55, v54
	v_mul_f32_e32 v65, v55, v63
	v_sub_f32_e32 v64, v56, v54
	v_mul_f32_e32 v56, v53, v65
	v_fma_f32 v58, v65, v53, -v56
	v_fmac_f32_e32 v58, v65, v27
	v_add_f32_e32 v54, v56, v58
	v_sub_f32_e32 v57, v55, v54
	v_pk_add_f32 v[60:61], v[54:55], v[56:57] neg_lo:[0,1] neg_hi:[0,1]
	v_mov_b32_e32 v59, v54
	v_pk_add_f32 v[54:55], v[60:61], v[58:59] neg_lo:[0,1] neg_hi:[0,1]
	v_cmp_neq_f32_e32 vcc, s31, v15
	v_add_f32_e32 v55, v64, v55
	v_add_f32_e32 v54, v54, v55
	v_add_f32_e32 v55, v57, v54
	v_mul_f32_e32 v64, v63, v55
	v_mul_f32_e32 v56, v53, v64
	v_fma_f32 v58, v64, v53, -v56
	v_fmac_f32_e32 v58, v64, v27
	v_sub_f32_e32 v27, v57, v55
	v_add_f32_e32 v27, v54, v27
	v_add_f32_e32 v54, v56, v58
	v_sub_f32_e32 v57, v55, v54
	v_pk_add_f32 v[60:61], v[54:55], v[56:57] neg_lo:[0,1] neg_hi:[0,1]
	v_mov_b32_e32 v59, v54
	v_pk_add_f32 v[54:55], v[60:61], v[58:59] neg_lo:[0,1] neg_hi:[0,1]
	v_add_f32_e32 v53, v65, v64
	v_add_f32_e32 v27, v27, v55
	v_add_f32_e32 v27, v54, v27
	v_add_f32_e32 v27, v57, v27
	v_sub_f32_e32 v54, v53, v65
	v_mul_f32_e32 v27, v63, v27
	v_sub_f32_e32 v54, v64, v54
	v_add_f32_e32 v27, v54, v27
	v_add_f32_e32 v55, v53, v27
	v_mul_f32_e32 v56, v55, v55
	v_fmamk_f32 v54, v56, 0x3e9b6dac, v212
	v_fmaak_f32 v211, v56, v54, 0x3f2aaada
	v_cvt_f32_i32_e32 v54, v62
	v_sub_f32_e32 v53, v55, v53
	v_ldexp_f32 v57, v55, 1
	v_mul_f32_e32 v55, v55, v56
	v_pk_mul_f32 v[58:59], v[54:55], v[210:211]
	v_sub_f32_e32 v27, v27, v53
	v_fma_f32 v56, v54, s30, -v58
	v_fmac_f32_e32 v56, 0xb102e308, v54
	v_pk_add_f32 v[54:55], v[58:59], v[56:57]
	v_ldexp_f32 v27, v27, 1
	v_sub_f32_e32 v53, v55, v57
	v_sub_f32_e32 v53, v59, v53
	v_add_f32_e32 v61, v27, v53
	v_mov_b32_e32 v60, v58
	v_pk_add_f32 v[58:59], v[54:55], v[58:59] neg_lo:[0,1] neg_hi:[0,1]
	v_pk_add_f32 v[62:63], v[54:55], v[60:61]
	v_mov_b32_e32 v57, v54
; DI float sigmoidf_(float x) { return 1.f / (1.f + __expf(-x)); }
; DI void hg_prep_unit(const Params& p, int l, int unit, unsigned char* smem) {
;     ...
;     float cum = 0.f;
; #pragma unroll
;     for (int i = 0; i < 16; ++i) {
;       const float kkv = fminf((1.f - lbv) * sigmoidf_(-KK[i]), 0.9999999f);
;       KK[i] = kkv;
;       cum += log1pf(-kkv);
;       G[i] = cum;
;     }
	v_mov_b32_e32 v59, v63
	v_pk_add_f32 v[64:65], v[56:57], v[58:59] neg_lo:[0,1] neg_hi:[0,1]
	v_pk_add_f32 v[56:57], v[56:57], v[58:59]
	v_mov_b32_e32 v60, v61
	v_pk_add_f32 v[58:59], v[56:57], v[54:55] op_sel:[1,0] op_sel_hi:[0,1] neg_lo:[0,1] neg_hi:[0,1]
	v_pk_add_f32 v[66:67], v[62:63], v[58:59] op_sel_hi:[1,0] neg_lo:[0,1] neg_hi:[0,1]
	v_mov_b32_e32 v62, v63
	v_mov_b32_e32 v63, v57
	v_pk_mov_b32 v[58:59], v[54:55], v[58:59] op_sel:[1,0]
	v_mov_b32_e32 v61, v54
	v_pk_add_f32 v[58:59], v[62:63], v[58:59] neg_lo:[0,1] neg_hi:[0,1]
	v_mov_b32_e32 v66, v64
	v_pk_add_f32 v[54:55], v[60:61], v[58:59] neg_lo:[0,1] neg_hi:[0,1]
	v_mov_b32_e32 v65, v57
	v_pk_add_f32 v[58:59], v[66:67], v[54:55]
	s_nop 0
	v_pk_add_f32 v[60:61], v[58:59], v[58:59] op_sel:[0,1] op_sel_hi:[1,0]
	s_nop 0
	v_pk_add_f32 v[56:57], v[56:57], v[60:61] op_sel:[1,0] op_sel_hi:[0,1]
	v_mov_b32_e32 v59, v56
	v_pk_add_f32 v[62:63], v[58:59], v[64:65] neg_lo:[0,1] neg_hi:[0,1]
	v_mov_b32_e32 v55, v60
	v_sub_f32_e32 v27, v58, v62
	v_pk_add_f32 v[54:55], v[54:55], v[62:63] neg_lo:[0,1] neg_hi:[0,1]
	v_sub_f32_e32 v27, v64, v27
	v_add_f32_e32 v27, v54, v27
	v_div_scale_f32 v54, s[6:7], v18, v18, 1.0
	v_add_f32_e32 v27, v27, v55
	v_rcp_f32_e32 v55, v54
	v_add_f32_e32 v27, v56, v27
	v_cndmask_b32_e32 v27, v214, v27, vcc
	v_cmp_lt_f32_e64 s[6:7], |v15|, s44
	s_nop 1
	v_cndmask_b32_e64 v27, v27, -v15, s[6:7]
	v_add_f32_e32 v53, v52, v27
	v_fma_f32 v27, -v54, v55, 1.0
	v_fmac_f32_e32 v55, v27, v55
	v_div_scale_f32 v27, vcc, 1.0, v18, 1.0
	v_mul_f32_e32 v56, v27, v55
	v_fma_f32 v57, -v54, v56, v27
	v_fmac_f32_e32 v56, v57, v55
	v_fma_f32 v27, -v54, v56, v27
	v_div_fmas_f32 v27, v27, v55, v56
	v_div_fixup_f32 v18, v27, v18, 1.0
	v_mul_f32_e32 v18, v25, v18
	v_min_f32_e32 v18, 0x3f7ffffe, v18
	v_sub_f32_e32 v27, 1.0, v18
	v_add_f32_e32 v54, -1.0, v27
	v_sub_f32_e32 v55, v54, v27
	v_add_f32_e32 v55, 1.0, v55
	v_sub_f32_e64 v54, -v18, v54
	v_add_f32_e32 v56, v54, v55
	v_frexp_mant_f32_e32 v57, v27
	v_cvt_f64_f32_e32 v[54:55], v27
	v_frexp_exp_i32_f64_e32 v54, v[54:55]
	v_cmp_gt_f32_e32 vcc, s25, v57
	s_nop 1
	v_subbrev_co_u32_e32 v62, vcc, 0, v54, vcc
	v_sub_u32_e32 v54, 0, v62
	v_ldexp_f32 v27, v27, v54
	v_ldexp_f32 v54, v56, v54
	v_add_f32_e32 v56, -1.0, v27
	v_add_f32_e32 v55, 1.0, v56
	v_sub_f32_e32 v55, v27, v55
	v_add_f32_e32 v57, v54, v55
	v_add_f32_e32 v55, 1.0, v27
	v_add_f32_e32 v58, -1.0, v55
	v_sub_f32_e32 v27, v27, v58
	v_add_f32_e32 v27, v54, v27
	v_add_f32_e32 v63, v55, v27
	v_rcp_f32_e32 v64, v63
	v_sub_f32_e32 v54, v63, v55
	v_add_f32_e32 v55, v56, v57
	v_sub_f32_e32 v27, v27, v54
	v_mul_f32_e32 v66, v55, v64
	v_sub_f32_e32 v54, v55, v56
	v_mul_f32_e32 v56, v63, v66
	v_fma_f32 v58, v66, v63, -v56
	v_fmac_f32_e32 v58, v66, v27
	v_sub_f32_e32 v65, v57, v54
	v_add_f32_e32 v54, v56, v58
	v_sub_f32_e32 v57, v55, v54
	v_pk_add_f32 v[60:61], v[54:55], v[56:57] neg_lo:[0,1] neg_hi:[0,1]
	v_mov_b32_e32 v59, v54
	v_pk_add_f32 v[54:55], v[60:61], v[58:59] neg_lo:[0,1] neg_hi:[0,1]
	v_cmp_neq_f32_e32 vcc, s31, v18
	v_add_f32_e32 v55, v65, v55
	v_add_f32_e32 v54, v54, v55
	v_add_f32_e32 v55, v57, v54
	v_mul_f32_e32 v65, v64, v55
	v_mul_f32_e32 v56, v63, v65
	v_fma_f32 v58, v65, v63, -v56
	v_fmac_f32_e32 v58, v65, v27
	v_sub_f32_e32 v27, v57, v55
	v_add_f32_e32 v27, v54, v27
	v_add_f32_e32 v54, v56, v58
	v_sub_f32_e32 v57, v55, v54
	v_pk_add_f32 v[60:61], v[54:55], v[56:57] neg_lo:[0,1] neg_hi:[0,1]
	v_mov_b32_e32 v59, v54
	v_pk_add_f32 v[54:55], v[60:61], v[58:59] neg_lo:[0,1] neg_hi:[0,1]
	s_nop 0
	v_add_f32_e32 v27, v27, v55
	v_add_f32_e32 v27, v54, v27
	v_add_f32_e32 v55, v66, v65
	v_add_f32_e32 v27, v57, v27
	v_sub_f32_e32 v54, v55, v66
	v_mul_f32_e32 v27, v64, v27
	v_sub_f32_e32 v54, v65, v54
	v_add_f32_e32 v27, v54, v27
	v_add_f32_e32 v56, v55, v27
	v_mul_f32_e32 v58, v56, v56
	v_fmamk_f32 v54, v58, 0x3e9b6dac, v212
	v_fmaak_f32 v211, v58, v54, 0x3f2aaada
	v_cvt_f32_i32_e32 v54, v62
	v_sub_f32_e32 v55, v56, v55
	v_sub_f32_e32 v27, v27, v55
	v_mul_f32_e32 v55, v56, v58
	v_pk_mul_f32 v[58:59], v[54:55], v[210:211]
	v_ldexp_f32 v57, v56, 1
	v_fma_f32 v56, v54, s30, -v58
	v_fmac_f32_e32 v56, 0xb102e308, v54
	v_pk_add_f32 v[54:55], v[58:59], v[56:57]
	v_ldexp_f32 v27, v27, 1
	v_sub_f32_e32 v57, v55, v57
	v_sub_f32_e32 v57, v59, v57
	v_add_f32_e32 v61, v27, v57
	v_mov_b32_e32 v60, v58
	v_pk_add_f32 v[58:59], v[54:55], v[58:59] neg_lo:[0,1] neg_hi:[0,1]
	v_pk_add_f32 v[62:63], v[54:55], v[60:61]
	v_mov_b32_e32 v57, v54
	v_mov_b32_e32 v59, v63
	v_pk_add_f32 v[64:65], v[56:57], v[58:59] neg_lo:[0,1] neg_hi:[0,1]
	v_pk_add_f32 v[56:57], v[56:57], v[58:59]
	v_mov_b32_e32 v60, v61
	v_pk_add_f32 v[58:59], v[56:57], v[54:55] op_sel:[1,0] op_sel_hi:[0,1] neg_lo:[0,1] neg_hi:[0,1]
	v_pk_add_f32 v[66:67], v[62:63], v[58:59] op_sel_hi:[1,0] neg_lo:[0,1] neg_hi:[0,1]
	v_mov_b32_e32 v62, v63
	v_mov_b32_e32 v63, v57
	v_pk_mov_b32 v[58:59], v[54:55], v[58:59] op_sel:[1,0]
	v_mov_b32_e32 v61, v54
	v_pk_add_f32 v[58:59], v[62:63], v[58:59] neg_lo:[0,1] neg_hi:[0,1]
	v_mov_b32_e32 v66, v64
	v_pk_add_f32 v[54:55], v[60:61], v[58:59] neg_lo:[0,1] neg_hi:[0,1]
	v_mov_b32_e32 v65, v57
	v_pk_add_f32 v[58:59], v[66:67], v[54:55]
	s_nop 0
	v_pk_add_f32 v[60:61], v[58:59], v[58:59] op_sel:[0,1] op_sel_hi:[1,0]
	s_nop 0
	v_pk_add_f32 v[56:57], v[56:57], v[60:61] op_sel:[1,0] op_sel_hi:[0,1]
	v_mov_b32_e32 v59, v56
	v_pk_add_f32 v[62:63], v[58:59], v[64:65] neg_lo:[0,1] neg_hi:[0,1]
	v_mov_b32_e32 v55, v60
	v_sub_f32_e32 v27, v58, v62
	v_pk_add_f32 v[54:55], v[54:55], v[62:63] neg_lo:[0,1] neg_hi:[0,1]
	v_sub_f32_e32 v27, v64, v27
	v_add_f32_e32 v27, v54, v27
	v_add_f32_e32 v27, v27, v55
; DI float sigmoidf_(float x) { return 1.f / (1.f + __expf(-x)); }
; DI void hg_prep_unit(const Params& p, int l, int unit, unsigned char* smem) {
;     ...
;     float cum = 0.f;
; #pragma unroll
;     for (int i = 0; i < 16; ++i) {
;       const float kkv = fminf((1.f - lbv) * sigmoidf_(-KK[i]), 0.9999999f);
;       KK[i] = kkv;
;       cum += log1pf(-kkv);
;       G[i] = cum;
;     }
	v_div_scale_f32 v54, s[6:7], v20, v20, 1.0
	v_add_f32_e32 v27, v56, v27
	v_rcp_f32_e32 v56, v54
	v_cndmask_b32_e32 v27, v214, v27, vcc
	v_cmp_lt_f32_e64 s[6:7], |v18|, s44
	s_nop 1
	v_cndmask_b32_e64 v27, v27, -v18, s[6:7]
	v_add_f32_e32 v55, v53, v27
	v_fma_f32 v27, -v54, v56, 1.0
	v_fmac_f32_e32 v56, v27, v56
	v_div_scale_f32 v27, vcc, 1.0, v20, 1.0
	v_mul_f32_e32 v57, v27, v56
	v_fma_f32 v58, -v54, v57, v27
	v_fmac_f32_e32 v57, v58, v56
	v_fma_f32 v27, -v54, v57, v27
	v_div_fmas_f32 v27, v27, v56, v57
	v_div_fixup_f32 v20, v27, v20, 1.0
	v_mul_f32_e32 v20, v25, v20
	v_min_f32_e32 v20, 0x3f7ffffe, v20
	v_sub_f32_e32 v27, 1.0, v20
	v_add_f32_e32 v54, -1.0, v27
	v_sub_f32_e32 v56, v54, v27
	v_add_f32_e32 v56, 1.0, v56
	v_sub_f32_e64 v54, -v20, v54
	v_add_f32_e32 v54, v54, v56
	v_frexp_mant_f32_e32 v58, v27
	v_cvt_f64_f32_e32 v[56:57], v27
	v_frexp_exp_i32_f64_e32 v56, v[56:57]
	v_cmp_gt_f32_e32 vcc, s25, v58
	s_nop 1
	v_subbrev_co_u32_e32 v64, vcc, 0, v56, vcc
	v_sub_u32_e32 v56, 0, v64
	v_ldexp_f32 v27, v27, v56
	v_ldexp_f32 v54, v54, v56
	v_add_f32_e32 v56, -1.0, v27
	v_add_f32_e32 v57, 1.0, v56
	v_sub_f32_e32 v57, v27, v57
	v_add_f32_e32 v58, v54, v57
	v_add_f32_e32 v57, 1.0, v27
	v_add_f32_e32 v59, -1.0, v57
	v_sub_f32_e32 v27, v27, v59
	v_add_f32_e32 v27, v54, v27
	v_add_f32_e32 v54, v57, v27
	v_rcp_f32_e32 v65, v54
	v_sub_f32_e32 v57, v54, v57
	v_sub_f32_e32 v27, v27, v57
	v_add_f32_e32 v57, v56, v58
	v_sub_f32_e32 v56, v57, v56
	v_mul_f32_e32 v67, v57, v65
	v_sub_f32_e32 v66, v58, v56
	v_mul_f32_e32 v58, v54, v67
	v_fma_f32 v60, v67, v54, -v58
	v_fmac_f32_e32 v60, v67, v27
	v_add_f32_e32 v56, v58, v60
	v_sub_f32_e32 v59, v57, v56
	v_pk_add_f32 v[62:63], v[56:57], v[58:59] neg_lo:[0,1] neg_hi:[0,1]
	v_mov_b32_e32 v61, v56
	v_pk_add_f32 v[56:57], v[62:63], v[60:61] neg_lo:[0,1] neg_hi:[0,1]
	v_cmp_neq_f32_e32 vcc, s31, v20
	v_add_f32_e32 v57, v66, v57
	v_add_f32_e32 v56, v56, v57
	v_add_f32_e32 v57, v59, v56
	v_mul_f32_e32 v66, v65, v57
	v_mul_f32_e32 v58, v54, v66
	v_fma_f32 v60, v66, v54, -v58
	v_fmac_f32_e32 v60, v66, v27
	v_sub_f32_e32 v27, v59, v57
	v_add_f32_e32 v27, v56, v27
	v_add_f32_e32 v56, v58, v60
	v_sub_f32_e32 v59, v57, v56
	v_pk_add_f32 v[62:63], v[56:57], v[58:59] neg_lo:[0,1] neg_hi:[0,1]
	v_mov_b32_e32 v61, v56
	v_pk_add_f32 v[56:57], v[62:63], v[60:61] neg_lo:[0,1] neg_hi:[0,1]
	v_add_f32_e32 v54, v67, v66
	v_add_f32_e32 v27, v27, v57
	v_add_f32_e32 v27, v56, v27
	v_add_f32_e32 v27, v59, v27
	v_sub_f32_e32 v56, v54, v67
	v_mul_f32_e32 v27, v65, v27
	v_sub_f32_e32 v56, v66, v56
	v_add_f32_e32 v27, v56, v27
	v_add_f32_e32 v57, v54, v27
	v_mul_f32_e32 v58, v57, v57
	v_fmamk_f32 v56, v58, 0x3e9b6dac, v212
	v_fmaak_f32 v211, v58, v56, 0x3f2aaada
	v_cvt_f32_i32_e32 v56, v64
	v_sub_f32_e32 v54, v57, v54
	v_ldexp_f32 v59, v57, 1
	v_mul_f32_e32 v57, v57, v58
	v_pk_mul_f32 v[60:61], v[56:57], v[210:211]
	v_sub_f32_e32 v27, v27, v54
	v_fma_f32 v58, v56, s30, -v60
	v_fmac_f32_e32 v58, 0xb102e308, v56
	v_pk_add_f32 v[56:57], v[60:61], v[58:59]
	v_ldexp_f32 v27, v27, 1
	v_sub_f32_e32 v54, v57, v59
	v_sub_f32_e32 v54, v61, v54
	v_add_f32_e32 v63, v27, v54
	v_mov_b32_e32 v62, v60
	v_pk_add_f32 v[60:61], v[56:57], v[60:61] neg_lo:[0,1] neg_hi:[0,1]
	v_pk_add_f32 v[64:65], v[56:57], v[62:63]
	v_mov_b32_e32 v59, v56
	v_mov_b32_e32 v61, v65
	v_pk_add_f32 v[66:67], v[58:59], v[60:61] neg_lo:[0,1] neg_hi:[0,1]
	v_pk_add_f32 v[58:59], v[58:59], v[60:61]
	v_mov_b32_e32 v62, v63
	v_pk_add_f32 v[60:61], v[58:59], v[56:57] op_sel:[1,0] op_sel_hi:[0,1] neg_lo:[0,1] neg_hi:[0,1]
	v_pk_add_f32 v[68:69], v[64:65], v[60:61] op_sel_hi:[1,0] neg_lo:[0,1] neg_hi:[0,1]
	v_mov_b32_e32 v64, v65
	v_mov_b32_e32 v65, v59
	v_pk_mov_b32 v[60:61], v[56:57], v[60:61] op_sel:[1,0]
	v_mov_b32_e32 v63, v56
	v_pk_add_f32 v[60:61], v[64:65], v[60:61] neg_lo:[0,1] neg_hi:[0,1]
	v_mov_b32_e32 v68, v66
	v_pk_add_f32 v[56:57], v[62:63], v[60:61] neg_lo:[0,1] neg_hi:[0,1]
	v_mov_b32_e32 v67, v59
	v_pk_add_f32 v[60:61], v[68:69], v[56:57]
	v_div_scale_f32 v54, s[6:7], v19, v19, 1.0
	v_pk_add_f32 v[62:63], v[60:61], v[60:61] op_sel:[0,1] op_sel_hi:[1,0]
	v_cmp_lt_f32_e64 s[6:7], |v20|, s44
	v_pk_add_f32 v[58:59], v[58:59], v[62:63] op_sel:[1,0] op_sel_hi:[0,1]
	v_mov_b32_e32 v61, v58
	v_pk_add_f32 v[64:65], v[60:61], v[66:67] neg_lo:[0,1] neg_hi:[0,1]
	v_mov_b32_e32 v57, v62
	v_sub_f32_e32 v27, v60, v64
	v_pk_add_f32 v[56:57], v[56:57], v[64:65] neg_lo:[0,1] neg_hi:[0,1]
	v_sub_f32_e32 v27, v66, v27
	v_add_f32_e32 v27, v56, v27
	v_add_f32_e32 v27, v27, v57
	v_rcp_f32_e32 v57, v54
	v_add_f32_e32 v27, v58, v27
	v_cndmask_b32_e32 v27, v214, v27, vcc
	v_cndmask_b32_e64 v27, v27, -v20, s[6:7]
	v_add_f32_e32 v56, v55, v27
	v_fma_f32 v27, -v54, v57, 1.0
	v_fmac_f32_e32 v57, v27, v57
	v_div_scale_f32 v27, vcc, 1.0, v19, 1.0
	v_mul_f32_e32 v58, v27, v57
	v_fma_f32 v59, -v54, v58, v27
	v_fmac_f32_e32 v58, v59, v57
	v_fma_f32 v27, -v54, v58, v27
	v_div_fmas_f32 v27, v27, v57, v58
	v_div_fixup_f32 v19, v27, v19, 1.0
	v_mul_f32_e32 v19, v25, v19
	v_min_f32_e32 v19, 0x3f7ffffe, v19
	v_sub_f32_e32 v27, 1.0, v19
	v_add_f32_e32 v54, -1.0, v27
	v_sub_f32_e32 v57, v54, v27
	v_add_f32_e32 v57, 1.0, v57
	v_sub_f32_e64 v54, -v19, v54
	v_add_f32_e32 v54, v54, v57
	v_frexp_mant_f32_e32 v57, v27
	v_cvt_f64_f32_e32 v[58:59], v27
	v_frexp_exp_i32_f64_e32 v58, v[58:59]
	v_cmp_gt_f32_e32 vcc, s25, v57
	s_nop 1
	v_subbrev_co_u32_e32 v57, vcc, 0, v58, vcc
	v_sub_u32_e32 v58, 0, v57
	v_ldexp_f32 v27, v27, v58
	v_ldexp_f32 v54, v54, v58
	v_add_f32_e32 v58, -1.0, v27
	v_add_f32_e32 v59, 1.0, v58
	v_sub_f32_e32 v59, v27, v59
	v_add_f32_e32 v60, v54, v59
	v_add_f32_e32 v59, 1.0, v27
	v_add_f32_e32 v61, -1.0, v59
; DI float sigmoidf_(float x) { return 1.f / (1.f + __expf(-x)); }
; DI void hg_prep_unit(const Params& p, int l, int unit, unsigned char* smem) {
;     ...
;     float cum = 0.f;
; #pragma unroll
;     for (int i = 0; i < 16; ++i) {
;       const float kkv = fminf((1.f - lbv) * sigmoidf_(-KK[i]), 0.9999999f);
;       KK[i] = kkv;
;       cum += log1pf(-kkv);
;       G[i] = cum;
;     }
	v_sub_f32_e32 v27, v27, v61
	v_add_f32_e32 v27, v54, v27
	v_add_f32_e32 v54, v59, v27
	v_rcp_f32_e32 v66, v54
	v_sub_f32_e32 v59, v54, v59
	v_sub_f32_e32 v27, v27, v59
	v_add_f32_e32 v59, v58, v60
	v_sub_f32_e32 v58, v59, v58
	v_mul_f32_e32 v68, v59, v66
	v_sub_f32_e32 v67, v60, v58
	v_mul_f32_e32 v60, v54, v68
	v_fma_f32 v62, v68, v54, -v60
	v_fmac_f32_e32 v62, v68, v27
	v_add_f32_e32 v58, v60, v62
	v_sub_f32_e32 v61, v59, v58
	v_pk_add_f32 v[64:65], v[58:59], v[60:61] neg_lo:[0,1] neg_hi:[0,1]
	v_mov_b32_e32 v63, v58
	v_pk_add_f32 v[58:59], v[64:65], v[62:63] neg_lo:[0,1] neg_hi:[0,1]
	v_cmp_neq_f32_e32 vcc, s31, v19
	v_add_f32_e32 v59, v67, v59
	v_add_f32_e32 v58, v58, v59
	v_add_f32_e32 v59, v61, v58
	v_mul_f32_e32 v67, v66, v59
	v_mul_f32_e32 v60, v54, v67
	v_fma_f32 v62, v67, v54, -v60
	v_fmac_f32_e32 v62, v67, v27
	v_sub_f32_e32 v27, v61, v59
	v_add_f32_e32 v27, v58, v27
	v_add_f32_e32 v58, v60, v62
	v_sub_f32_e32 v61, v59, v58
	v_pk_add_f32 v[64:65], v[58:59], v[60:61] neg_lo:[0,1] neg_hi:[0,1]
	v_mov_b32_e32 v63, v58
	v_pk_add_f32 v[58:59], v[64:65], v[62:63] neg_lo:[0,1] neg_hi:[0,1]
	v_add_f32_e32 v54, v68, v67
	v_add_f32_e32 v27, v27, v59
	v_add_f32_e32 v27, v58, v27
	v_add_f32_e32 v27, v61, v27
	v_sub_f32_e32 v58, v54, v68
	v_mul_f32_e32 v27, v66, v27
	v_sub_f32_e32 v58, v67, v58
	v_add_f32_e32 v27, v58, v27
	v_add_f32_e32 v59, v54, v27
	v_mul_f32_e32 v60, v59, v59
	v_fmamk_f32 v58, v60, 0x3e9b6dac, v212
	v_fmaak_f32 v211, v60, v58, 0x3f2aaada
	v_cvt_f32_i32_e32 v58, v57
	v_sub_f32_e32 v54, v59, v54
	v_ldexp_f32 v61, v59, 1
	v_mul_f32_e32 v59, v59, v60
	v_pk_mul_f32 v[62:63], v[58:59], v[210:211]
	v_sub_f32_e32 v27, v27, v54
	v_fma_f32 v60, v58, s30, -v62
	v_fmac_f32_e32 v60, 0xb102e308, v58
	v_pk_add_f32 v[58:59], v[62:63], v[60:61]
	v_ldexp_f32 v27, v27, 1
	v_sub_f32_e32 v54, v59, v61
	v_sub_f32_e32 v54, v63, v54
	v_add_f32_e32 v65, v27, v54
	v_mov_b32_e32 v64, v62
	v_pk_add_f32 v[62:63], v[58:59], v[62:63] neg_lo:[0,1] neg_hi:[0,1]
	v_pk_add_f32 v[66:67], v[58:59], v[64:65]
	v_mov_b32_e32 v61, v58
	v_mov_b32_e32 v63, v67
	v_pk_add_f32 v[68:69], v[60:61], v[62:63] neg_lo:[0,1] neg_hi:[0,1]
	v_pk_add_f32 v[60:61], v[60:61], v[62:63]
	v_mov_b32_e32 v64, v65
	v_pk_add_f32 v[62:63], v[60:61], v[58:59] op_sel:[1,0] op_sel_hi:[0,1] neg_lo:[0,1] neg_hi:[0,1]
	v_pk_add_f32 v[70:71], v[66:67], v[62:63] op_sel_hi:[1,0] neg_lo:[0,1] neg_hi:[0,1]
	v_mov_b32_e32 v66, v67
	v_mov_b32_e32 v67, v61
	v_pk_mov_b32 v[62:63], v[58:59], v[62:63] op_sel:[1,0]
	v_mov_b32_e32 v65, v58
	v_pk_add_f32 v[62:63], v[66:67], v[62:63] neg_lo:[0,1] neg_hi:[0,1]
	v_mov_b32_e32 v70, v68
	v_pk_add_f32 v[58:59], v[64:65], v[62:63] neg_lo:[0,1] neg_hi:[0,1]
	v_mov_b32_e32 v69, v61
	v_pk_add_f32 v[62:63], v[70:71], v[58:59]
	v_div_scale_f32 v54, s[6:7], v21, v21, 1.0
	v_pk_add_f32 v[64:65], v[62:63], v[62:63] op_sel:[0,1] op_sel_hi:[1,0]
	v_cmp_lt_f32_e64 s[6:7], |v19|, s44
	v_pk_add_f32 v[60:61], v[60:61], v[64:65] op_sel:[1,0] op_sel_hi:[0,1]
	v_mov_b32_e32 v63, v60
	v_pk_add_f32 v[66:67], v[62:63], v[68:69] neg_lo:[0,1] neg_hi:[0,1]
	v_mov_b32_e32 v59, v64
	v_sub_f32_e32 v27, v62, v66
	v_pk_add_f32 v[58:59], v[58:59], v[66:67] neg_lo:[0,1] neg_hi:[0,1]
	v_sub_f32_e32 v27, v68, v27
	v_add_f32_e32 v27, v58, v27
	v_add_f32_e32 v27, v27, v59
	v_rcp_f32_e32 v58, v54
	v_add_f32_e32 v27, v60, v27
	v_cndmask_b32_e32 v27, v214, v27, vcc
	v_cndmask_b32_e64 v27, v27, -v19, s[6:7]
	v_add_f32_e32 v57, v56, v27
	v_fma_f32 v27, -v54, v58, 1.0
	v_fmac_f32_e32 v58, v27, v58
	v_div_scale_f32 v27, vcc, 1.0, v21, 1.0
	v_mul_f32_e32 v59, v27, v58
	v_fma_f32 v60, -v54, v59, v27
	v_fmac_f32_e32 v59, v60, v58
	v_fma_f32 v27, -v54, v59, v27
	v_div_fmas_f32 v27, v27, v58, v59
	v_div_fixup_f32 v21, v27, v21, 1.0
	v_mul_f32_e32 v21, v25, v21
	v_min_f32_e32 v21, 0x3f7ffffe, v21
	v_sub_f32_e32 v27, 1.0, v21
	v_add_f32_e32 v54, -1.0, v27
	v_sub_f32_e32 v58, v54, v27
	v_add_f32_e32 v58, 1.0, v58
	v_sub_f32_e64 v54, -v21, v54
	v_add_f32_e32 v54, v54, v58
	v_frexp_mant_f32_e32 v60, v27
	v_cvt_f64_f32_e32 v[58:59], v27
	v_frexp_exp_i32_f64_e32 v58, v[58:59]
	v_cmp_gt_f32_e32 vcc, s25, v60
	s_nop 1
	v_subbrev_co_u32_e32 v66, vcc, 0, v58, vcc
	v_sub_u32_e32 v58, 0, v66
	v_ldexp_f32 v27, v27, v58
	v_ldexp_f32 v54, v54, v58
	v_add_f32_e32 v58, -1.0, v27
	v_add_f32_e32 v59, 1.0, v58
	v_sub_f32_e32 v59, v27, v59
	v_add_f32_e32 v60, v54, v59
	v_add_f32_e32 v59, 1.0, v27
	v_add_f32_e32 v61, -1.0, v59
	v_sub_f32_e32 v27, v27, v61
	v_add_f32_e32 v27, v54, v27
	v_add_f32_e32 v54, v59, v27
	v_rcp_f32_e32 v67, v54
	v_sub_f32_e32 v59, v54, v59
	v_sub_f32_e32 v27, v27, v59
	v_add_f32_e32 v59, v58, v60
	v_sub_f32_e32 v58, v59, v58
	v_mul_f32_e32 v69, v59, v67
	v_sub_f32_e32 v68, v60, v58
	v_mul_f32_e32 v60, v54, v69
	v_fma_f32 v62, v69, v54, -v60
	v_fmac_f32_e32 v62, v69, v27
	v_add_f32_e32 v58, v60, v62
	v_sub_f32_e32 v61, v59, v58
	v_pk_add_f32 v[64:65], v[58:59], v[60:61] neg_lo:[0,1] neg_hi:[0,1]
	v_mov_b32_e32 v63, v58
	v_pk_add_f32 v[58:59], v[64:65], v[62:63] neg_lo:[0,1] neg_hi:[0,1]
	v_cmp_neq_f32_e32 vcc, s31, v21
	v_add_f32_e32 v59, v68, v59
	v_add_f32_e32 v58, v58, v59
	v_add_f32_e32 v59, v61, v58
	v_mul_f32_e32 v68, v67, v59
	v_mul_f32_e32 v60, v54, v68
	v_fma_f32 v62, v68, v54, -v60
	v_fmac_f32_e32 v62, v68, v27
	v_sub_f32_e32 v27, v61, v59
	v_add_f32_e32 v27, v58, v27
	v_add_f32_e32 v58, v60, v62
	v_sub_f32_e32 v61, v59, v58
	v_pk_add_f32 v[64:65], v[58:59], v[60:61] neg_lo:[0,1] neg_hi:[0,1]
	v_mov_b32_e32 v63, v58
	v_pk_add_f32 v[58:59], v[64:65], v[62:63] neg_lo:[0,1] neg_hi:[0,1]
	v_add_f32_e32 v54, v69, v68
	v_add_f32_e32 v27, v27, v59
	v_add_f32_e32 v27, v58, v27
	v_add_f32_e32 v27, v61, v27
; DI float sigmoidf_(float x) { return 1.f / (1.f + __expf(-x)); }
; DI void hg_prep_unit(const Params& p, int l, int unit, unsigned char* smem) {
;     ...
;     float cum = 0.f;
; #pragma unroll
;     for (int i = 0; i < 16; ++i) {
;       const float kkv = fminf((1.f - lbv) * sigmoidf_(-KK[i]), 0.9999999f);
;       KK[i] = kkv;
;       cum += log1pf(-kkv);
;       G[i] = cum;
;     }
	v_sub_f32_e32 v58, v54, v69
	v_mul_f32_e32 v27, v67, v27
	v_sub_f32_e32 v58, v68, v58
	v_add_f32_e32 v27, v58, v27
	v_add_f32_e32 v59, v54, v27
	v_mul_f32_e32 v60, v59, v59
	v_fmamk_f32 v58, v60, 0x3e9b6dac, v212
	v_fmaak_f32 v211, v60, v58, 0x3f2aaada
	v_cvt_f32_i32_e32 v58, v66
	v_sub_f32_e32 v54, v59, v54
	v_ldexp_f32 v61, v59, 1
	v_mul_f32_e32 v59, v59, v60
	v_pk_mul_f32 v[62:63], v[58:59], v[210:211]
	v_sub_f32_e32 v27, v27, v54
	v_fma_f32 v60, v58, s30, -v62
	v_fmac_f32_e32 v60, 0xb102e308, v58
	v_pk_add_f32 v[58:59], v[62:63], v[60:61]
	v_ldexp_f32 v27, v27, 1
	v_sub_f32_e32 v54, v59, v61
	v_sub_f32_e32 v54, v63, v54
	v_add_f32_e32 v65, v27, v54
	v_mov_b32_e32 v64, v62
	v_pk_add_f32 v[62:63], v[58:59], v[62:63] neg_lo:[0,1] neg_hi:[0,1]
	v_pk_add_f32 v[66:67], v[58:59], v[64:65]
	v_mov_b32_e32 v61, v58
	v_mov_b32_e32 v63, v67
	v_pk_add_f32 v[68:69], v[60:61], v[62:63] neg_lo:[0,1] neg_hi:[0,1]
	v_pk_add_f32 v[60:61], v[60:61], v[62:63]
	v_mov_b32_e32 v64, v65
	v_pk_add_f32 v[62:63], v[60:61], v[58:59] op_sel:[1,0] op_sel_hi:[0,1] neg_lo:[0,1] neg_hi:[0,1]
	v_pk_add_f32 v[70:71], v[66:67], v[62:63] op_sel_hi:[1,0] neg_lo:[0,1] neg_hi:[0,1]
	v_mov_b32_e32 v66, v67
	v_mov_b32_e32 v67, v61
	v_pk_mov_b32 v[62:63], v[58:59], v[62:63] op_sel:[1,0]
	v_mov_b32_e32 v65, v58
	v_pk_add_f32 v[62:63], v[66:67], v[62:63] neg_lo:[0,1] neg_hi:[0,1]
	v_mov_b32_e32 v70, v68
	v_pk_add_f32 v[58:59], v[64:65], v[62:63] neg_lo:[0,1] neg_hi:[0,1]
	v_mov_b32_e32 v69, v61
	v_pk_add_f32 v[62:63], v[70:71], v[58:59]
	v_div_scale_f32 v54, s[6:7], v22, v22, 1.0
	v_pk_add_f32 v[64:65], v[62:63], v[62:63] op_sel:[0,1] op_sel_hi:[1,0]
	v_cmp_lt_f32_e64 s[6:7], |v21|, s44
	v_pk_add_f32 v[60:61], v[60:61], v[64:65] op_sel:[1,0] op_sel_hi:[0,1]
	v_mov_b32_e32 v63, v60
	v_pk_add_f32 v[66:67], v[62:63], v[68:69] neg_lo:[0,1] neg_hi:[0,1]
	v_mov_b32_e32 v59, v64
	v_sub_f32_e32 v27, v62, v66
	v_pk_add_f32 v[58:59], v[58:59], v[66:67] neg_lo:[0,1] neg_hi:[0,1]
	v_sub_f32_e32 v27, v68, v27
	v_add_f32_e32 v27, v58, v27
	v_add_f32_e32 v27, v27, v59
	v_rcp_f32_e32 v59, v54
	v_add_f32_e32 v27, v60, v27
	v_cndmask_b32_e32 v27, v214, v27, vcc
	v_cndmask_b32_e64 v27, v27, -v21, s[6:7]
	v_add_f32_e32 v58, v57, v27
	v_fma_f32 v27, -v54, v59, 1.0
	v_fmac_f32_e32 v59, v27, v59
	v_div_scale_f32 v27, vcc, 1.0, v22, 1.0
	v_mul_f32_e32 v60, v27, v59
	v_fma_f32 v61, -v54, v60, v27
	v_fmac_f32_e32 v60, v61, v59
	v_fma_f32 v27, -v54, v60, v27
	v_div_fmas_f32 v27, v27, v59, v60
	v_div_fixup_f32 v22, v27, v22, 1.0
	v_mul_f32_e32 v22, v25, v22
	v_min_f32_e32 v22, 0x3f7ffffe, v22
	v_sub_f32_e32 v27, 1.0, v22
	v_add_f32_e32 v54, -1.0, v27
	v_sub_f32_e32 v59, v54, v27
	v_add_f32_e32 v59, 1.0, v59
	v_sub_f32_e64 v54, -v22, v54
	v_add_f32_e32 v54, v54, v59
	v_frexp_mant_f32_e32 v59, v27
	v_cvt_f64_f32_e32 v[60:61], v27
	v_frexp_exp_i32_f64_e32 v60, v[60:61]
	v_cmp_gt_f32_e32 vcc, s25, v59
	s_nop 1
	v_subbrev_co_u32_e32 v59, vcc, 0, v60, vcc
	v_sub_u32_e32 v60, 0, v59
	v_ldexp_f32 v27, v27, v60
	v_ldexp_f32 v54, v54, v60
	v_add_f32_e32 v60, -1.0, v27
	v_add_f32_e32 v61, 1.0, v60
	v_sub_f32_e32 v61, v27, v61
	v_add_f32_e32 v62, v54, v61
	v_add_f32_e32 v61, 1.0, v27
	v_add_f32_e32 v63, -1.0, v61
	v_sub_f32_e32 v27, v27, v63
	v_add_f32_e32 v27, v54, v27
	v_add_f32_e32 v54, v61, v27
	v_rcp_f32_e32 v68, v54
	v_sub_f32_e32 v61, v54, v61
	v_sub_f32_e32 v27, v27, v61
	v_add_f32_e32 v61, v60, v62
	v_sub_f32_e32 v60, v61, v60
	v_mul_f32_e32 v70, v61, v68
	v_sub_f32_e32 v69, v62, v60
	v_mul_f32_e32 v62, v54, v70
	v_fma_f32 v64, v70, v54, -v62
	v_fmac_f32_e32 v64, v70, v27
	v_add_f32_e32 v60, v62, v64
	v_sub_f32_e32 v63, v61, v60
	v_pk_add_f32 v[66:67], v[60:61], v[62:63] neg_lo:[0,1] neg_hi:[0,1]
	v_mov_b32_e32 v65, v60
	v_pk_add_f32 v[60:61], v[66:67], v[64:65] neg_lo:[0,1] neg_hi:[0,1]
	v_cmp_neq_f32_e32 vcc, s31, v22
	v_add_f32_e32 v61, v69, v61
	v_add_f32_e32 v60, v60, v61
	v_add_f32_e32 v61, v63, v60
	v_mul_f32_e32 v69, v68, v61
	v_mul_f32_e32 v62, v54, v69
	v_fma_f32 v64, v69, v54, -v62
	v_fmac_f32_e32 v64, v69, v27
	v_sub_f32_e32 v27, v63, v61
	v_add_f32_e32 v27, v60, v27
	v_add_f32_e32 v60, v62, v64
	v_sub_f32_e32 v63, v61, v60
	v_pk_add_f32 v[66:67], v[60:61], v[62:63] neg_lo:[0,1] neg_hi:[0,1]
	v_mov_b32_e32 v65, v60
	v_pk_add_f32 v[60:61], v[66:67], v[64:65] neg_lo:[0,1] neg_hi:[0,1]
	v_add_f32_e32 v54, v70, v69
	v_add_f32_e32 v27, v27, v61
	v_add_f32_e32 v27, v60, v27
	v_add_f32_e32 v27, v63, v27
	v_sub_f32_e32 v60, v54, v70
	v_mul_f32_e32 v27, v68, v27
	v_sub_f32_e32 v60, v69, v60
	v_add_f32_e32 v27, v60, v27
	v_add_f32_e32 v61, v54, v27
	v_mul_f32_e32 v62, v61, v61
	v_fmamk_f32 v60, v62, 0x3e9b6dac, v212
	v_fmaak_f32 v211, v62, v60, 0x3f2aaada
	v_cvt_f32_i32_e32 v60, v59
	v_sub_f32_e32 v54, v61, v54
	v_ldexp_f32 v63, v61, 1
	v_mul_f32_e32 v61, v61, v62
	v_pk_mul_f32 v[64:65], v[60:61], v[210:211]
	v_sub_f32_e32 v27, v27, v54
	v_fma_f32 v62, v60, s30, -v64
	v_fmac_f32_e32 v62, 0xb102e308, v60
	v_pk_add_f32 v[60:61], v[64:65], v[62:63]
	v_ldexp_f32 v27, v27, 1
	v_sub_f32_e32 v54, v61, v63
	v_sub_f32_e32 v54, v65, v54
	v_add_f32_e32 v67, v27, v54
	v_mov_b32_e32 v66, v64
	v_pk_add_f32 v[64:65], v[60:61], v[64:65] neg_lo:[0,1] neg_hi:[0,1]
	v_pk_add_f32 v[68:69], v[60:61], v[66:67]
	v_mov_b32_e32 v63, v60
	v_mov_b32_e32 v65, v69
	v_pk_add_f32 v[70:71], v[62:63], v[64:65] neg_lo:[0,1] neg_hi:[0,1]
	v_pk_add_f32 v[62:63], v[62:63], v[64:65]
	v_mov_b32_e32 v66, v67
	v_pk_add_f32 v[64:65], v[62:63], v[60:61] op_sel:[1,0] op_sel_hi:[0,1] neg_lo:[0,1] neg_hi:[0,1]
	v_pk_add_f32 v[72:73], v[68:69], v[64:65] op_sel_hi:[1,0] neg_lo:[0,1] neg_hi:[0,1]
	v_mov_b32_e32 v68, v69
	v_mov_b32_e32 v69, v63
; DI float sigmoidf_(float x) { return 1.f / (1.f + __expf(-x)); }
; DI void hg_prep_unit(const Params& p, int l, int unit, unsigned char* smem) {
;     ...
;     float cum = 0.f;
; #pragma unroll
;     for (int i = 0; i < 16; ++i) {
;       const float kkv = fminf((1.f - lbv) * sigmoidf_(-KK[i]), 0.9999999f);
;       KK[i] = kkv;
;       cum += log1pf(-kkv);
;       G[i] = cum;
;     }
	v_pk_mov_b32 v[64:65], v[60:61], v[64:65] op_sel:[1,0]
	v_mov_b32_e32 v67, v60
	v_pk_add_f32 v[64:65], v[68:69], v[64:65] neg_lo:[0,1] neg_hi:[0,1]
	v_mov_b32_e32 v72, v70
	v_pk_add_f32 v[60:61], v[66:67], v[64:65] neg_lo:[0,1] neg_hi:[0,1]
	v_mov_b32_e32 v71, v63
	v_pk_add_f32 v[64:65], v[72:73], v[60:61]
	v_div_scale_f32 v54, s[6:7], v24, v24, 1.0
	v_pk_add_f32 v[66:67], v[64:65], v[64:65] op_sel:[0,1] op_sel_hi:[1,0]
	v_cmp_lt_f32_e64 s[6:7], |v22|, s44
	v_pk_add_f32 v[62:63], v[62:63], v[66:67] op_sel:[1,0] op_sel_hi:[0,1]
	v_mov_b32_e32 v65, v62
	v_pk_add_f32 v[68:69], v[64:65], v[70:71] neg_lo:[0,1] neg_hi:[0,1]
	v_mov_b32_e32 v61, v66
	v_sub_f32_e32 v27, v64, v68
	v_pk_add_f32 v[60:61], v[60:61], v[68:69] neg_lo:[0,1] neg_hi:[0,1]
	v_sub_f32_e32 v27, v70, v27
	v_add_f32_e32 v27, v60, v27
	v_add_f32_e32 v27, v27, v61
	v_rcp_f32_e32 v60, v54
	v_add_f32_e32 v27, v62, v27
	v_cndmask_b32_e32 v27, v214, v27, vcc
	v_cndmask_b32_e64 v27, v27, -v22, s[6:7]
	v_add_f32_e32 v59, v58, v27
	v_fma_f32 v27, -v54, v60, 1.0
	v_fmac_f32_e32 v60, v27, v60
	v_div_scale_f32 v27, vcc, 1.0, v24, 1.0
	v_mul_f32_e32 v61, v27, v60
	v_fma_f32 v62, -v54, v61, v27
	v_fmac_f32_e32 v61, v62, v60
	v_fma_f32 v27, -v54, v61, v27
	v_div_fmas_f32 v27, v27, v60, v61
	v_div_fixup_f32 v24, v27, v24, 1.0
	v_mul_f32_e32 v24, v25, v24
	v_min_f32_e32 v24, 0x3f7ffffe, v24
	v_sub_f32_e32 v27, 1.0, v24
	v_add_f32_e32 v54, -1.0, v27
	v_sub_f32_e32 v60, v54, v27
	v_add_f32_e32 v60, 1.0, v60
	v_sub_f32_e64 v54, -v24, v54
	v_add_f32_e32 v54, v54, v60
	v_frexp_mant_f32_e32 v62, v27
	v_cvt_f64_f32_e32 v[60:61], v27
	v_frexp_exp_i32_f64_e32 v60, v[60:61]
	v_cmp_gt_f32_e32 vcc, s25, v62
	s_nop 1
	v_subbrev_co_u32_e32 v68, vcc, 0, v60, vcc
	v_sub_u32_e32 v60, 0, v68
	v_ldexp_f32 v27, v27, v60
	v_ldexp_f32 v54, v54, v60
	v_add_f32_e32 v60, -1.0, v27
	v_add_f32_e32 v61, 1.0, v60
	v_sub_f32_e32 v61, v27, v61
	v_add_f32_e32 v62, v54, v61
	v_add_f32_e32 v61, 1.0, v27
	v_add_f32_e32 v63, -1.0, v61
	v_sub_f32_e32 v27, v27, v63
	v_add_f32_e32 v27, v54, v27
	v_add_f32_e32 v54, v61, v27
	v_rcp_f32_e32 v69, v54
	v_sub_f32_e32 v61, v54, v61
	v_sub_f32_e32 v27, v27, v61
	v_add_f32_e32 v61, v60, v62
	v_sub_f32_e32 v60, v61, v60
	v_mul_f32_e32 v71, v61, v69
	v_sub_f32_e32 v70, v62, v60
	v_mul_f32_e32 v62, v54, v71
	v_fma_f32 v64, v71, v54, -v62
	v_fmac_f32_e32 v64, v71, v27
	v_add_f32_e32 v60, v62, v64
	v_sub_f32_e32 v63, v61, v60
	v_pk_add_f32 v[66:67], v[60:61], v[62:63] neg_lo:[0,1] neg_hi:[0,1]
	v_mov_b32_e32 v65, v60
	v_pk_add_f32 v[60:61], v[66:67], v[64:65] neg_lo:[0,1] neg_hi:[0,1]
	v_cmp_neq_f32_e32 vcc, s31, v24
	v_add_f32_e32 v61, v70, v61
	v_add_f32_e32 v60, v60, v61
	v_add_f32_e32 v61, v63, v60
	v_mul_f32_e32 v70, v69, v61
	v_mul_f32_e32 v62, v54, v70
	v_fma_f32 v64, v70, v54, -v62
	v_fmac_f32_e32 v64, v70, v27
	v_sub_f32_e32 v27, v63, v61
	v_add_f32_e32 v27, v60, v27
	v_add_f32_e32 v60, v62, v64
	v_sub_f32_e32 v63, v61, v60
	v_pk_add_f32 v[66:67], v[60:61], v[62:63] neg_lo:[0,1] neg_hi:[0,1]
	v_mov_b32_e32 v65, v60
	v_pk_add_f32 v[60:61], v[66:67], v[64:65] neg_lo:[0,1] neg_hi:[0,1]
	v_add_f32_e32 v54, v71, v70
	v_add_f32_e32 v27, v27, v61
	v_add_f32_e32 v27, v60, v27
	v_add_f32_e32 v27, v63, v27
	v_sub_f32_e32 v60, v54, v71
	v_mul_f32_e32 v27, v69, v27
	v_sub_f32_e32 v60, v70, v60
	v_add_f32_e32 v27, v60, v27
	v_add_f32_e32 v61, v54, v27
	v_mul_f32_e32 v62, v61, v61
	v_fmamk_f32 v60, v62, 0x3e9b6dac, v212
	v_fmaak_f32 v211, v62, v60, 0x3f2aaada
	v_cvt_f32_i32_e32 v60, v68
	v_sub_f32_e32 v54, v61, v54
	v_ldexp_f32 v63, v61, 1
	v_mul_f32_e32 v61, v61, v62
	v_pk_mul_f32 v[64:65], v[60:61], v[210:211]
	v_sub_f32_e32 v27, v27, v54
	v_fma_f32 v62, v60, s30, -v64
	v_fmac_f32_e32 v62, 0xb102e308, v60
	v_pk_add_f32 v[60:61], v[64:65], v[62:63]
	v_ldexp_f32 v27, v27, 1
	v_sub_f32_e32 v54, v61, v63
	v_sub_f32_e32 v54, v65, v54
	v_add_f32_e32 v67, v27, v54
	v_mov_b32_e32 v66, v64
	v_pk_add_f32 v[64:65], v[60:61], v[64:65] neg_lo:[0,1] neg_hi:[0,1]
	v_pk_add_f32 v[68:69], v[60:61], v[66:67]
	v_mov_b32_e32 v63, v60
	v_mov_b32_e32 v65, v69
	v_pk_add_f32 v[70:71], v[62:63], v[64:65] neg_lo:[0,1] neg_hi:[0,1]
	v_pk_add_f32 v[62:63], v[62:63], v[64:65]
	v_mov_b32_e32 v66, v67
	v_pk_add_f32 v[64:65], v[62:63], v[60:61] op_sel:[1,0] op_sel_hi:[0,1] neg_lo:[0,1] neg_hi:[0,1]
	v_pk_add_f32 v[72:73], v[68:69], v[64:65] op_sel_hi:[1,0] neg_lo:[0,1] neg_hi:[0,1]
	v_mov_b32_e32 v68, v69
	v_mov_b32_e32 v69, v63
	v_pk_mov_b32 v[64:65], v[60:61], v[64:65] op_sel:[1,0]
	v_mov_b32_e32 v67, v60
	v_pk_add_f32 v[64:65], v[68:69], v[64:65] neg_lo:[0,1] neg_hi:[0,1]
	v_mov_b32_e32 v72, v70
	v_pk_add_f32 v[60:61], v[66:67], v[64:65] neg_lo:[0,1] neg_hi:[0,1]
	v_mov_b32_e32 v71, v63
	v_pk_add_f32 v[64:65], v[72:73], v[60:61]
	v_div_scale_f32 v54, s[6:7], v23, v23, 1.0
	v_pk_add_f32 v[66:67], v[64:65], v[64:65] op_sel:[0,1] op_sel_hi:[1,0]
	v_cmp_lt_f32_e64 s[6:7], |v24|, s44
	v_pk_add_f32 v[62:63], v[62:63], v[66:67] op_sel:[1,0] op_sel_hi:[0,1]
	v_mov_b32_e32 v65, v62
	v_pk_add_f32 v[68:69], v[64:65], v[70:71] neg_lo:[0,1] neg_hi:[0,1]
	v_mov_b32_e32 v61, v66
	v_sub_f32_e32 v27, v64, v68
	v_pk_add_f32 v[60:61], v[60:61], v[68:69] neg_lo:[0,1] neg_hi:[0,1]
	v_sub_f32_e32 v27, v70, v27
	v_add_f32_e32 v27, v60, v27
	v_add_f32_e32 v27, v27, v61
	v_rcp_f32_e32 v61, v54
	v_add_f32_e32 v27, v62, v27
	v_cndmask_b32_e32 v27, v214, v27, vcc
	v_cndmask_b32_e64 v27, v27, -v24, s[6:7]
	v_add_f32_e32 v60, v59, v27
	v_fma_f32 v27, -v54, v61, 1.0
	v_fmac_f32_e32 v61, v27, v61
	v_div_scale_f32 v27, vcc, 1.0, v23, 1.0
	v_mul_f32_e32 v62, v27, v61
	v_fma_f32 v63, -v54, v62, v27
	v_fmac_f32_e32 v62, v63, v61
	v_fma_f32 v27, -v54, v62, v27
; DI float sigmoidf_(float x) { return 1.f / (1.f + __expf(-x)); }
; DI void hg_prep_unit(const Params& p, int l, int unit, unsigned char* smem) {
;     ...
;     float cum = 0.f;
; #pragma unroll
;     for (int i = 0; i < 16; ++i) {
;       const float kkv = fminf((1.f - lbv) * sigmoidf_(-KK[i]), 0.9999999f);
;       KK[i] = kkv;
;       cum += log1pf(-kkv);
;       G[i] = cum;
;     }
	v_div_fmas_f32 v27, v27, v61, v62
	v_div_fixup_f32 v23, v27, v23, 1.0
	v_mul_f32_e32 v23, v25, v23
	v_min_f32_e32 v23, 0x3f7ffffe, v23
	v_sub_f32_e32 v27, 1.0, v23
	v_add_f32_e32 v54, -1.0, v27
	v_sub_f32_e32 v61, v54, v27
	v_add_f32_e32 v61, 1.0, v61
	v_sub_f32_e64 v54, -v23, v54
	v_add_f32_e32 v54, v54, v61
	v_frexp_mant_f32_e32 v61, v27
	v_cvt_f64_f32_e32 v[62:63], v27
	v_frexp_exp_i32_f64_e32 v62, v[62:63]
	v_cmp_gt_f32_e32 vcc, s25, v61
	s_nop 1
	v_subbrev_co_u32_e32 v61, vcc, 0, v62, vcc
	v_sub_u32_e32 v62, 0, v61
	v_ldexp_f32 v27, v27, v62
	v_ldexp_f32 v54, v54, v62
	v_add_f32_e32 v62, -1.0, v27
	v_add_f32_e32 v63, 1.0, v62
	v_sub_f32_e32 v63, v27, v63
	v_add_f32_e32 v64, v54, v63
	v_add_f32_e32 v63, 1.0, v27
	v_add_f32_e32 v65, -1.0, v63
	v_sub_f32_e32 v27, v27, v65
	v_add_f32_e32 v27, v54, v27
	v_add_f32_e32 v54, v63, v27
	v_rcp_f32_e32 v70, v54
	v_sub_f32_e32 v63, v54, v63
	v_sub_f32_e32 v27, v27, v63
	v_add_f32_e32 v63, v62, v64
	v_sub_f32_e32 v62, v63, v62
	v_mul_f32_e32 v72, v63, v70
	v_sub_f32_e32 v71, v64, v62
	v_mul_f32_e32 v64, v54, v72
	v_fma_f32 v66, v72, v54, -v64
	v_fmac_f32_e32 v66, v72, v27
	v_add_f32_e32 v62, v64, v66
	v_sub_f32_e32 v65, v63, v62
	v_pk_add_f32 v[68:69], v[62:63], v[64:65] neg_lo:[0,1] neg_hi:[0,1]
	v_mov_b32_e32 v67, v62
	v_pk_add_f32 v[62:63], v[68:69], v[66:67] neg_lo:[0,1] neg_hi:[0,1]
	v_cmp_neq_f32_e32 vcc, s31, v23
	v_add_f32_e32 v63, v71, v63
	v_add_f32_e32 v62, v62, v63
	v_add_f32_e32 v63, v65, v62
	v_mul_f32_e32 v71, v70, v63
	v_mul_f32_e32 v64, v54, v71
	v_fma_f32 v66, v71, v54, -v64
	v_fmac_f32_e32 v66, v71, v27
	v_sub_f32_e32 v27, v65, v63
	v_add_f32_e32 v27, v62, v27
	v_add_f32_e32 v62, v64, v66
	v_sub_f32_e32 v65, v63, v62
	v_pk_add_f32 v[68:69], v[62:63], v[64:65] neg_lo:[0,1] neg_hi:[0,1]
	v_mov_b32_e32 v67, v62
	v_pk_add_f32 v[62:63], v[68:69], v[66:67] neg_lo:[0,1] neg_hi:[0,1]
	v_add_f32_e32 v54, v72, v71
	v_add_f32_e32 v27, v27, v63
	v_add_f32_e32 v27, v62, v27
	v_add_f32_e32 v27, v65, v27
	v_sub_f32_e32 v62, v54, v72
	v_mul_f32_e32 v27, v70, v27
	v_sub_f32_e32 v62, v71, v62
	v_add_f32_e32 v27, v62, v27
	v_add_f32_e32 v63, v54, v27
	v_mul_f32_e32 v64, v63, v63
	v_fmamk_f32 v62, v64, 0x3e9b6dac, v212
	v_fmaak_f32 v211, v64, v62, 0x3f2aaada
	v_cvt_f32_i32_e32 v62, v61
	v_sub_f32_e32 v54, v63, v54
	v_ldexp_f32 v65, v63, 1
	v_mul_f32_e32 v63, v63, v64
	v_pk_mul_f32 v[66:67], v[62:63], v[210:211]
	v_sub_f32_e32 v27, v27, v54
	v_fma_f32 v64, v62, s30, -v66
	v_fmac_f32_e32 v64, 0xb102e308, v62
	v_pk_add_f32 v[62:63], v[66:67], v[64:65]
	v_ldexp_f32 v27, v27, 1
	v_sub_f32_e32 v54, v63, v65
	v_sub_f32_e32 v54, v67, v54
	v_add_f32_e32 v69, v27, v54
	v_mov_b32_e32 v68, v66
	v_pk_add_f32 v[66:67], v[62:63], v[66:67] neg_lo:[0,1] neg_hi:[0,1]
	v_pk_add_f32 v[70:71], v[62:63], v[68:69]
	v_mov_b32_e32 v65, v62
	v_mov_b32_e32 v67, v71
	v_pk_add_f32 v[72:73], v[64:65], v[66:67] neg_lo:[0,1] neg_hi:[0,1]
	v_pk_add_f32 v[64:65], v[64:65], v[66:67]
	v_mov_b32_e32 v68, v69
	v_pk_add_f32 v[66:67], v[64:65], v[62:63] op_sel:[1,0] op_sel_hi:[0,1] neg_lo:[0,1] neg_hi:[0,1]
	v_pk_add_f32 v[74:75], v[70:71], v[66:67] op_sel_hi:[1,0] neg_lo:[0,1] neg_hi:[0,1]
	v_mov_b32_e32 v70, v71
	v_mov_b32_e32 v71, v65
	v_pk_mov_b32 v[66:67], v[62:63], v[66:67] op_sel:[1,0]
	v_mov_b32_e32 v69, v62
	v_pk_add_f32 v[66:67], v[70:71], v[66:67] neg_lo:[0,1] neg_hi:[0,1]
	v_mov_b32_e32 v74, v72
	v_pk_add_f32 v[62:63], v[68:69], v[66:67] neg_lo:[0,1] neg_hi:[0,1]
	v_mov_b32_e32 v73, v65
	v_pk_add_f32 v[66:67], v[74:75], v[62:63]
	v_div_scale_f32 v54, s[6:7], v26, v26, 1.0
	v_pk_add_f32 v[68:69], v[66:67], v[66:67] op_sel:[0,1] op_sel_hi:[1,0]
	v_cmp_lt_f32_e64 s[6:7], |v23|, s44
	v_pk_add_f32 v[64:65], v[64:65], v[68:69] op_sel:[1,0] op_sel_hi:[0,1]
	v_mov_b32_e32 v67, v64
	v_pk_add_f32 v[70:71], v[66:67], v[72:73] neg_lo:[0,1] neg_hi:[0,1]
	v_mov_b32_e32 v63, v68
	v_sub_f32_e32 v27, v66, v70
	v_pk_add_f32 v[62:63], v[62:63], v[70:71] neg_lo:[0,1] neg_hi:[0,1]
	v_sub_f32_e32 v27, v72, v27
	v_add_f32_e32 v27, v62, v27
	v_add_f32_e32 v27, v27, v63
	v_rcp_f32_e32 v62, v54
	v_add_f32_e32 v27, v64, v27
	v_cndmask_b32_e32 v27, v214, v27, vcc
	v_cndmask_b32_e64 v27, v27, -v23, s[6:7]
	v_add_f32_e32 v61, v60, v27
	v_fma_f32 v27, -v54, v62, 1.0
	v_fmac_f32_e32 v62, v27, v62
	v_div_scale_f32 v27, vcc, 1.0, v26, 1.0
	v_mul_f32_e32 v63, v27, v62
	v_fma_f32 v64, -v54, v63, v27
	v_fmac_f32_e32 v63, v64, v62
	v_fma_f32 v27, -v54, v63, v27
	v_div_fmas_f32 v27, v27, v62, v63
	v_div_fixup_f32 v26, v27, v26, 1.0
	v_mul_f32_e32 v25, v25, v26
	v_min_f32_e32 v25, 0x3f7ffffe, v25
	v_sub_f32_e32 v54, 1.0, v25
	v_add_f32_e32 v26, -1.0, v54
	v_sub_f32_e32 v27, v26, v54
	v_add_f32_e32 v27, 1.0, v27
	v_sub_f32_e64 v26, -v25, v26
	v_add_f32_e32 v62, v26, v27
	v_frexp_mant_f32_e32 v63, v54
	v_cvt_f64_f32_e32 v[26:27], v54
	v_frexp_exp_i32_f64_e32 v26, v[26:27]
	v_cmp_gt_f32_e32 vcc, s25, v63
	v_cmp_lt_f32_e64 s[6:7], |v25|, s44
	s_mov_b32 s25, 0x1fffffc
	v_subbrev_co_u32_e32 v68, vcc, 0, v26, vcc
	v_sub_u32_e32 v26, 0, v68
	v_ldexp_f32 v27, v54, v26
	v_add_f32_e32 v54, -1.0, v27
	v_add_f32_e32 v63, 1.0, v27
	v_ldexp_f32 v26, v62, v26
	v_add_f32_e32 v62, 1.0, v54
	v_add_f32_e32 v64, -1.0, v63
	v_sub_f32_e32 v62, v27, v62
	v_sub_f32_e32 v27, v27, v64
	v_add_f32_e32 v62, v26, v62
	v_add_f32_e32 v26, v26, v27
	v_add_f32_e32 v69, v63, v26
	v_rcp_f32_e32 v71, v69
	v_sub_f32_e32 v27, v69, v63
	v_sub_f32_e32 v70, v26, v27
	v_add_f32_e32 v27, v54, v62
	v_sub_f32_e32 v26, v27, v54
	v_mul_f32_e32 v72, v27, v71
	v_sub_f32_e32 v54, v62, v26
	v_mul_f32_e32 v62, v69, v72
	v_fma_f32 v64, v72, v69, -v62
	v_fmac_f32_e32 v64, v72, v70
	v_add_f32_e32 v26, v62, v64
; DI float siluf_(float x) { return x / (1.f + __expf(-x)); }
; DI void hg_prep_unit(const Params& p, int l, int unit, unsigned char* smem) {
;     ...
;       cum += log1pf(-kkv);
;       G[i] = cum;
;     }
;     sTot[hf * 128 + dk] = cum;
; #pragma unroll
;     for (int q = 0; q < 2; ++q) {
;       u32x4 w; w[0] = vv[4 * q]; w[1] = vv[4 * q + 1]; w[2] = vv[4 * q + 2]; w[3] = vv[4 * q + 3];
;       *(u32x4*)(g_vT + fragn_idx(dk, i0 + 8 * q, 2)) = w;
;       *(u32x4*)(sVT + dk * 40 + i0 + 8 * q) = w;
;     }
;     __syncthreads();
;     const float t0 = sTot[dk], t1 = sTot[128 + dk];
;     const float Gl = t0 + t1, Gr = t0, goff = hf ? t0 : 0.f;
;     unsigned kh[8];
; #pragma unroll
;     for (int i = 0; i < 16; ++i) {
;       const int ig = i0 + i;
;       const float Gi = G[i] + goff;
;       const float kkv = KK[i];
;       const float q = siluf_(Q[i]);
	v_sub_f32_e32 v63, v27, v26
	v_pk_add_f32 v[66:67], v[26:27], v[62:63] neg_lo:[0,1] neg_hi:[0,1]
	v_mov_b32_e32 v65, v26
	v_pk_add_f32 v[26:27], v[66:67], v[64:65] neg_lo:[0,1] neg_hi:[0,1]
	v_cmp_neq_f32_e32 vcc, s31, v25
	v_add_f32_e32 v27, v54, v27
	v_add_f32_e32 v26, v26, v27
	v_add_f32_e32 v27, v63, v26
	v_mul_f32_e32 v54, v71, v27
	v_mul_f32_e32 v62, v69, v54
	v_fma_f32 v64, v54, v69, -v62
	v_fmac_f32_e32 v64, v54, v70
	v_sub_f32_e32 v63, v63, v27
	v_add_f32_e32 v69, v26, v63
	v_add_f32_e32 v26, v62, v64
	v_sub_f32_e32 v63, v27, v26
	v_pk_add_f32 v[66:67], v[26:27], v[62:63] neg_lo:[0,1] neg_hi:[0,1]
	v_mov_b32_e32 v65, v26
	v_pk_add_f32 v[26:27], v[66:67], v[64:65] neg_lo:[0,1] neg_hi:[0,1]
	s_movk_i32 s44, 0x50
	v_add_f32_e32 v27, v69, v27
	v_add_f32_e32 v26, v26, v27
	v_add_f32_e32 v27, v72, v54
	v_add_f32_e32 v26, v63, v26
	v_sub_f32_e32 v62, v27, v72
	v_mul_f32_e32 v26, v71, v26
	v_sub_f32_e32 v54, v54, v62
	v_add_f32_e32 v54, v54, v26
	v_add_f32_e32 v62, v27, v54
	v_mul_f32_e32 v64, v62, v62
	v_fmamk_f32 v26, v64, 0x3e9b6dac, v212
	v_fmaak_f32 v211, v64, v26, 0x3f2aaada
	v_cvt_f32_i32_e32 v26, v68
	v_sub_f32_e32 v27, v62, v27
	v_sub_f32_e32 v27, v54, v27
	v_ldexp_f32 v54, v27, 1
	v_mul_f32_e32 v27, v62, v64
	v_pk_mul_f32 v[64:65], v[26:27], v[210:211]
	v_ldexp_f32 v63, v62, 1
	v_fma_f32 v62, v26, s30, -v64
	v_fmac_f32_e32 v62, 0xb102e308, v26
	v_pk_add_f32 v[26:27], v[64:65], v[62:63]
	v_mov_b32_e32 v66, v64
	v_sub_f32_e32 v63, v27, v63
	v_sub_f32_e32 v63, v65, v63
	v_add_f32_e32 v67, v54, v63
	v_pk_add_f32 v[64:65], v[26:27], v[64:65] neg_lo:[0,1] neg_hi:[0,1]
	v_pk_add_f32 v[68:69], v[26:27], v[66:67]
	v_mov_b32_e32 v63, v26
	v_mov_b32_e32 v65, v69
	v_pk_add_f32 v[70:71], v[62:63], v[64:65] neg_lo:[0,1] neg_hi:[0,1]
	v_pk_add_f32 v[62:63], v[62:63], v[64:65]
	v_mov_b32_e32 v66, v67
	v_pk_add_f32 v[64:65], v[62:63], v[26:27] op_sel:[1,0] op_sel_hi:[0,1] neg_lo:[0,1] neg_hi:[0,1]
	v_pk_add_f32 v[72:73], v[68:69], v[64:65] op_sel_hi:[1,0] neg_lo:[0,1] neg_hi:[0,1]
	v_mov_b32_e32 v68, v69
	v_mov_b32_e32 v69, v63
	v_pk_mov_b32 v[64:65], v[26:27], v[64:65] op_sel:[1,0]
	v_mov_b32_e32 v67, v26
	v_pk_add_f32 v[64:65], v[68:69], v[64:65] neg_lo:[0,1] neg_hi:[0,1]
	v_mov_b32_e32 v72, v70
	v_pk_add_f32 v[26:27], v[66:67], v[64:65] neg_lo:[0,1] neg_hi:[0,1]
	v_mov_b32_e32 v71, v63
	v_pk_add_f32 v[64:65], v[72:73], v[26:27]
	s_mov_b64 s[30:31], 0x4000
	v_pk_add_f32 v[66:67], v[64:65], v[64:65] op_sel:[0,1] op_sel_hi:[1,0]
	s_nop 0
	v_pk_add_f32 v[62:63], v[62:63], v[66:67] op_sel:[1,0] op_sel_hi:[0,1]
	v_mov_b32_e32 v65, v62
	v_pk_add_f32 v[68:69], v[64:65], v[70:71] neg_lo:[0,1] neg_hi:[0,1]
	v_mov_b32_e32 v27, v66
	v_sub_f32_e32 v54, v64, v68
	v_pk_add_f32 v[26:27], v[26:27], v[68:69] neg_lo:[0,1] neg_hi:[0,1]
	v_sub_f32_e32 v54, v70, v54
	v_add_f32_e32 v26, v26, v54
	v_add_f32_e32 v26, v26, v27
	v_add_f32_e32 v26, v62, v26
	v_cndmask_b32_e32 v26, v214, v26, vcc
	v_cndmask_b32_e64 v26, v26, -v25, s[6:7]
	v_lshrrev_b32_e32 v27, 4, v28
	v_add_f32_e32 v63, v61, v26
	v_lshrrev_b32_e32 v26, 7, v28
	v_and_b32_e32 v27, 6, v27
	v_lshlrev_b32_e32 v62, 1, v31
	s_movk_i32 s7, 0x50
	v_and_b32_e32 v54, 31, v28
	v_mad_u32_u24 v66, v29, s7, v62
	v_add_lshl_u32 v62, v27, v26, 9
	v_lshl_or_b32 v26, v54, 3, v62
	v_ashrrev_i32_e32 v27, 31, v26
	v_lshl_add_u64 v[26:27], v[26:27], 1, s[28:29]
	s_movk_i32 s6, 0x4000
	v_lshl_add_u64 v[64:65], v[26:27], 0, s[30:31]
	v_add_co_u32_e32 v26, vcc, s6, v26
	v_lshlrev_b32_e32 v67, 2, v28
	s_nop 0
	v_addc_co_u32_e32 v27, vcc, 0, v27, vcc
	ds_write_b32 v67, v63 offset:27648
	flat_store_dwordx4 v[26:27], v[0:3]
	ds_write_b128 v66, v[0:3] offset:17408
	flat_store_dwordx4 v[64:65], v[4:7] offset:512
	v_mul_i32_i24_e32 v0, 0xffffffb4, v29
	v_mul_f32_e32 v3, 0xbfb8aa3b, v43
	v_mad_u32_u24 v0, v29, s7, v0
	v_exp_f32_e32 v3, v3
	ds_write_b128 v66, v[4:7] offset:17424
	s_waitcnt lgkmcnt(0)
	s_barrier
	ds_read2st64_b32 v[26:27], v0 offset0:108 offset1:110
	v_bfe_u32 v0, v28, 5, 2
	v_lshrrev_b32_e32 v2, 3, v30
	v_lshlrev_b32_e32 v65, 16, v45
	v_lshlrev_b32_e32 v45, 16, v44
	v_and_or_b32 v0, v2, s25, v0
	v_lshlrev_b32_e32 v44, 3, v28
	v_lshlrev_b32_e32 v0, 7, v0
	v_and_b32_e32 v2, 64, v67
	v_and_b32_e32 v4, 32, v44
	v_lshlrev_b32_e32 v66, 16, v46
	v_or3_b32 v46, v0, v2, v4
	v_add_f32_e32 v0, 1.0, v3
	v_div_scale_f32 v2, s[30:31], v0, v0, v43
	v_rcp_f32_e32 v3, v2
	v_and_b32_e32 v1, 3, v28
	v_lshrrev_b32_e32 v4, 1, v28
	v_and_or_b32 v64, v4, 4, v1
	v_fma_f32 v1, -v2, v3, 1.0
	s_movk_i32 s6, 0x80
	v_fmac_f32_e32 v3, v1, v3
	v_div_scale_f32 v1, vcc, v43, v0, v43
	v_cmp_gt_u32_e64 s[6:7], s6, v28
	v_mul_f32_e32 v5, v1, v3
	v_fma_f32 v6, -v2, v5, v1
	s_waitcnt lgkmcnt(0)
; DI bfr f2bf(float a) { return (bfr)(pk2(a, 0.f) & 0xffffu); }
; DI float siluf_(float x) { return x / (1.f + __expf(-x)); }
; DI void hg_prep_unit(const Params& p, int l, int unit, unsigned char* smem) {
;     ...
;     for (int i = 0; i < 16; ++i) {
;       const int ig = i0 + i;
;       const float Gi = G[i] + goff;
;       const float kkv = KK[i];
;       const float q = siluf_(Q[i]);
;       g_qhat[fragp_idx(ig, dk, 4)] = f2bf(q * __expf(Gi));
;       const float khv = kkv * __expf(Gl - Gi);
;       if (i & 1) kh[i >> 1] |= ((unsigned)f2bf(khv)) << 16; else kh[i >> 1] = f2bf(khv);
;       sQt[ig * 136 + dk] = f2bf(q * __expf(fminf(Gi - Gr, 80.f)));
;       sKt[ig * 136 + dk] = f2bf(kkv * __expf(fminf(Gr - Gi, 80.f)));
	v_cndmask_b32_e64 v7, v26, 0, s[6:7]
	v_add_f32_e32 v4, v7, v47
	v_fmac_f32_e32 v5, v6, v3
	v_fma_f32 v1, -v2, v5, v1
	v_mul_f32_e32 v2, 0x3fb8aa3b, v4
	v_exp_f32_e32 v2, v2
	v_div_fmas_f32 v1, v1, v3, v5
	v_div_fixup_f32 v3, v1, v0, v43
	v_sub_f32_e32 v1, v4, v26
	v_mul_f32_e32 v0, v3, v2
	v_cvt_pk_bf16_f32 v2, v0, s0
	v_and_or_b32 v0, v30, 16, v46
	v_min_f32_e32 v1, 0x42a00000, v1
	v_lshl_or_b32 v0, v0, 3, v64
	v_mul_f32_e32 v1, 0x3fb8aa3b, v1
	v_exp_f32_e32 v5, v1
	v_ashrrev_i32_e32 v1, 31, v0
	v_lshl_add_u64 v[0:1], v[0:1], 1, s[28:29]
	s_movk_i32 s25, 0x88
	flat_store_short v[0:1], v2
	v_mul_lo_u32 v1, v31, s25
	v_or_b32_e32 v1, v1, v29
	v_lshlrev_b32_e32 v43, 1, v1
	v_sub_f32_e32 v1, v26, v4
	v_min_f32_e32 v1, 0x42a00000, v1
	v_mul_f32_e32 v1, 0x3fb8aa3b, v1
	v_mul_f32_e32 v2, 0xbfb8aa3b, v42
	v_exp_f32_e32 v1, v1
	v_exp_f32_e32 v2, v2
	v_mul_f32_e32 v0, v3, v5
	v_cvt_pk_bf16_f32 v0, v0, s0
	ds_write_b16 v43, v0
	v_mul_f32_e32 v0, v8, v1
	v_add_f32_e32 v1, 1.0, v2
	v_div_scale_f32 v2, s[30:31], v1, v1, v42
	v_rcp_f32_e32 v3, v2
	v_add_f32_e32 v5, v7, v48
	v_cvt_pk_bf16_f32 v0, v0, s0
	ds_write_b16 v43, v0 offset:8704
	v_fma_f32 v6, -v2, v3, 1.0
	v_fmac_f32_e32 v3, v6, v3
	v_div_scale_f32 v6, vcc, v42, v1, v42
	v_mul_f32_e32 v47, v6, v3
	v_fma_f32 v48, -v2, v47, v6
	v_fmac_f32_e32 v47, v48, v3
	v_fma_f32 v2, -v2, v47, v6
	v_mul_f32_e32 v6, 0x3fb8aa3b, v5
	v_exp_f32_e32 v6, v6
	v_div_fmas_f32 v2, v2, v3, v47
	v_div_fixup_f32 v2, v2, v1, v42
	v_or_b32_e32 v0, 1, v31
	v_mul_f32_e32 v1, v2, v6
	v_cvt_pk_bf16_f32 v3, v1, s0
	v_sub_f32_e32 v1, v5, v26
	v_and_or_b32 v0, v0, 17, v46
	v_min_f32_e32 v1, 0x42a00000, v1
	v_lshl_or_b32 v0, v0, 3, v64
	v_mul_f32_e32 v1, 0x3fb8aa3b, v1
	v_exp_f32_e32 v6, v1
	v_ashrrev_i32_e32 v1, 31, v0
	v_lshl_add_u64 v[0:1], v[0:1], 1, s[28:29]
	flat_store_short v[0:1], v3
	v_sub_f32_e32 v1, v26, v5
	v_min_f32_e32 v1, 0x42a00000, v1
	v_mul_f32_e32 v0, v2, v6
	v_mul_f32_e32 v1, 0x3fb8aa3b, v1
	v_mul_f32_e32 v2, 0xbfb8aa3b, v16
	v_exp_f32_e32 v1, v1
	v_exp_f32_e32 v2, v2
	v_cvt_pk_bf16_f32 v0, v0, s0
	ds_write_b16 v43, v0 offset:272
	v_mul_f32_e32 v0, v10, v1
	v_add_f32_e32 v1, 1.0, v2
	v_div_scale_f32 v2, s[30:31], v1, v1, v16
	v_rcp_f32_e32 v3, v2
	v_add_f32_e32 v42, v7, v49
	v_cvt_pk_bf16_f32 v0, v0, s0
	ds_write_b16 v43, v0 offset:8976
	v_fma_f32 v6, -v2, v3, 1.0
	v_fmac_f32_e32 v3, v6, v3
	v_div_scale_f32 v6, vcc, v16, v1, v16
	v_mul_f32_e32 v47, v6, v3
	v_fma_f32 v48, -v2, v47, v6
	v_fmac_f32_e32 v47, v48, v3
	v_fma_f32 v2, -v2, v47, v6
	v_mul_f32_e32 v6, 0x3fb8aa3b, v42
	v_exp_f32_e32 v6, v6
	v_or_b32_e32 v0, 2, v31
	v_div_fmas_f32 v2, v2, v3, v47
	v_div_fixup_f32 v2, v2, v1, v16
	v_and_or_b32 v0, v0, 18, v46
	v_mul_f32_e32 v1, v2, v6
	v_lshl_or_b32 v0, v0, 3, v64
	v_cvt_pk_bf16_f32 v3, v1, s0
	v_ashrrev_i32_e32 v1, 31, v0
	v_lshl_add_u64 v[0:1], v[0:1], 1, s[28:29]
	flat_store_short v[0:1], v3
	v_sub_f32_e32 v0, v42, v26
	v_min_f32_e32 v0, 0x42a00000, v0
	v_mul_f32_e32 v0, 0x3fb8aa3b, v0
	v_sub_f32_e32 v1, v26, v42
	v_exp_f32_e32 v0, v0
	v_min_f32_e32 v1, 0x42a00000, v1
	v_mul_f32_e32 v1, 0x3fb8aa3b, v1
	v_exp_f32_e32 v1, v1
	v_mul_f32_e32 v0, v2, v0
	v_cvt_pk_bf16_f32 v0, v0, s0
	ds_write_b16 v43, v0 offset:544
	v_mul_f32_e32 v0, v9, v1
	v_mul_f32_e32 v1, 0xbfb8aa3b, v41
	v_exp_f32_e32 v1, v1
	v_mov_b32_e32 v6, v26
	v_mov_b32_e32 v16, v27
	v_cvt_pk_bf16_f32 v0, v0, s0
	v_pk_add_f32 v[16:17], v[6:7], v[16:17]
	ds_write_b16 v43, v0 offset:9248
	v_sub_f32_e32 v0, v16, v4
	v_add_f32_e32 v4, 1.0, v1
	v_sub_f32_e32 v2, v16, v5
	v_div_scale_f32 v5, s[30:31], v4, v4, v41
	v_rcp_f32_e32 v6, v5
	v_sub_f32_e32 v1, v16, v42
	v_or_b32_e32 v3, 3, v31
	v_and_or_b32 v3, v3, 19, v46
	v_fma_f32 v27, -v5, v6, 1.0
	v_fmac_f32_e32 v6, v27, v6
	v_div_scale_f32 v27, vcc, v41, v4, v41
	v_mul_f32_e32 v42, v27, v6
	v_fma_f32 v47, -v5, v42, v27
	v_fmac_f32_e32 v42, v47, v6
	v_fma_f32 v5, -v5, v42, v27
	v_mul_f32_e32 v27, 0x3fb8aa3b, v17
	v_exp_f32_e32 v27, v27
	v_div_fmas_f32 v5, v5, v6, v42
	v_div_fixup_f32 v6, v5, v4, v41
	v_mul_f32_e32 v0, 0x3fb8aa3b, v0
	v_mul_f32_e32 v4, v6, v27
	v_mul_f32_e32 v1, 0x3fb8aa3b, v1
	v_cvt_pk_bf16_f32 v27, v4, s0
	v_lshl_or_b32 v4, v3, 3, v64
	v_sub_f32_e32 v3, v16, v17
	v_exp_f32_e32 v0, v0
	v_mul_f32_e32 v2, 0x3fb8aa3b, v2
	v_exp_f32_e32 v1, v1
	v_mul_f32_e32 v3, 0x3fb8aa3b, v3
	v_exp_f32_e32 v2, v2
	v_exp_f32_e32 v3, v3
	v_ashrrev_i32_e32 v5, 31, v4
	v_lshl_add_u64 v[4:5], v[4:5], 1, s[28:29]
	v_pk_mul_f32 v[0:1], v[8:9], v[0:1]
	flat_store_short v[4:5], v27
	v_cvt_pk_bf16_f32 v4, v0, v1
	v_pk_mul_f32 v[0:1], v[10:11], v[2:3]
	v_sub_f32_e32 v2, v17, v26
	v_min_f32_e32 v2, 0x42a00000, v2
	v_cvt_pk_bf16_f32 v0, v0, v1
	v_mul_f32_e32 v2, 0x3fb8aa3b, v2
	v_sub_f32_e32 v3, v26, v17
	v_and_b32_e32 v1, 0xffff0000, v0
	v_exp_f32_e32 v2, v2
	v_lshlrev_b32_e32 v0, 16, v0
	v_min_f32_e32 v3, 0x42a00000, v3
	v_or_b32_sdwa v1, v1, v4 dst_sel:DWORD dst_unused:UNUSED_PAD src0_sel:DWORD src1_sel:WORD_1
	v_or_b32_sdwa v0, v0, v4 dst_sel:DWORD dst_unused:UNUSED_PAD src0_sel:DWORD src1_sel:WORD_0
	v_mul_f32_e32 v3, 0x3fb8aa3b, v3
	v_mul_f32_e32 v4, 0xbfb8aa3b, v40
	v_exp_f32_e32 v3, v3
	v_exp_f32_e32 v4, v4
	v_mul_f32_e32 v2, v6, v2
	v_cvt_pk_bf16_f32 v2, v2, s0
	ds_write_b16 v43, v2 offset:816
	v_mul_f32_e32 v2, v11, v3
	v_add_f32_e32 v3, 1.0, v4
	v_div_scale_f32 v4, s[30:31], v3, v3, v40
	v_rcp_f32_e32 v5, v4
	v_add_f32_e32 v6, v7, v50
	v_cvt_pk_bf16_f32 v2, v2, s0
	ds_write_b16 v43, v2 offset:9520
	v_fma_f32 v8, -v4, v5, 1.0
	v_fmac_f32_e32 v5, v8, v5
	v_div_scale_f32 v8, vcc, v40, v3, v40
	v_mul_f32_e32 v9, v8, v5
	v_fma_f32 v10, -v4, v9, v8
	v_fmac_f32_e32 v9, v10, v5
	v_fma_f32 v4, -v4, v9, v8
; DI bfr f2bf(float a) { return (bfr)(pk2(a, 0.f) & 0xffffu); }
; DI float siluf_(float x) { return x / (1.f + __expf(-x)); }
; DI void hg_prep_unit(const Params& p, int l, int unit, unsigned char* smem) {
;     ...
;     for (int i = 0; i < 16; ++i) {
;       const int ig = i0 + i;
;       const float Gi = G[i] + goff;
;       const float kkv = KK[i];
;       const float q = siluf_(Q[i]);
;       g_qhat[fragp_idx(ig, dk, 4)] = f2bf(q * __expf(Gi));
;       const float khv = kkv * __expf(Gl - Gi);
;       if (i & 1) kh[i >> 1] |= ((unsigned)f2bf(khv)) << 16; else kh[i >> 1] = f2bf(khv);
;       sQt[ig * 136 + dk] = f2bf(q * __expf(fminf(Gi - Gr, 80.f)));
;       sKt[ig * 136 + dk] = f2bf(kkv * __expf(fminf(Gr - Gi, 80.f)));
	v_mul_f32_e32 v8, 0x3fb8aa3b, v6
	v_exp_f32_e32 v8, v8
	v_or_b32_e32 v2, 4, v31
	v_div_fmas_f32 v4, v4, v5, v9
	v_div_fixup_f32 v4, v4, v3, v40
	v_and_or_b32 v2, v2, 20, v46
	v_mul_f32_e32 v3, v4, v8
	v_lshl_or_b32 v2, v2, 3, v64
	v_cvt_pk_bf16_f32 v5, v3, s0
	v_ashrrev_i32_e32 v3, 31, v2
	v_lshl_add_u64 v[2:3], v[2:3], 1, s[28:29]
	flat_store_short v[2:3], v5
	v_sub_f32_e32 v2, v6, v26
	v_min_f32_e32 v2, 0x42a00000, v2
	v_mul_f32_e32 v2, 0x3fb8aa3b, v2
	v_exp_f32_e32 v3, v2
	v_mul_f32_e32 v5, 0xbfb8aa3b, v39
	v_exp_f32_e32 v5, v5
	v_sub_f32_e32 v2, v16, v6
	v_mul_f32_e32 v3, v4, v3
	v_sub_f32_e32 v4, v26, v6
	v_min_f32_e32 v4, 0x42a00000, v4
	v_mul_f32_e32 v4, 0x3fb8aa3b, v4
	v_exp_f32_e32 v4, v4
	v_cvt_pk_bf16_f32 v3, v3, s0
	ds_write_b16 v43, v3 offset:1088
	v_add_f32_e32 v8, v7, v51
	v_mul_f32_e32 v3, v12, v4
	v_add_f32_e32 v4, 1.0, v5
	v_div_scale_f32 v5, s[30:31], v4, v4, v39
	v_rcp_f32_e32 v6, v5
	v_cvt_pk_bf16_f32 v3, v3, s0
	ds_write_b16 v43, v3 offset:9792
	v_or_b32_e32 v3, 5, v31
	v_fma_f32 v9, -v5, v6, 1.0
	v_fmac_f32_e32 v6, v9, v6
	v_div_scale_f32 v9, vcc, v39, v4, v39
	v_mul_f32_e32 v10, v9, v6
	v_fma_f32 v11, -v5, v10, v9
	v_fmac_f32_e32 v10, v11, v6
	v_fma_f32 v5, -v5, v10, v9
	v_mul_f32_e32 v9, 0x3fb8aa3b, v8
	v_exp_f32_e32 v9, v9
	v_div_fmas_f32 v5, v5, v6, v10
	v_div_fixup_f32 v6, v5, v4, v39
	v_and_or_b32 v3, v3, 21, v46
	v_mul_f32_e32 v4, v6, v9
	v_cvt_pk_bf16_f32 v9, v4, s0
	v_lshl_or_b32 v4, v3, 3, v64
	v_sub_f32_e32 v3, v8, v26
	v_min_f32_e32 v3, 0x42a00000, v3
	v_mul_f32_e32 v3, 0x3fb8aa3b, v3
	v_ashrrev_i32_e32 v5, 31, v4
	v_exp_f32_e32 v3, v3
	v_lshl_add_u64 v[4:5], v[4:5], 1, s[28:29]
	flat_store_short v[4:5], v9
	v_sub_f32_e32 v5, v26, v8
	v_min_f32_e32 v5, 0x42a00000, v5
	v_mul_f32_e32 v3, v6, v3
	v_mul_f32_e32 v5, 0x3fb8aa3b, v5
	v_mul_f32_e32 v6, 0xbfb8aa3b, v38
	v_exp_f32_e32 v5, v5
	v_exp_f32_e32 v6, v6
	v_cvt_pk_bf16_f32 v3, v3, s0
	ds_write_b16 v43, v3 offset:1360
	v_mul_f32_e32 v3, v14, v5
	v_add_f32_e32 v5, 1.0, v6
	v_div_scale_f32 v6, s[30:31], v5, v5, v38
	v_sub_f32_e32 v4, v16, v8
	v_rcp_f32_e32 v8, v6
	v_add_f32_e32 v10, v7, v52
	v_cvt_pk_bf16_f32 v3, v3, s0
	ds_write_b16 v43, v3 offset:10064
	v_fma_f32 v9, -v6, v8, 1.0
	v_fmac_f32_e32 v8, v9, v8
	v_div_scale_f32 v9, vcc, v38, v5, v38
	v_mul_f32_e32 v11, v9, v8
	v_fma_f32 v17, -v6, v11, v9
	v_fmac_f32_e32 v11, v17, v8
	v_fma_f32 v6, -v6, v11, v9
	v_mul_f32_e32 v9, 0x3fb8aa3b, v10
	v_exp_f32_e32 v9, v9
	v_or_b32_e32 v3, 6, v31
	v_div_fmas_f32 v6, v6, v8, v11
	v_and_or_b32 v3, v3, 22, v46
	v_div_fixup_f32 v5, v6, v5, v38
	v_lshl_or_b32 v8, v3, 3, v64
	v_sub_f32_e32 v3, v10, v26
	v_mul_f32_e32 v6, v5, v9
	v_ashrrev_i32_e32 v9, 31, v8
	v_min_f32_e32 v3, 0x42a00000, v3
	v_cvt_pk_bf16_f32 v6, v6, s0
	v_lshl_add_u64 v[8:9], v[8:9], 1, s[28:29]
	v_mul_f32_e32 v3, 0x3fb8aa3b, v3
	flat_store_short v[8:9], v6
	v_exp_f32_e32 v6, v3
	v_mul_f32_e32 v8, 0xbfb8aa3b, v37
	v_exp_f32_e32 v8, v8
	v_sub_f32_e32 v3, v16, v10
	v_mul_f32_e32 v5, v5, v6
	v_sub_f32_e32 v6, v26, v10
	v_min_f32_e32 v6, 0x42a00000, v6
	v_mul_f32_e32 v6, 0x3fb8aa3b, v6
	v_exp_f32_e32 v6, v6
	v_cvt_pk_bf16_f32 v5, v5, s0
	ds_write_b16 v43, v5 offset:1632
	v_add_f32_e32 v10, v7, v53
	v_mul_f32_e32 v5, v13, v6
	v_add_f32_e32 v6, 1.0, v8
	v_div_scale_f32 v8, s[30:31], v6, v6, v37
	v_rcp_f32_e32 v9, v8
	v_cvt_pk_bf16_f32 v5, v5, s0
	ds_write_b16 v43, v5 offset:10336
	v_or_b32_e32 v5, 7, v31
	v_fma_f32 v11, -v8, v9, 1.0
	v_fmac_f32_e32 v9, v11, v9
	v_div_scale_f32 v11, vcc, v37, v6, v37
	v_mul_f32_e32 v17, v11, v9
	v_fma_f32 v27, -v8, v17, v11
	v_fmac_f32_e32 v17, v27, v9
	v_fma_f32 v8, -v8, v17, v11
	v_mul_f32_e32 v11, 0x3fb8aa3b, v10
	v_exp_f32_e32 v11, v11
	v_div_fmas_f32 v8, v8, v9, v17
	v_div_fixup_f32 v6, v8, v6, v37
	v_and_or_b32 v5, v5, 23, v46
	v_mul_f32_e32 v8, v6, v11
	v_mul_f32_e32 v2, 0x3fb8aa3b, v2
	v_mul_f32_e32 v3, 0x3fb8aa3b, v3
	v_cvt_pk_bf16_f32 v11, v8, s0
	v_lshl_or_b32 v8, v5, 3, v64
	v_sub_f32_e32 v5, v16, v10
	v_exp_f32_e32 v2, v2
	v_mul_f32_e32 v4, 0x3fb8aa3b, v4
	v_exp_f32_e32 v3, v3
	v_mul_f32_e32 v5, 0x3fb8aa3b, v5
	v_exp_f32_e32 v4, v4
	v_exp_f32_e32 v5, v5
	v_ashrrev_i32_e32 v9, 31, v8
	v_lshl_add_u64 v[8:9], v[8:9], 1, s[28:29]
	v_pk_mul_f32 v[2:3], v[12:13], v[2:3]
	flat_store_short v[8:9], v11
	v_cvt_pk_bf16_f32 v8, v2, v3
	v_pk_mul_f32 v[2:3], v[14:15], v[4:5]
	v_sub_f32_e32 v4, v10, v26
	v_min_f32_e32 v4, 0x42a00000, v4
	v_mul_f32_e32 v4, 0x3fb8aa3b, v4
	v_exp_f32_e32 v4, v4
	v_sub_f32_e32 v5, v26, v10
	v_min_f32_e32 v5, 0x42a00000, v5
	v_mul_f32_e32 v5, 0x3fb8aa3b, v5
	v_mul_f32_e32 v4, v6, v4
	v_mul_f32_e32 v6, 0xbfb8aa3b, v36
	v_exp_f32_e32 v5, v5
	v_exp_f32_e32 v6, v6
	v_cvt_pk_bf16_f32 v4, v4, s0
	v_cvt_pk_bf16_f32 v2, v2, v3
	ds_write_b16 v43, v4 offset:1904
	v_mul_f32_e32 v4, v15, v5
	v_add_f32_e32 v5, 1.0, v6
	v_and_b32_e32 v3, 0xffff0000, v2
	v_lshlrev_b32_e32 v2, 16, v2
	v_div_scale_f32 v6, s[30:31], v5, v5, v36
	v_or_b32_sdwa v3, v3, v8 dst_sel:DWORD dst_unused:UNUSED_PAD src0_sel:DWORD src1_sel:WORD_1
	v_or_b32_sdwa v2, v2, v8 dst_sel:DWORD dst_unused:UNUSED_PAD src0_sel:DWORD src1_sel:WORD_0
	v_rcp_f32_e32 v8, v6
	v_add_f32_e32 v9, v7, v55
	v_cvt_pk_bf16_f32 v4, v4, s0
	ds_write_b16 v43, v4 offset:10608
	v_fma_f32 v10, -v6, v8, 1.0
	v_fmac_f32_e32 v8, v10, v8
	v_div_scale_f32 v10, vcc, v36, v5, v36
	v_mul_f32_e32 v11, v10, v8
	v_fma_f32 v12, -v6, v11, v10
	v_fmac_f32_e32 v11, v12, v8
	v_fma_f32 v6, -v6, v11, v10
	v_mul_f32_e32 v10, 0x3fb8aa3b, v9
	v_exp_f32_e32 v10, v10
	v_or_b32_e32 v4, 8, v31
	v_div_fmas_f32 v6, v6, v8, v11
	v_div_fixup_f32 v6, v6, v5, v36
	v_and_or_b32 v4, v4, 24, v46
	v_mul_f32_e32 v5, v6, v10
	v_lshl_or_b32 v4, v4, 3, v64
; DI bfr f2bf(float a) { return (bfr)(pk2(a, 0.f) & 0xffffu); }
; DI float siluf_(float x) { return x / (1.f + __expf(-x)); }
; DI void hg_prep_unit(const Params& p, int l, int unit, unsigned char* smem) {
;     ...
;     for (int i = 0; i < 16; ++i) {
;       const int ig = i0 + i;
;       const float Gi = G[i] + goff;
;       const float kkv = KK[i];
;       const float q = siluf_(Q[i]);
;       g_qhat[fragp_idx(ig, dk, 4)] = f2bf(q * __expf(Gi));
;       const float khv = kkv * __expf(Gl - Gi);
;       if (i & 1) kh[i >> 1] |= ((unsigned)f2bf(khv)) << 16; else kh[i >> 1] = f2bf(khv);
;       sQt[ig * 136 + dk] = f2bf(q * __expf(fminf(Gi - Gr, 80.f)));
;       sKt[ig * 136 + dk] = f2bf(kkv * __expf(fminf(Gr - Gi, 80.f)));
	v_cvt_pk_bf16_f32 v8, v5, s0
	v_ashrrev_i32_e32 v5, 31, v4
	v_lshl_add_u64 v[4:5], v[4:5], 1, s[28:29]
	flat_store_short v[4:5], v8
	v_sub_f32_e32 v4, v9, v26
	v_min_f32_e32 v4, 0x42a00000, v4
	v_mul_f32_e32 v4, 0x3fb8aa3b, v4
	v_exp_f32_e32 v5, v4
	v_mul_f32_e32 v8, 0xbfb8aa3b, v35
	v_exp_f32_e32 v8, v8
	v_sub_f32_e32 v4, v16, v9
	v_mul_f32_e32 v5, v6, v5
	v_sub_f32_e32 v6, v26, v9
	v_min_f32_e32 v6, 0x42a00000, v6
	v_mul_f32_e32 v6, 0x3fb8aa3b, v6
	v_exp_f32_e32 v6, v6
	v_cvt_pk_bf16_f32 v5, v5, s0
	ds_write_b16 v43, v5 offset:2176
	v_add_f32_e32 v10, v7, v56
	v_mul_f32_e32 v5, v18, v6
	v_add_f32_e32 v6, 1.0, v8
	v_div_scale_f32 v8, s[30:31], v6, v6, v35
	v_rcp_f32_e32 v9, v8
	v_cvt_pk_bf16_f32 v5, v5, s0
	ds_write_b16 v43, v5 offset:10880
	v_or_b32_e32 v5, 9, v31
	v_fma_f32 v11, -v8, v9, 1.0
	v_fmac_f32_e32 v9, v11, v9
	v_div_scale_f32 v11, vcc, v35, v6, v35
	v_mul_f32_e32 v12, v11, v9
	v_fma_f32 v13, -v8, v12, v11
	v_fmac_f32_e32 v12, v13, v9
	v_fma_f32 v8, -v8, v12, v11
	v_mul_f32_e32 v11, 0x3fb8aa3b, v10
	v_exp_f32_e32 v11, v11
	v_div_fmas_f32 v8, v8, v9, v12
	v_div_fixup_f32 v6, v8, v6, v35
	v_and_or_b32 v5, v5, 25, v46
	v_mul_f32_e32 v8, v6, v11
	v_cvt_pk_bf16_f32 v11, v8, s0
	v_lshl_or_b32 v8, v5, 3, v64
	v_sub_f32_e32 v5, v10, v26
	v_min_f32_e32 v5, 0x42a00000, v5
	v_mul_f32_e32 v5, 0x3fb8aa3b, v5
	v_exp_f32_e32 v5, v5
	v_ashrrev_i32_e32 v9, 31, v8
	v_lshl_add_u64 v[8:9], v[8:9], 1, s[28:29]
	flat_store_short v[8:9], v11
	v_mul_f32_e32 v5, v6, v5
	v_sub_f32_e32 v6, v26, v10
	v_min_f32_e32 v6, 0x42a00000, v6
	v_mul_f32_e32 v6, 0x3fb8aa3b, v6
	v_mul_f32_e32 v9, 0xbfb8aa3b, v34
	v_exp_f32_e32 v6, v6
	v_exp_f32_e32 v9, v9
	v_cvt_pk_bf16_f32 v5, v5, s0
	ds_write_b16 v43, v5 offset:2448
	v_mul_f32_e32 v5, v20, v6
	v_add_f32_e32 v6, 1.0, v9
	v_div_scale_f32 v9, s[30:31], v6, v6, v34
	v_sub_f32_e32 v8, v16, v10
	v_rcp_f32_e32 v10, v9
	v_add_f32_e32 v12, v7, v57
	v_cvt_pk_bf16_f32 v5, v5, s0
	ds_write_b16 v43, v5 offset:11152
	v_fma_f32 v11, -v9, v10, 1.0
	v_fmac_f32_e32 v10, v11, v10
	v_div_scale_f32 v11, vcc, v34, v6, v34
	v_mul_f32_e32 v13, v11, v10
	v_fma_f32 v14, -v9, v13, v11
	v_fmac_f32_e32 v13, v14, v10
	v_fma_f32 v9, -v9, v13, v11
	v_mul_f32_e32 v11, 0x3fb8aa3b, v12
	v_exp_f32_e32 v11, v11
	v_or_b32_e32 v5, 10, v31
	v_div_fmas_f32 v9, v9, v10, v13
	v_and_or_b32 v5, v5, 26, v46
	v_div_fixup_f32 v6, v9, v6, v34
	v_lshl_or_b32 v10, v5, 3, v64
	v_sub_f32_e32 v5, v12, v26
	v_mul_f32_e32 v9, v6, v11
	v_ashrrev_i32_e32 v11, 31, v10
	v_min_f32_e32 v5, 0x42a00000, v5
	v_cvt_pk_bf16_f32 v9, v9, s0
	v_lshl_add_u64 v[10:11], v[10:11], 1, s[28:29]
	v_mul_f32_e32 v5, 0x3fb8aa3b, v5
	flat_store_short v[10:11], v9
	v_exp_f32_e32 v9, v5
	v_mul_f32_e32 v10, 0xbfb8aa3b, v33
	v_exp_f32_e32 v10, v10
	v_sub_f32_e32 v5, v16, v12
	v_mul_f32_e32 v6, v6, v9
	v_sub_f32_e32 v9, v26, v12
	v_min_f32_e32 v9, 0x42a00000, v9
	v_mul_f32_e32 v9, 0x3fb8aa3b, v9
	v_exp_f32_e32 v9, v9
	v_cvt_pk_bf16_f32 v6, v6, s0
	ds_write_b16 v43, v6 offset:2720
	v_add_f32_e32 v12, v7, v58
	v_mul_f32_e32 v6, v19, v9
	v_add_f32_e32 v9, 1.0, v10
	v_div_scale_f32 v10, s[30:31], v9, v9, v33
	v_rcp_f32_e32 v11, v10
	v_cvt_pk_bf16_f32 v6, v6, s0
	ds_write_b16 v43, v6 offset:11424
	v_or_b32_e32 v6, 11, v31
	v_fma_f32 v13, -v10, v11, 1.0
	v_fmac_f32_e32 v11, v13, v11
	v_div_scale_f32 v13, vcc, v33, v9, v33
	v_mul_f32_e32 v14, v13, v11
	v_fma_f32 v15, -v10, v14, v13
	v_fmac_f32_e32 v14, v15, v11
	v_fma_f32 v10, -v10, v14, v13
	v_mul_f32_e32 v13, 0x3fb8aa3b, v12
	v_exp_f32_e32 v13, v13
	v_div_fmas_f32 v10, v10, v11, v14
	v_and_or_b32 v6, v6, 27, v46
	v_mul_f32_e32 v4, 0x3fb8aa3b, v4
	v_mul_f32_e32 v5, 0x3fb8aa3b, v5
	v_div_fixup_f32 v14, v10, v9, v33
	v_lshl_or_b32 v10, v6, 3, v64
	v_sub_f32_e32 v6, v16, v12
	v_exp_f32_e32 v4, v4
	v_mul_f32_e32 v8, 0x3fb8aa3b, v8
	v_exp_f32_e32 v5, v5
	v_mul_f32_e32 v9, v14, v13
	v_mul_f32_e32 v6, 0x3fb8aa3b, v6
	v_exp_f32_e32 v8, v8
	v_cvt_pk_bf16_f32 v13, v9, s0
	v_exp_f32_e32 v9, v6
	v_pk_mul_f32 v[4:5], v[18:19], v[4:5]
	v_ashrrev_i32_e32 v11, 31, v10
	v_cvt_pk_bf16_f32 v6, v4, v5
	v_pk_mul_f32 v[4:5], v[20:21], v[8:9]
	v_sub_f32_e32 v8, v12, v26
	v_min_f32_e32 v8, 0x42a00000, v8
	v_mul_f32_e32 v8, 0x3fb8aa3b, v8
	v_exp_f32_e32 v8, v8
	v_cvt_pk_bf16_f32 v4, v4, v5
	v_and_b32_e32 v5, 0xffff0000, v4
	v_lshlrev_b32_e32 v4, 16, v4
	v_or_b32_sdwa v5, v5, v6 dst_sel:DWORD dst_unused:UNUSED_PAD src0_sel:DWORD src1_sel:WORD_1
	v_or_b32_sdwa v4, v4, v6 dst_sel:DWORD dst_unused:UNUSED_PAD src0_sel:DWORD src1_sel:WORD_0
	v_mul_f32_e32 v6, v14, v8
	v_sub_f32_e32 v8, v26, v12
	v_min_f32_e32 v8, 0x42a00000, v8
	v_mul_f32_e32 v8, 0x3fb8aa3b, v8
	v_mul_f32_e32 v9, 0xbfb8aa3b, v32
	v_exp_f32_e32 v8, v8
	v_exp_f32_e32 v9, v9
	v_lshl_add_u64 v[10:11], v[10:11], 1, s[28:29]
	v_cvt_pk_bf16_f32 v6, v6, s0
	flat_store_short v[10:11], v13
	ds_write_b16 v43, v6 offset:2992
	v_mul_f32_e32 v6, v21, v8
	v_add_f32_e32 v8, 1.0, v9
	v_div_scale_f32 v9, s[30:31], v8, v8, v32
	v_rcp_f32_e32 v10, v9
	v_add_f32_e32 v11, v7, v59
	v_cvt_pk_bf16_f32 v6, v6, s0
	ds_write_b16 v43, v6 offset:11696
	v_fma_f32 v12, -v9, v10, 1.0
	v_fmac_f32_e32 v10, v12, v10
	v_div_scale_f32 v12, vcc, v32, v8, v32
	v_mul_f32_e32 v13, v12, v10
	v_fma_f32 v14, -v9, v13, v12
	v_fmac_f32_e32 v13, v14, v10
	v_fma_f32 v9, -v9, v13, v12
	v_mul_f32_e32 v12, 0x3fb8aa3b, v11
	v_exp_f32_e32 v12, v12
	v_div_fmas_f32 v9, v9, v10, v13
	v_or_b32_e32 v6, 12, v31
	v_div_fixup_f32 v10, v9, v8, v32
	v_mul_f32_e32 v8, v10, v12
	v_and_or_b32 v6, v6, 28, v46
	v_cvt_pk_bf16_f32 v12, v8, s0
	v_lshl_or_b32 v8, v6, 3, v64
	v_sub_f32_e32 v6, v11, v26
	v_min_f32_e32 v6, 0x42a00000, v6
	v_mul_f32_e32 v6, 0x3fb8aa3b, v6
	v_ashrrev_i32_e32 v9, 31, v8
; DI bfr f2bf(float a) { return (bfr)(pk2(a, 0.f) & 0xffffu); }
; DI float siluf_(float x) { return x / (1.f + __expf(-x)); }
; DI void hg_prep_unit(const Params& p, int l, int unit, unsigned char* smem) {
;     ...
;     for (int i = 0; i < 16; ++i) {
;       const int ig = i0 + i;
;       const float Gi = G[i] + goff;
;       const float kkv = KK[i];
;       const float q = siluf_(Q[i]);
;       g_qhat[fragp_idx(ig, dk, 4)] = f2bf(q * __expf(Gi));
;       const float khv = kkv * __expf(Gl - Gi);
;       if (i & 1) kh[i >> 1] |= ((unsigned)f2bf(khv)) << 16; else kh[i >> 1] = f2bf(khv);
;       sQt[ig * 136 + dk] = f2bf(q * __expf(fminf(Gi - Gr, 80.f)));
;       sKt[ig * 136 + dk] = f2bf(kkv * __expf(fminf(Gr - Gi, 80.f)));
;     }
; #pragma unroll
;     for (int q = 0; q < 2; ++q) { u32x4 w; w[0] = kh[4 * q]; w[1] = kh[4 * q + 1]; w[2] = kh[4 * q + 2]; w[3] = kh[4 * q + 3]; *(u32x4*)(g_khT + fragn_idx(dk, i0 + 8 * q, 2)) = w; }
;     if (hf == 0) ((float*)(WS_ + O_HGD))[(size_t)unit * 128 + dk] = __expf(Gl);
	v_exp_f32_e32 v6, v6
	v_lshl_add_u64 v[8:9], v[8:9], 1, s[28:29]
	flat_store_short v[8:9], v12
	v_sub_f32_e32 v9, v26, v11
	v_min_f32_e32 v9, 0x42a00000, v9
	v_mul_f32_e32 v6, v10, v6
	v_mul_f32_e32 v9, 0x3fb8aa3b, v9
	v_mul_f32_e32 v10, 0xbfb8aa3b, v66
	v_exp_f32_e32 v9, v9
	v_exp_f32_e32 v10, v10
	v_cvt_pk_bf16_f32 v6, v6, s0
	ds_write_b16 v43, v6 offset:3264
	v_mul_f32_e32 v6, v22, v9
	v_add_f32_e32 v9, 1.0, v10
	v_div_scale_f32 v10, s[30:31], v9, v9, v66
	v_sub_f32_e32 v8, v16, v11
	v_rcp_f32_e32 v11, v10
	v_add_f32_e32 v12, v7, v60
	v_cvt_pk_bf16_f32 v6, v6, s0
	ds_write_b16 v43, v6 offset:11968
	v_fma_f32 v13, -v10, v11, 1.0
	v_fmac_f32_e32 v11, v13, v11
	v_div_scale_f32 v13, vcc, v66, v9, v66
	v_mul_f32_e32 v14, v13, v11
	v_fma_f32 v15, -v10, v14, v13
	v_fmac_f32_e32 v14, v15, v11
	v_fma_f32 v10, -v10, v14, v13
	v_mul_f32_e32 v13, 0x3fb8aa3b, v12
	v_exp_f32_e32 v13, v13
	v_div_fmas_f32 v10, v10, v11, v14
	v_or_b32_e32 v6, 13, v31
	v_div_fixup_f32 v9, v10, v9, v66
	v_mul_f32_e32 v10, v9, v13
	v_and_or_b32 v6, v6, 29, v46
	v_cvt_pk_bf16_f32 v13, v10, s0
	v_lshl_or_b32 v10, v6, 3, v64
	v_sub_f32_e32 v6, v12, v26
	v_ashrrev_i32_e32 v11, 31, v10
	v_min_f32_e32 v6, 0x42a00000, v6
	v_lshl_add_u64 v[10:11], v[10:11], 1, s[28:29]
	v_mul_f32_e32 v6, 0x3fb8aa3b, v6
	flat_store_short v[10:11], v13
	v_exp_f32_e32 v10, v6
	v_mul_f32_e32 v11, 0xbfb8aa3b, v65
	v_exp_f32_e32 v11, v11
	v_sub_f32_e32 v6, v16, v12
	v_mul_f32_e32 v9, v9, v10
	v_sub_f32_e32 v10, v26, v12
	v_min_f32_e32 v10, 0x42a00000, v10
	v_mul_f32_e32 v10, 0x3fb8aa3b, v10
	v_exp_f32_e32 v10, v10
	v_cvt_pk_bf16_f32 v9, v9, s0
	ds_write_b16 v43, v9 offset:3536
	v_add_f32_e32 v13, v7, v61
	v_mul_f32_e32 v9, v24, v10
	v_add_f32_e32 v10, 1.0, v11
	v_div_scale_f32 v11, s[30:31], v10, v10, v65
	v_rcp_f32_e32 v12, v11
	v_cvt_pk_bf16_f32 v9, v9, s0
	ds_write_b16 v43, v9 offset:12240
	v_or_b32_e32 v9, 14, v31
	v_fma_f32 v14, -v11, v12, 1.0
	v_fmac_f32_e32 v12, v14, v12
	v_div_scale_f32 v14, vcc, v65, v10, v65
	v_mul_f32_e32 v15, v14, v12
	v_fma_f32 v17, -v11, v15, v14
	v_fmac_f32_e32 v15, v17, v12
	v_fma_f32 v11, -v11, v15, v14
	v_mul_f32_e32 v14, 0x3fb8aa3b, v13
	v_exp_f32_e32 v14, v14
	v_div_fmas_f32 v11, v11, v12, v15
	v_div_fixup_f32 v12, v11, v10, v65
	v_and_or_b32 v9, v9, 30, v46
	v_mul_f32_e32 v10, v12, v14
	v_cvt_pk_bf16_f32 v14, v10, s0
	v_lshl_or_b32 v10, v9, 3, v64
	v_sub_f32_e32 v9, v13, v26
	v_ashrrev_i32_e32 v11, 31, v10
	v_min_f32_e32 v9, 0x42a00000, v9
	v_lshl_add_u64 v[10:11], v[10:11], 1, s[28:29]
	v_mul_f32_e32 v9, 0x3fb8aa3b, v9
	flat_store_short v[10:11], v14
	v_exp_f32_e32 v10, v9
	v_sub_f32_e32 v11, v26, v13
	v_min_f32_e32 v11, 0x42a00000, v11
	v_mul_f32_e32 v11, 0x3fb8aa3b, v11
	v_mul_f32_e32 v10, v12, v10
	v_mul_f32_e32 v12, 0xbfb8aa3b, v45
	v_exp_f32_e32 v11, v11
	v_exp_f32_e32 v12, v12
	v_cvt_pk_bf16_f32 v10, v10, s0
	ds_write_b16 v43, v10 offset:3808
	v_mul_f32_e32 v10, v23, v11
	v_add_f32_e32 v11, 1.0, v12
	v_div_scale_f32 v12, s[30:31], v11, v11, v45
	v_sub_f32_e32 v9, v16, v13
	v_rcp_f32_e32 v13, v12
	v_add_f32_e32 v15, v7, v63
	v_cvt_pk_bf16_f32 v10, v10, s0
	ds_write_b16 v43, v10 offset:12512
	v_fma_f32 v7, -v12, v13, 1.0
	v_fmac_f32_e32 v13, v7, v13
	v_div_scale_f32 v7, vcc, v45, v11, v45
	v_mul_f32_e32 v10, v7, v13
	v_fma_f32 v17, -v12, v10, v7
	v_fmac_f32_e32 v10, v17, v13
	v_fma_f32 v7, -v12, v10, v7
	v_mul_f32_e32 v12, 0x3fb8aa3b, v15
	v_exp_f32_e32 v12, v12
	v_mul_f32_e32 v8, 0x3fb8aa3b, v8
	v_mul_f32_e32 v9, 0x3fb8aa3b, v9
	v_div_fmas_f32 v7, v7, v13, v10
	v_exp_f32_e32 v8, v8
	v_exp_f32_e32 v9, v9
	v_div_fixup_f32 v13, v7, v11, v45
	v_or_b32_e32 v14, 15, v30
	v_mul_f32_e32 v7, v13, v12
	v_cvt_pk_bf16_f32 v12, v7, s0
	v_and_or_b32 v7, v14, 31, v46
	v_lshl_or_b32 v10, v7, 3, v64
	v_sub_f32_e32 v7, v16, v15
	v_mul_f32_e32 v6, 0x3fb8aa3b, v6
	v_mul_f32_e32 v7, 0x3fb8aa3b, v7
	v_pk_mul_f32 v[8:9], v[22:23], v[8:9]
	v_exp_f32_e32 v6, v6
	v_exp_f32_e32 v7, v7
	v_cvt_pk_bf16_f32 v8, v8, v9
	v_sub_f32_e32 v9, v15, v26
	v_min_f32_e32 v9, 0x42a00000, v9
	v_mul_f32_e32 v9, 0x3fb8aa3b, v9
	v_exp_f32_e32 v9, v9
	v_pk_mul_f32 v[6:7], v[24:25], v[6:7]
	v_ashrrev_i32_e32 v11, 31, v10
	v_cvt_pk_bf16_f32 v6, v6, v7
	v_and_b32_e32 v7, 0xffff0000, v6
	v_lshlrev_b32_e32 v6, 16, v6
	v_or_b32_sdwa v7, v7, v8 dst_sel:DWORD dst_unused:UNUSED_PAD src0_sel:DWORD src1_sel:WORD_1
	v_or_b32_sdwa v6, v6, v8 dst_sel:DWORD dst_unused:UNUSED_PAD src0_sel:DWORD src1_sel:WORD_0
	v_mul_f32_e32 v8, v13, v9
	v_sub_f32_e32 v9, v26, v15
	v_min_f32_e32 v9, 0x42a00000, v9
	v_mul_f32_e32 v9, 0x3fb8aa3b, v9
	v_exp_f32_e32 v9, v9
	v_lshl_add_u64 v[10:11], v[10:11], 1, s[28:29]
	flat_store_short v[10:11], v12
	v_mul_lo_u32 v10, v14, s25
	v_cvt_pk_bf16_f32 v8, v8, s0
	v_add_lshl_u32 v10, v10, v29, 1
	ds_write_b16 v10, v8
	v_mul_f32_e32 v8, v25, v9
	v_cvt_pk_bf16_f32 v8, v8, s0
	s_movk_i32 s25, 0xf8
	ds_write_b16 v10, v8 offset:8704
	v_and_or_b32 v8, v44, s25, v62
	v_ashrrev_i32_e32 v9, 31, v8
	v_lshl_add_u64 v[8:9], v[8:9], 1, s[28:29]
	s_mov_b64 s[28:29], 0x2000
	v_lshl_add_u64 v[10:11], v[8:9], 0, s[28:29]
	v_add_co_u32_e32 v8, vcc, 0x2000, v8
	s_nop 1
	v_addc_co_u32_e32 v9, vcc, 0, v9, vcc
	flat_store_dwordx4 v[8:9], v[0:3]
	flat_store_dwordx4 v[10:11], v[4:7] offset:512
	s_and_saveexec_b64 s[28:29], s[6:7]
	s_cbranch_execz .LBB0_321
	s_mov_b32 s25, s45
	s_lshl_b64 s[6:7], s[24:25], 9
	v_mul_f32_e32 v0, 0x3fb8aa3b, v16
	s_add_u32 s6, s8, s6
	v_exp_f32_e32 v2, v0
	s_addc_u32 s7, s9, s7
	v_lshlrev_b32_e32 v208, 2, v29
	v_lshl_add_u64 v[0:1], s[6:7], 0, v[208:209]
	v_add_co_u32_e32 v0, vcc, 0x67fcf000, v0
	s_nop 1
	v_addc_co_u32_e32 v1, vcc, 0, v1, vcc
	flat_store_dword v[0:1], v2 offset:1536
